# static prio 1 waves 4-7 + early barrier k=4 (tail prio 2, restored per group) + int8 nop trims
# baseline (speedup 1.0000x reference)
_Z10fwd_kernel4Args:
	s_load_dword s97, s[0:1], 0xa0
	s_mov_b32 s8, s2
	s_add_u32 s2, s0, 0xa0
	s_addc_u32 s3, s1, 0
	v_lshl_add_u32 v1, v0, 2, 0
	v_writelane_b32 v254, s2, 0
	v_add_u32_e32 v1, 0x20000, v1
	v_mov_b32_e32 v2, 0
	v_readfirstlane_b32 s9, v0
	v_writelane_b32 v254, s3, 1
	ds_write2st64_b32 v1, v2, v2 offset1:8
	ds_write2st64_b32 v1, v2, v2 offset0:16 offset1:24
	v_or_b32_e32 v1, 0x800, v0
	s_mov_b64 s[2:3], -1
	s_and_saveexec_b64 s[4:5], s[2:3]
	v_lshl_add_u32 v3, v1, 2, 0
	v_add_u32_e32 v3, 0x20000, v3
	ds_write_b32 v3, v2
	s_or_b64 exec, exec, s[4:5]
	s_and_saveexec_b64 s[4:5], s[2:3]
	s_add_i32 s2, 0, 0x20000
	v_lshl_add_u32 v1, v1, 2, s2
	v_mov_b32_e32 v2, 0
	ds_write_b32 v1, v2 offset:2048
	s_or_b64 exec, exec, s[4:5]
	v_or_b32_e32 v1, 0xc00, v0
	v_cmp_gt_u32_e64 s[2:3], 7, 6
	v_cmp_gt_u32_e64 s[6:7], 7, 5
	s_and_saveexec_b64 s[4:5], s[6:7]
	v_lshl_add_u32 v2, v1, 2, 0
	v_add_u32_e32 v2, 0x20000, v2
	v_mov_b32_e32 v3, 0
	ds_write_b32 v2, v3
	s_or_b64 exec, exec, s[4:5]
	s_load_dwordx8 s[88:95], s[0:1], 0x80
	s_and_saveexec_b64 s[4:5], s[2:3]
	s_add_i32 s2, 0, 0x20000
	v_lshl_add_u32 v1, v1, 2, s2
	v_mov_b32_e32 v2, 0
	ds_write_b32 v1, v2 offset:2048
	s_or_b64 exec, exec, s[4:5]
	s_load_dwordx16 s[12:27], s[0:1], 0x0
	s_waitcnt lgkmcnt(0)
	s_barrier
	s_mov_b32 s98, 0
	s_cmp_ge_u32 s9, 0x100
	s_cbranch_scc0 .Lmy_prio_done
	s_mov_b32 s98, 1
	s_setprio 1

.LBB0_308:
	ds_read_b128 v[142:145], v191
	ds_read_b128 v[138:141], v191 offset:1024
	ds_read_b128 v[134:137], v191 offset:2048
	ds_read_b128 v[130:133], v191 offset:3072
	s_add_u32 s46, s44, 0xfff80080
	s_addc_u32 s47, s45, -1
	s_cmp_eq_u32 s37, 28
	s_cselect_b32 s49, s0, s47
	s_cselect_b32 s48, s1, s46
	s_cselect_b32 s47, s7, s31
	s_cselect_b32 s46, s14, s15
	v_lshl_add_u64 v[166:167], s[44:45], 0, v[162:163]
	s_add_i32 m0, s9, 0xc000
	ds_read_b128 v[170:173], v192
	ds_read_b128 v[174:177], v192 offset:1024
	s_waitcnt lgkmcnt(0)
	ds_read_b128 v[178:181], v192 offset:2048
	ds_read_b128 v[182:185], v192 offset:3072
	ds_read_b128 v[204:207], v192 offset:4096
	ds_read_b128 v[208:211], v192 offset:5120
	ds_read_b128 v[212:215], v192 offset:6144
	ds_read_b128 v[216:219], v192 offset:7168
	global_load_lds_dwordx4 v[166:167], off
	v_lshl_add_u64 v[166:167], s[44:45], 0, v[164:165]
	s_add_i32 m0, s9, 0xe000
	s_nop 0
	global_load_lds_dwordx4 v[166:167], off
	s_waitcnt lgkmcnt(8)
	s_barrier
	s_waitcnt lgkmcnt(0)
	s_waitcnt lgkmcnt(0)
	v_mfma_i32_16x16x64_i8 v[126:129], v[142:145], v[170:173], v[126:129]
	v_mfma_i32_16x16x64_i8 v[126:129], v[138:141], v[174:177], v[126:129]
	v_mfma_i32_16x16x64_i8 v[122:125], v[134:137], v[170:173], v[122:125]
	v_mfma_i32_16x16x64_i8 v[122:125], v[130:133], v[174:177], v[122:125]
	v_mfma_i32_16x16x64_i8 v[110:113], v[142:145], v[178:181], v[110:113]
	v_mfma_i32_16x16x64_i8 v[110:113], v[138:141], v[182:185], v[110:113]
	v_mfma_i32_16x16x64_i8 v[106:109], v[134:137], v[178:181], v[106:109]
	v_mfma_i32_16x16x64_i8 v[106:109], v[130:133], v[182:185], v[106:109]
	v_mfma_i32_16x16x64_i8 v[94:97], v[142:145], v[204:207], v[94:97]
	v_mfma_i32_16x16x64_i8 v[94:97], v[138:141], v[208:211], v[94:97]
	v_mfma_i32_16x16x64_i8 v[90:93], v[134:137], v[204:207], v[90:93]
	v_mfma_i32_16x16x64_i8 v[90:93], v[130:133], v[208:211], v[90:93]
	s_barrier
	s_setprio 2
	v_mfma_i32_16x16x64_i8 v[78:81], v[142:145], v[212:215], v[78:81]
	v_mfma_i32_16x16x64_i8 v[78:81], v[138:141], v[216:219], v[78:81]
	v_mfma_i32_16x16x64_i8 v[74:77], v[134:137], v[212:215], v[74:77]
	v_mfma_i32_16x16x64_i8 v[74:77], v[130:133], v[216:219], v[74:77]
	s_setprio 0
	s_cmp_eq_u32 s98, 1
	s_cbranch_scc0 .Lmy_pr_P1a_0
	s_setprio 1
.Lmy_pr_P1a_0:
	s_add_i32 s50, s55, s8
	v_lshl_add_u64 v[166:167], s[46:47], 0, v[148:149]
	s_mov_b32 m0, s50
	ds_read_b128 v[220:223], v193
	ds_read_b128 v[224:227], v193 offset:1024
	ds_read_b128 v[234:237], v193 offset:2048
	ds_read_b128 v[238:241], v193 offset:3072
	global_load_lds_dwordx4 v[166:167], off
	v_lshl_add_u64 v[168:169], s[46:47], 0, v[152:153]
	s_add_i32 m0, s50, 0x2000
	s_nop 0
	global_load_lds_dwordx4 v[168:169], off
	s_barrier
	s_waitcnt lgkmcnt(0)
	s_waitcnt lgkmcnt(0)
	v_mfma_i32_16x16x64_i8 v[118:121], v[220:223], v[170:173], v[118:121]
	v_mfma_i32_16x16x64_i8 v[118:121], v[224:227], v[174:177], v[118:121]
	v_mfma_i32_16x16x64_i8 v[114:117], v[234:237], v[170:173], v[114:117]
	v_mfma_i32_16x16x64_i8 v[114:117], v[238:241], v[174:177], v[114:117]
	v_mfma_i32_16x16x64_i8 v[102:105], v[220:223], v[178:181], v[102:105]
	v_mfma_i32_16x16x64_i8 v[102:105], v[224:227], v[182:185], v[102:105]
	v_mfma_i32_16x16x64_i8 v[98:101], v[234:237], v[178:181], v[98:101]
	v_mfma_i32_16x16x64_i8 v[98:101], v[238:241], v[182:185], v[98:101]
	v_mfma_i32_16x16x64_i8 v[86:89], v[220:223], v[204:207], v[86:89]
	v_mfma_i32_16x16x64_i8 v[86:89], v[224:227], v[208:211], v[86:89]
	v_mfma_i32_16x16x64_i8 v[82:85], v[234:237], v[204:207], v[82:85]
	v_mfma_i32_16x16x64_i8 v[82:85], v[238:241], v[208:211], v[82:85]
	s_barrier
	s_setprio 2
	v_mfma_i32_16x16x64_i8 v[70:73], v[220:223], v[212:215], v[70:73]
	v_mfma_i32_16x16x64_i8 v[70:73], v[224:227], v[216:219], v[70:73]
	v_mfma_i32_16x16x64_i8 v[66:69], v[234:237], v[212:215], v[66:69]
	v_mfma_i32_16x16x64_i8 v[66:69], v[238:241], v[216:219], v[66:69]
	s_setprio 0
	s_cmp_eq_u32 s98, 1
	s_cbranch_scc0 .Lmy_pr_P1a_1
	s_setprio 1
.Lmy_pr_P1a_1:
	s_mov_b32 m0, s9
	v_lshl_add_u64 v[170:171], s[48:49], 0, v[146:147]
	ds_read_b128 v[174:177], v192 offset:16384
	ds_read_b128 v[178:181], v192 offset:17408
	ds_read_b128 v[182:185], v192 offset:18432
	ds_read_b128 v[204:207], v192 offset:19456
	ds_read_b128 v[208:211], v192 offset:20480
	ds_read_b128 v[212:215], v192 offset:21504
	ds_read_b128 v[216:219], v192 offset:22528
	ds_read_b128 v[242:245], v192 offset:23552
	global_load_lds_dwordx4 v[170:171], off
	v_lshl_add_u64 v[172:173], s[48:49], 0, v[150:151]
	s_mov_b32 m0, s13
	s_nop 0
	global_load_lds_dwordx4 v[172:173], off
	s_barrier
	s_waitcnt lgkmcnt(0)
	s_waitcnt lgkmcnt(0)
	v_mfma_i32_16x16x64_i8 v[62:65], v[142:145], v[174:177], v[62:65]
	v_mfma_i32_16x16x64_i8 v[62:65], v[138:141], v[178:181], v[62:65]
	v_mfma_i32_16x16x64_i8 v[58:61], v[134:137], v[174:177], v[58:61]
	v_mfma_i32_16x16x64_i8 v[58:61], v[130:133], v[178:181], v[58:61]
	v_mfma_i32_16x16x64_i8 v[46:49], v[142:145], v[182:185], v[46:49]
	v_mfma_i32_16x16x64_i8 v[46:49], v[138:141], v[204:207], v[46:49]
	v_mfma_i32_16x16x64_i8 v[42:45], v[134:137], v[182:185], v[42:45]
	v_mfma_i32_16x16x64_i8 v[42:45], v[130:133], v[204:207], v[42:45]
	v_mfma_i32_16x16x64_i8 v[30:33], v[142:145], v[208:211], v[30:33]
	v_mfma_i32_16x16x64_i8 v[30:33], v[138:141], v[212:215], v[30:33]
	v_mfma_i32_16x16x64_i8 v[26:29], v[134:137], v[208:211], v[26:29]
	v_mfma_i32_16x16x64_i8 v[26:29], v[130:133], v[212:215], v[26:29]
	s_barrier
	s_setprio 2
	v_mfma_i32_16x16x64_i8 v[14:17], v[142:145], v[216:219], v[14:17]
	v_mfma_i32_16x16x64_i8 v[14:17], v[138:141], v[242:245], v[14:17]
	v_mfma_i32_16x16x64_i8 v[10:13], v[134:137], v[216:219], v[10:13]
	v_mfma_i32_16x16x64_i8 v[10:13], v[130:133], v[242:245], v[10:13]
	s_setprio 0
	s_cmp_eq_u32 s98, 1
	s_cbranch_scc0 .Lmy_pr_P1a_2
	s_setprio 1
.Lmy_pr_P1a_2:
	s_add_u32 s50, s46, 0x80000
	s_addc_u32 s51, s47, 0
	s_add_i32 s59, s56, s8
	v_lshl_add_u64 v[130:131], s[50:51], 0, v[148:149]
	s_mov_b32 m0, s59
	s_nop 0
	global_load_lds_dwordx4 v[130:131], off
	v_lshl_add_u64 v[130:131], s[50:51], 0, v[152:153]
	s_add_i32 m0, s59, 0x2000
	s_nop 0
	global_load_lds_dwordx4 v[130:131], off
	s_waitcnt vmcnt(6)
	s_barrier
	v_mfma_i32_16x16x64_i8 v[54:57], v[220:223], v[174:177], v[54:57]
	v_mfma_i32_16x16x64_i8 v[54:57], v[224:227], v[178:181], v[54:57]
	v_mfma_i32_16x16x64_i8 v[50:53], v[234:237], v[174:177], v[50:53]
	v_mfma_i32_16x16x64_i8 v[50:53], v[238:241], v[178:181], v[50:53]
	v_mfma_i32_16x16x64_i8 v[38:41], v[220:223], v[182:185], v[38:41]
	v_mfma_i32_16x16x64_i8 v[38:41], v[224:227], v[204:207], v[38:41]
	v_mfma_i32_16x16x64_i8 v[34:37], v[234:237], v[182:185], v[34:37]
	v_mfma_i32_16x16x64_i8 v[34:37], v[238:241], v[204:207], v[34:37]
	v_mfma_i32_16x16x64_i8 v[22:25], v[220:223], v[208:211], v[22:25]
	v_mfma_i32_16x16x64_i8 v[22:25], v[224:227], v[212:215], v[22:25]
	v_mfma_i32_16x16x64_i8 v[18:21], v[234:237], v[208:211], v[18:21]
	v_mfma_i32_16x16x64_i8 v[18:21], v[238:241], v[212:215], v[18:21]
	s_barrier
	s_setprio 2
	v_mfma_i32_16x16x64_i8 v[6:9], v[220:223], v[216:219], v[6:9]
	v_mfma_i32_16x16x64_i8 v[6:9], v[224:227], v[242:245], v[6:9]
	v_mfma_i32_16x16x64_i8 v[2:5], v[234:237], v[216:219], v[2:5]
	v_mfma_i32_16x16x64_i8 v[2:5], v[238:241], v[242:245], v[2:5]
	s_setprio 0
	s_cmp_eq_u32 s98, 1
	s_cbranch_scc0 .Lmy_pr_P1a_3
	s_setprio 1
.Lmy_pr_P1a_3:
	s_add_i32 s50, 0, 0x18000
	v_add_u32_e32 v142, s50, v188
	ds_read_b128 v[130:133], v142
	ds_read_b128 v[134:137], v142 offset:1024
	ds_read_b128 v[138:141], v142 offset:2048
	ds_read_b128 v[142:145], v142 offset:3072
	s_add_u32 s48, s48, 0x80000
	s_addc_u32 s49, s49, 0
	s_mov_b32 m0, s29
	v_lshl_add_u64 v[186:187], s[48:49], 0, v[146:147]
	ds_read_b128 v[174:177], v192 offset:32768
	ds_read_b128 v[178:181], v192 offset:33792
	ds_read_b128 v[182:185], v192 offset:34816
	ds_read_b128 v[204:207], v192 offset:35840
	ds_read_b128 v[208:211], v192 offset:36864
	ds_read_b128 v[212:215], v192 offset:37888
	ds_read_b128 v[216:219], v192 offset:38912
	ds_read_b128 v[220:223], v192 offset:39936
	global_load_lds_dwordx4 v[186:187], off
	v_lshl_add_u64 v[186:187], s[48:49], 0, v[150:151]
	s_mov_b32 m0, s33
	s_nop 0
	global_load_lds_dwordx4 v[186:187], off
	s_waitcnt lgkmcnt(8)
	s_barrier
	s_waitcnt lgkmcnt(0)
	s_waitcnt lgkmcnt(0)
	v_mfma_i32_16x16x64_i8 v[126:129], v[130:133], v[174:177], v[126:129]
	v_mfma_i32_16x16x64_i8 v[126:129], v[134:137], v[178:181], v[126:129]
	v_mfma_i32_16x16x64_i8 v[122:125], v[138:141], v[174:177], v[122:125]
	v_mfma_i32_16x16x64_i8 v[122:125], v[142:145], v[178:181], v[122:125]
	v_mfma_i32_16x16x64_i8 v[110:113], v[130:133], v[182:185], v[110:113]
	v_mfma_i32_16x16x64_i8 v[110:113], v[134:137], v[204:207], v[110:113]
	v_mfma_i32_16x16x64_i8 v[106:109], v[138:141], v[182:185], v[106:109]
	v_mfma_i32_16x16x64_i8 v[106:109], v[142:145], v[204:207], v[106:109]
	v_mfma_i32_16x16x64_i8 v[94:97], v[130:133], v[208:211], v[94:97]
	v_mfma_i32_16x16x64_i8 v[94:97], v[134:137], v[212:215], v[94:97]
	v_mfma_i32_16x16x64_i8 v[90:93], v[138:141], v[208:211], v[90:93]
	v_mfma_i32_16x16x64_i8 v[90:93], v[142:145], v[212:215], v[90:93]
	s_barrier
	s_setprio 2
	v_mfma_i32_16x16x64_i8 v[78:81], v[130:133], v[216:219], v[78:81]
	v_mfma_i32_16x16x64_i8 v[78:81], v[134:137], v[220:223], v[78:81]
	v_mfma_i32_16x16x64_i8 v[74:77], v[138:141], v[216:219], v[74:77]
	v_mfma_i32_16x16x64_i8 v[74:77], v[142:145], v[220:223], v[74:77]
	s_setprio 0
	s_cmp_eq_u32 s98, 1
	s_cbranch_scc0 .Lmy_pr_P1a_4
	s_setprio 1
.Lmy_pr_P1a_4:
	s_add_i32 s48, 0, 0x1c000
	s_add_i32 s49, s50, s8
	v_add_u32_e32 v156, s48, v188
	v_lshl_add_u64 v[166:167], v[166:167], 0, s[22:23]
	s_mov_b32 m0, s49
	ds_read_b128 v[224:227], v156
	ds_read_b128 v[234:237], v156 offset:1024
	ds_read_b128 v[238:241], v156 offset:2048
	ds_read_b128 v[242:245], v156 offset:3072
	global_load_lds_dwordx4 v[166:167], off
	v_lshl_add_u64 v[166:167], v[168:169], 0, s[22:23]
	s_add_i32 m0, s49, 0x2000
	s_nop 0
	global_load_lds_dwordx4 v[166:167], off
	s_barrier
	s_waitcnt lgkmcnt(0)
	s_waitcnt lgkmcnt(0)
	v_mfma_i32_16x16x64_i8 v[118:121], v[224:227], v[174:177], v[118:121]
	v_mfma_i32_16x16x64_i8 v[118:121], v[234:237], v[178:181], v[118:121]
	v_mfma_i32_16x16x64_i8 v[114:117], v[238:241], v[174:177], v[114:117]
	v_mfma_i32_16x16x64_i8 v[114:117], v[242:245], v[178:181], v[114:117]
	v_mfma_i32_16x16x64_i8 v[102:105], v[224:227], v[182:185], v[102:105]
	v_mfma_i32_16x16x64_i8 v[102:105], v[234:237], v[204:207], v[102:105]
	v_mfma_i32_16x16x64_i8 v[98:101], v[238:241], v[182:185], v[98:101]
	v_mfma_i32_16x16x64_i8 v[98:101], v[242:245], v[204:207], v[98:101]
	v_mfma_i32_16x16x64_i8 v[86:89], v[224:227], v[208:211], v[86:89]
	v_mfma_i32_16x16x64_i8 v[86:89], v[234:237], v[212:215], v[86:89]
	v_mfma_i32_16x16x64_i8 v[82:85], v[238:241], v[208:211], v[82:85]
	v_mfma_i32_16x16x64_i8 v[82:85], v[242:245], v[212:215], v[82:85]
	s_barrier
	s_setprio 2
	v_mfma_i32_16x16x64_i8 v[70:73], v[224:227], v[216:219], v[70:73]
	v_mfma_i32_16x16x64_i8 v[70:73], v[234:237], v[220:223], v[70:73]
	v_mfma_i32_16x16x64_i8 v[66:69], v[238:241], v[216:219], v[66:69]
	v_mfma_i32_16x16x64_i8 v[66:69], v[242:245], v[220:223], v[66:69]
	s_setprio 0
	s_cmp_eq_u32 s98, 1
	s_cbranch_scc0 .Lmy_pr_P1a_5
	s_setprio 1
.Lmy_pr_P1a_5:
	s_mov_b32 m0, s53
	v_lshl_add_u64 v[170:171], v[170:171], 0, s[22:23]
	ds_read_b128 v[166:169], v192 offset:49152
	ds_read_b128 v[174:177], v192 offset:50176
	ds_read_b128 v[178:181], v192 offset:51200
	ds_read_b128 v[182:185], v192 offset:52224
	ds_read_b128 v[204:207], v192 offset:53248
	ds_read_b128 v[208:211], v192 offset:54272
	ds_read_b128 v[212:215], v192 offset:55296
	ds_read_b128 v[216:219], v192 offset:56320
	global_load_lds_dwordx4 v[170:171], off
	v_lshl_add_u64 v[170:171], v[172:173], 0, s[22:23]
	s_mov_b32 m0, s54
	s_nop 0
	global_load_lds_dwordx4 v[170:171], off
	s_barrier
	s_waitcnt lgkmcnt(0)
	s_waitcnt lgkmcnt(0)
	v_mfma_i32_16x16x64_i8 v[62:65], v[130:133], v[166:169], v[62:65]
	v_mfma_i32_16x16x64_i8 v[62:65], v[134:137], v[174:177], v[62:65]
	v_mfma_i32_16x16x64_i8 v[58:61], v[138:141], v[166:169], v[58:61]
	v_mfma_i32_16x16x64_i8 v[58:61], v[142:145], v[174:177], v[58:61]
	v_mfma_i32_16x16x64_i8 v[46:49], v[130:133], v[178:181], v[46:49]
	v_mfma_i32_16x16x64_i8 v[46:49], v[134:137], v[182:185], v[46:49]
	v_mfma_i32_16x16x64_i8 v[42:45], v[138:141], v[178:181], v[42:45]
	v_mfma_i32_16x16x64_i8 v[42:45], v[142:145], v[182:185], v[42:45]
	v_mfma_i32_16x16x64_i8 v[30:33], v[130:133], v[204:207], v[30:33]
	v_mfma_i32_16x16x64_i8 v[30:33], v[134:137], v[208:211], v[30:33]
	v_mfma_i32_16x16x64_i8 v[26:29], v[138:141], v[204:207], v[26:29]
	v_mfma_i32_16x16x64_i8 v[26:29], v[142:145], v[208:211], v[26:29]
	s_barrier
	s_setprio 2
	v_mfma_i32_16x16x64_i8 v[14:17], v[130:133], v[212:215], v[14:17]
	v_mfma_i32_16x16x64_i8 v[14:17], v[134:137], v[216:219], v[14:17]
	v_mfma_i32_16x16x64_i8 v[10:13], v[138:141], v[212:215], v[10:13]
	v_mfma_i32_16x16x64_i8 v[10:13], v[142:145], v[216:219], v[10:13]
	s_setprio 0
	s_cmp_eq_u32 s98, 1
	s_cbranch_scc0 .Lmy_pr_P1a_6
	s_setprio 1
.Lmy_pr_P1a_6:
	s_add_u32 s46, s46, 0x80080
	s_addc_u32 s47, s47, 0
	s_add_i32 s48, s48, s8
	v_lshl_add_u64 v[130:131], s[46:47], 0, v[148:149]
	s_mov_b32 m0, s48
	s_nop 0
	global_load_lds_dwordx4 v[130:131], off
	v_lshl_add_u64 v[130:131], s[46:47], 0, v[152:153]
	s_add_i32 m0, s48, 0x2000
	s_nop 0
	global_load_lds_dwordx4 v[130:131], off
	s_waitcnt vmcnt(6)
	s_barrier
	v_mfma_i32_16x16x64_i8 v[54:57], v[224:227], v[166:169], v[54:57]
	v_mfma_i32_16x16x64_i8 v[54:57], v[234:237], v[174:177], v[54:57]
	v_mfma_i32_16x16x64_i8 v[50:53], v[238:241], v[166:169], v[50:53]
	v_mfma_i32_16x16x64_i8 v[50:53], v[242:245], v[174:177], v[50:53]
	v_mfma_i32_16x16x64_i8 v[38:41], v[224:227], v[178:181], v[38:41]
	v_mfma_i32_16x16x64_i8 v[38:41], v[234:237], v[182:185], v[38:41]
	v_mfma_i32_16x16x64_i8 v[34:37], v[238:241], v[178:181], v[34:37]
	v_mfma_i32_16x16x64_i8 v[34:37], v[242:245], v[182:185], v[34:37]
	v_mfma_i32_16x16x64_i8 v[22:25], v[224:227], v[204:207], v[22:25]
	v_mfma_i32_16x16x64_i8 v[22:25], v[234:237], v[208:211], v[22:25]
	v_mfma_i32_16x16x64_i8 v[18:21], v[238:241], v[204:207], v[18:21]
	v_mfma_i32_16x16x64_i8 v[18:21], v[242:245], v[208:211], v[18:21]
	s_barrier
	s_setprio 2
	v_mfma_i32_16x16x64_i8 v[6:9], v[224:227], v[212:215], v[6:9]
	v_mfma_i32_16x16x64_i8 v[6:9], v[234:237], v[216:219], v[6:9]
	v_mfma_i32_16x16x64_i8 v[2:5], v[238:241], v[212:215], v[2:5]
	v_mfma_i32_16x16x64_i8 v[2:5], v[242:245], v[216:219], v[2:5]
	s_setprio 0
	s_cmp_eq_u32 s98, 1
	s_cbranch_scc0 .Lmy_pr_P1a_7
	s_setprio 1
.Lmy_pr_P1a_7:
	s_add_i32 s37, s37, 2
	s_add_u32 s44, s44, 0x100
	s_addc_u32 s45, s45, 0
	s_add_u32 s15, s15, 0x100
	s_addc_u32 s31, s31, 0
	s_cmp_gt_u32 s37, 29
	s_cbranch_scc0 .LBB0_308
	s_nop 15
	s_nop 15
	s_and_b64 vcc, exec, s[24:25]
	s_cbranch_vccz .LBB0_311
	s_barrier

.LBB0_412:
	ds_read_b128 v[130:133], v191
	ds_read_b128 v[134:137], v191 offset:1024
	ds_read_b128 v[138:141], v191 offset:2048
	ds_read_b128 v[142:145], v191 offset:3072
	ds_read_b128 v[146:149], v192
	ds_read_b128 v[150:153], v192 offset:1024
	ds_read_b128 v[174:177], v192 offset:2048
	s_waitcnt lgkmcnt(0)
	ds_read_b128 v[178:181], v192 offset:3072
	s_add_u32 s42, s40, 0xfff00080
	s_addc_u32 s43, s41, -1
	s_cmp_eq_u32 s29, 60
	s_cselect_b32 s45, s0, s43
	s_cselect_b32 s44, s1, s42
	s_cselect_b32 s43, s7, s27
	s_cselect_b32 s42, s14, s15
	v_lshl_add_u64 v[186:187], s[40:41], 0, v[170:171]
	s_add_i32 m0, s9, 0xc000
	ds_read_b128 v[182:185], v193
	ds_read_b128 v[204:207], v193 offset:1024
	ds_read_b128 v[208:211], v193 offset:2048
	ds_read_b128 v[212:215], v193 offset:3072
	ds_read_b128 v[216:219], v193 offset:4096
	ds_read_b128 v[220:223], v193 offset:5120
	ds_read_b128 v[224:227], v193 offset:6144
	ds_read_b128 v[234:237], v193 offset:7168
	global_load_lds_dwordx4 v[186:187], off
	v_lshl_add_u64 v[186:187], s[40:41], 0, v[172:173]
	s_add_i32 m0, s9, 0xe000
	s_nop 0
	global_load_lds_dwordx4 v[186:187], off
	s_waitcnt vmcnt(8)
	s_waitcnt lgkmcnt(0)
	s_barrier
	s_waitcnt lgkmcnt(0)
	v_mfma_f32_16x16x32_bf16 v[126:129], v[130:133], v[182:185], v[126:129]
	v_mfma_f32_16x16x32_bf16 v[122:125], v[138:141], v[182:185], v[122:125]
	v_mfma_f32_16x16x32_bf16 v[118:121], v[130:133], v[208:211], v[118:121]
	v_mfma_f32_16x16x32_bf16 v[110:113], v[138:141], v[208:211], v[110:113]
	v_mfma_f32_16x16x32_bf16 v[102:105], v[130:133], v[216:219], v[102:105]
	v_mfma_f32_16x16x32_bf16 v[94:97], v[138:141], v[216:219], v[94:97]
	v_mfma_f32_16x16x32_bf16 v[86:89], v[130:133], v[224:227], v[86:89]
	v_mfma_f32_16x16x32_bf16 v[78:81], v[138:141], v[224:227], v[78:81]
	v_mfma_f32_16x16x32_bf16 v[126:129], v[134:137], v[204:207], v[126:129]
	v_mfma_f32_16x16x32_bf16 v[122:125], v[142:145], v[204:207], v[122:125]
	v_mfma_f32_16x16x32_bf16 v[118:121], v[134:137], v[212:215], v[118:121]
	v_mfma_f32_16x16x32_bf16 v[110:113], v[142:145], v[212:215], v[110:113]
	v_mfma_f32_16x16x32_bf16 v[102:105], v[134:137], v[220:223], v[102:105]
	v_mfma_f32_16x16x32_bf16 v[94:97], v[142:145], v[220:223], v[94:97]
	v_mfma_f32_16x16x32_bf16 v[86:89], v[134:137], v[234:237], v[86:89]
	v_mfma_f32_16x16x32_bf16 v[78:81], v[142:145], v[234:237], v[78:81]
	v_mfma_f32_16x16x32_bf16 v[114:117], v[146:149], v[182:185], v[114:117]
	v_mfma_f32_16x16x32_bf16 v[106:109], v[174:177], v[182:185], v[106:109]
	v_mfma_f32_16x16x32_bf16 v[98:101], v[146:149], v[208:211], v[98:101]
	v_mfma_f32_16x16x32_bf16 v[90:93], v[174:177], v[208:211], v[90:93]
	v_mfma_f32_16x16x32_bf16 v[82:85], v[146:149], v[216:219], v[82:85]
	v_mfma_f32_16x16x32_bf16 v[74:77], v[174:177], v[216:219], v[74:77]
	v_mfma_f32_16x16x32_bf16 v[70:73], v[146:149], v[224:227], v[70:73]
	v_mfma_f32_16x16x32_bf16 v[66:69], v[174:177], v[224:227], v[66:69]
	v_mfma_f32_16x16x32_bf16 v[114:117], v[150:153], v[204:207], v[114:117]
	v_mfma_f32_16x16x32_bf16 v[106:109], v[178:181], v[204:207], v[106:109]
	v_mfma_f32_16x16x32_bf16 v[98:101], v[150:153], v[212:215], v[98:101]
	v_mfma_f32_16x16x32_bf16 v[90:93], v[178:181], v[212:215], v[90:93]
	s_barrier
	s_setprio 2
	v_mfma_f32_16x16x32_bf16 v[82:85], v[150:153], v[220:223], v[82:85]
	v_mfma_f32_16x16x32_bf16 v[74:77], v[178:181], v[220:223], v[74:77]
	v_mfma_f32_16x16x32_bf16 v[70:73], v[150:153], v[234:237], v[70:73]
	v_mfma_f32_16x16x32_bf16 v[66:69], v[178:181], v[234:237], v[66:69]
	s_setprio 0
	s_cmp_eq_u32 s98, 1
	s_cbranch_scc0 .Lmy_pr_P1b_0
	s_setprio 1
.Lmy_pr_P1b_0:
	s_add_i32 s46, s52, s8
	v_lshl_add_u64 v[186:187], s[42:43], 0, v[158:159]
	s_mov_b32 m0, s46
	ds_read_b128 v[182:185], v193 offset:16384
	ds_read_b128 v[204:207], v193 offset:17408
	ds_read_b128 v[208:211], v193 offset:18432
	ds_read_b128 v[212:215], v193 offset:19456
	ds_read_b128 v[216:219], v193 offset:20480
	ds_read_b128 v[220:223], v193 offset:21504
	ds_read_b128 v[224:227], v193 offset:22528
	ds_read_b128 v[234:237], v193 offset:23552
	global_load_lds_dwordx4 v[186:187], off
	s_add_i32 m0, s46, 0x2000
	s_add_u32 s46, s42, 0x100000
	v_lshl_add_u64 v[194:195], s[42:43], 0, v[162:163]
	s_addc_u32 s47, s43, 0
	s_add_i32 s56, s53, s8
	global_load_lds_dwordx4 v[194:195], off
	v_lshl_add_u64 v[200:201], s[46:47], 0, v[158:159]
	s_mov_b32 m0, s56
	v_lshl_add_u64 v[238:239], s[44:45], 0, v[160:161]
	global_load_lds_dwordx4 v[200:201], off
	v_lshl_add_u64 v[200:201], s[46:47], 0, v[162:163]
	s_add_i32 m0, s56, 0x2000
	s_nop 0
	global_load_lds_dwordx4 v[200:201], off
	v_lshl_add_u64 v[200:201], s[44:45], 0, v[156:157]
	s_mov_b32 m0, s9
	s_nop 0
	global_load_lds_dwordx4 v[200:201], off
	s_mov_b32 m0, s13
	s_nop 0
	global_load_lds_dwordx4 v[238:239], off
	s_waitcnt vmcnt(8)
	s_waitcnt lgkmcnt(0)
	s_barrier
	s_waitcnt lgkmcnt(0)
	v_mfma_f32_16x16x32_bf16 v[62:65], v[130:133], v[182:185], v[62:65]
	v_mfma_f32_16x16x32_bf16 v[58:61], v[138:141], v[182:185], v[58:61]
	v_mfma_f32_16x16x32_bf16 v[54:57], v[130:133], v[208:211], v[54:57]
	v_mfma_f32_16x16x32_bf16 v[46:49], v[138:141], v[208:211], v[46:49]
	v_mfma_f32_16x16x32_bf16 v[38:41], v[130:133], v[216:219], v[38:41]
	v_mfma_f32_16x16x32_bf16 v[30:33], v[138:141], v[216:219], v[30:33]
	v_mfma_f32_16x16x32_bf16 v[22:25], v[130:133], v[224:227], v[22:25]
	v_mfma_f32_16x16x32_bf16 v[14:17], v[138:141], v[224:227], v[14:17]
	v_mfma_f32_16x16x32_bf16 v[62:65], v[134:137], v[204:207], v[62:65]
	v_mfma_f32_16x16x32_bf16 v[58:61], v[142:145], v[204:207], v[58:61]
	v_mfma_f32_16x16x32_bf16 v[54:57], v[134:137], v[212:215], v[54:57]
	v_mfma_f32_16x16x32_bf16 v[46:49], v[142:145], v[212:215], v[46:49]
	v_mfma_f32_16x16x32_bf16 v[38:41], v[134:137], v[220:223], v[38:41]
	v_mfma_f32_16x16x32_bf16 v[30:33], v[142:145], v[220:223], v[30:33]
	v_mfma_f32_16x16x32_bf16 v[22:25], v[134:137], v[234:237], v[22:25]
	v_mfma_f32_16x16x32_bf16 v[14:17], v[142:145], v[234:237], v[14:17]
	v_mfma_f32_16x16x32_bf16 v[50:53], v[146:149], v[182:185], v[50:53]
	v_mfma_f32_16x16x32_bf16 v[42:45], v[174:177], v[182:185], v[42:45]
	v_mfma_f32_16x16x32_bf16 v[34:37], v[146:149], v[208:211], v[34:37]
	v_mfma_f32_16x16x32_bf16 v[26:29], v[174:177], v[208:211], v[26:29]
	v_mfma_f32_16x16x32_bf16 v[18:21], v[146:149], v[216:219], v[18:21]
	v_mfma_f32_16x16x32_bf16 v[10:13], v[174:177], v[216:219], v[10:13]
	v_mfma_f32_16x16x32_bf16 v[6:9], v[146:149], v[224:227], v[6:9]
	v_mfma_f32_16x16x32_bf16 v[2:5], v[174:177], v[224:227], v[2:5]
	v_mfma_f32_16x16x32_bf16 v[50:53], v[150:153], v[204:207], v[50:53]
	v_mfma_f32_16x16x32_bf16 v[42:45], v[178:181], v[204:207], v[42:45]
	v_mfma_f32_16x16x32_bf16 v[34:37], v[150:153], v[212:215], v[34:37]
	v_mfma_f32_16x16x32_bf16 v[26:29], v[178:181], v[212:215], v[26:29]
	s_barrier
	s_setprio 2
	v_mfma_f32_16x16x32_bf16 v[18:21], v[150:153], v[220:223], v[18:21]
	v_mfma_f32_16x16x32_bf16 v[10:13], v[178:181], v[220:223], v[10:13]
	v_mfma_f32_16x16x32_bf16 v[6:9], v[150:153], v[234:237], v[6:9]
	v_mfma_f32_16x16x32_bf16 v[2:5], v[178:181], v[234:237], v[2:5]
	s_setprio 0
	s_cmp_eq_u32 s98, 1
	s_cbranch_scc0 .Lmy_pr_P1b_1
	s_setprio 1
.Lmy_pr_P1b_1:
	s_add_i32 s46, 0, 0x18000
	s_add_i32 s47, 0, 0x1c000
	v_add_u32_e32 v142, s46, v188
	v_add_u32_e32 v164, s47, v188
	ds_read_b128 v[130:133], v142
	ds_read_b128 v[134:137], v142 offset:1024
	ds_read_b128 v[138:141], v142 offset:2048
	ds_read_b128 v[142:145], v142 offset:3072
	ds_read_b128 v[146:149], v164
	ds_read_b128 v[150:153], v164 offset:1024
	ds_read_b128 v[174:177], v164 offset:2048
	ds_read_b128 v[178:181], v164 offset:3072
	s_add_u32 s44, s44, 0x100000
	s_addc_u32 s45, s45, 0
	s_mov_b32 m0, s33
	v_lshl_add_u64 v[240:241], s[44:45], 0, v[156:157]
	ds_read_b128 v[182:185], v193 offset:32768
	ds_read_b128 v[204:207], v193 offset:33792
	ds_read_b128 v[208:211], v193 offset:34816
	ds_read_b128 v[212:215], v193 offset:35840
	ds_read_b128 v[216:219], v193 offset:36864
	ds_read_b128 v[220:223], v193 offset:37888
	ds_read_b128 v[224:227], v193 offset:38912
	ds_read_b128 v[234:237], v193 offset:39936
	global_load_lds_dwordx4 v[240:241], off
	v_lshl_add_u64 v[240:241], s[44:45], 0, v[160:161]
	s_mov_b32 m0, s39
	s_nop 0
	global_load_lds_dwordx4 v[240:241], off
	s_waitcnt vmcnt(8)
	s_waitcnt lgkmcnt(0)
	s_barrier
	s_waitcnt lgkmcnt(0)
	v_mfma_f32_16x16x32_bf16 v[126:129], v[130:133], v[182:185], v[126:129]
	v_mfma_f32_16x16x32_bf16 v[122:125], v[138:141], v[182:185], v[122:125]
	v_mfma_f32_16x16x32_bf16 v[118:121], v[130:133], v[208:211], v[118:121]
	v_mfma_f32_16x16x32_bf16 v[110:113], v[138:141], v[208:211], v[110:113]
	v_mfma_f32_16x16x32_bf16 v[102:105], v[130:133], v[216:219], v[102:105]
	v_mfma_f32_16x16x32_bf16 v[94:97], v[138:141], v[216:219], v[94:97]
	v_mfma_f32_16x16x32_bf16 v[86:89], v[130:133], v[224:227], v[86:89]
	v_mfma_f32_16x16x32_bf16 v[78:81], v[138:141], v[224:227], v[78:81]
	v_mfma_f32_16x16x32_bf16 v[126:129], v[134:137], v[204:207], v[126:129]
	v_mfma_f32_16x16x32_bf16 v[122:125], v[142:145], v[204:207], v[122:125]
	v_mfma_f32_16x16x32_bf16 v[118:121], v[134:137], v[212:215], v[118:121]
	v_mfma_f32_16x16x32_bf16 v[110:113], v[142:145], v[212:215], v[110:113]
	v_mfma_f32_16x16x32_bf16 v[102:105], v[134:137], v[220:223], v[102:105]
	v_mfma_f32_16x16x32_bf16 v[94:97], v[142:145], v[220:223], v[94:97]
	v_mfma_f32_16x16x32_bf16 v[86:89], v[134:137], v[234:237], v[86:89]
	v_mfma_f32_16x16x32_bf16 v[78:81], v[142:145], v[234:237], v[78:81]
	v_mfma_f32_16x16x32_bf16 v[114:117], v[146:149], v[182:185], v[114:117]
	v_mfma_f32_16x16x32_bf16 v[106:109], v[174:177], v[182:185], v[106:109]
	v_mfma_f32_16x16x32_bf16 v[98:101], v[146:149], v[208:211], v[98:101]
	v_mfma_f32_16x16x32_bf16 v[90:93], v[174:177], v[208:211], v[90:93]
	v_mfma_f32_16x16x32_bf16 v[82:85], v[146:149], v[216:219], v[82:85]
	v_mfma_f32_16x16x32_bf16 v[74:77], v[174:177], v[216:219], v[74:77]
	v_mfma_f32_16x16x32_bf16 v[70:73], v[146:149], v[224:227], v[70:73]
	v_mfma_f32_16x16x32_bf16 v[66:69], v[174:177], v[224:227], v[66:69]
	v_mfma_f32_16x16x32_bf16 v[114:117], v[150:153], v[204:207], v[114:117]
	v_mfma_f32_16x16x32_bf16 v[106:109], v[178:181], v[204:207], v[106:109]
	v_mfma_f32_16x16x32_bf16 v[98:101], v[150:153], v[212:215], v[98:101]
	v_mfma_f32_16x16x32_bf16 v[90:93], v[178:181], v[212:215], v[90:93]
	s_barrier
	s_setprio 2
	v_mfma_f32_16x16x32_bf16 v[82:85], v[150:153], v[220:223], v[82:85]
	v_mfma_f32_16x16x32_bf16 v[74:77], v[178:181], v[220:223], v[74:77]
	v_mfma_f32_16x16x32_bf16 v[70:73], v[150:153], v[234:237], v[70:73]
	v_mfma_f32_16x16x32_bf16 v[66:69], v[178:181], v[234:237], v[66:69]
	s_setprio 0
	s_cmp_eq_u32 s98, 1
	s_cbranch_scc0 .Lmy_pr_P1b_2
	s_setprio 1
.Lmy_pr_P1b_2:
	s_add_i32 s44, s46, s8
	v_lshl_add_u64 v[186:187], v[186:187], 0, s[20:21]
	s_mov_b32 m0, s44
	ds_read_b128 v[182:185], v193 offset:49152
	ds_read_b128 v[204:207], v193 offset:50176
	ds_read_b128 v[208:211], v193 offset:51200
	ds_read_b128 v[212:215], v193 offset:52224
	ds_read_b128 v[216:219], v193 offset:53248
	ds_read_b128 v[220:223], v193 offset:54272
	ds_read_b128 v[224:227], v193 offset:55296
	ds_read_b128 v[234:237], v193 offset:56320
	global_load_lds_dwordx4 v[186:187], off
	s_add_i32 m0, s44, 0x2000
	s_add_u32 s42, s42, 0x100080
	v_lshl_add_u64 v[186:187], v[194:195], 0, s[20:21]
	s_addc_u32 s43, s43, 0
	s_add_i32 s44, s47, s8
	global_load_lds_dwordx4 v[186:187], off
	v_lshl_add_u64 v[186:187], s[42:43], 0, v[158:159]
	s_mov_b32 m0, s44
	s_nop 0
	global_load_lds_dwordx4 v[186:187], off
	v_lshl_add_u64 v[186:187], s[42:43], 0, v[162:163]
	s_add_i32 m0, s44, 0x2000
	s_nop 0
	global_load_lds_dwordx4 v[186:187], off
	v_lshl_add_u64 v[186:187], v[200:201], 0, s[20:21]
	s_mov_b32 m0, s50
	s_nop 0
	global_load_lds_dwordx4 v[186:187], off
	v_lshl_add_u64 v[186:187], v[238:239], 0, s[20:21]
	s_mov_b32 m0, s51
	s_nop 0
	global_load_lds_dwordx4 v[186:187], off
	s_waitcnt vmcnt(8)
	s_waitcnt lgkmcnt(0)
	s_barrier
	s_waitcnt lgkmcnt(0)
	v_mfma_f32_16x16x32_bf16 v[62:65], v[130:133], v[182:185], v[62:65]
	v_mfma_f32_16x16x32_bf16 v[58:61], v[138:141], v[182:185], v[58:61]
	v_mfma_f32_16x16x32_bf16 v[54:57], v[130:133], v[208:211], v[54:57]
	v_mfma_f32_16x16x32_bf16 v[46:49], v[138:141], v[208:211], v[46:49]
	v_mfma_f32_16x16x32_bf16 v[38:41], v[130:133], v[216:219], v[38:41]
	v_mfma_f32_16x16x32_bf16 v[30:33], v[138:141], v[216:219], v[30:33]
	v_mfma_f32_16x16x32_bf16 v[22:25], v[130:133], v[224:227], v[22:25]
	v_mfma_f32_16x16x32_bf16 v[14:17], v[138:141], v[224:227], v[14:17]
	v_mfma_f32_16x16x32_bf16 v[62:65], v[134:137], v[204:207], v[62:65]
	v_mfma_f32_16x16x32_bf16 v[58:61], v[142:145], v[204:207], v[58:61]
	v_mfma_f32_16x16x32_bf16 v[54:57], v[134:137], v[212:215], v[54:57]
	v_mfma_f32_16x16x32_bf16 v[46:49], v[142:145], v[212:215], v[46:49]
	v_mfma_f32_16x16x32_bf16 v[38:41], v[134:137], v[220:223], v[38:41]
	v_mfma_f32_16x16x32_bf16 v[30:33], v[142:145], v[220:223], v[30:33]
	v_mfma_f32_16x16x32_bf16 v[22:25], v[134:137], v[234:237], v[22:25]
	v_mfma_f32_16x16x32_bf16 v[14:17], v[142:145], v[234:237], v[14:17]
	v_mfma_f32_16x16x32_bf16 v[50:53], v[146:149], v[182:185], v[50:53]
	v_mfma_f32_16x16x32_bf16 v[42:45], v[174:177], v[182:185], v[42:45]
	v_mfma_f32_16x16x32_bf16 v[34:37], v[146:149], v[208:211], v[34:37]
	v_mfma_f32_16x16x32_bf16 v[26:29], v[174:177], v[208:211], v[26:29]
	v_mfma_f32_16x16x32_bf16 v[18:21], v[146:149], v[216:219], v[18:21]
	v_mfma_f32_16x16x32_bf16 v[10:13], v[174:177], v[216:219], v[10:13]
	v_mfma_f32_16x16x32_bf16 v[6:9], v[146:149], v[224:227], v[6:9]
	v_mfma_f32_16x16x32_bf16 v[2:5], v[174:177], v[224:227], v[2:5]
	v_mfma_f32_16x16x32_bf16 v[50:53], v[150:153], v[204:207], v[50:53]
	v_mfma_f32_16x16x32_bf16 v[42:45], v[178:181], v[204:207], v[42:45]
	v_mfma_f32_16x16x32_bf16 v[34:37], v[150:153], v[212:215], v[34:37]
	v_mfma_f32_16x16x32_bf16 v[26:29], v[178:181], v[212:215], v[26:29]
	s_barrier
	s_setprio 2
	v_mfma_f32_16x16x32_bf16 v[18:21], v[150:153], v[220:223], v[18:21]
	v_mfma_f32_16x16x32_bf16 v[10:13], v[178:181], v[220:223], v[10:13]
	v_mfma_f32_16x16x32_bf16 v[6:9], v[150:153], v[234:237], v[6:9]
	v_mfma_f32_16x16x32_bf16 v[2:5], v[178:181], v[234:237], v[2:5]
	s_setprio 0
	s_cmp_eq_u32 s98, 1
	s_cbranch_scc0 .Lmy_pr_P1b_3
	s_setprio 1
.Lmy_pr_P1b_3:
	s_add_i32 s29, s29, 2
	s_add_u32 s40, s40, 0x100
	s_addc_u32 s41, s41, 0
	s_add_u32 s15, s15, 0x100
	s_addc_u32 s27, s27, 0
	s_cmp_gt_u32 s29, 61
	s_cbranch_scc0 .LBB0_412
	s_and_b64 vcc, exec, s[22:23]
	s_cbranch_vccz .LBB0_415
	s_barrier

.LBB0_514:
	ds_read_b128 v[156:159], v146
	ds_read_b128 v[160:163], v146 offset:1024
	ds_read_b128 v[164:167], v146 offset:2048
	ds_read_b128 v[168:171], v146 offset:3072
	ds_read_b128 v[172:175], v147
	s_waitcnt lgkmcnt(0)
	ds_read_b128 v[176:179], v147 offset:1024
	ds_read_b128 v[180:183], v147 offset:2048
	ds_read_b128 v[184:187], v147 offset:3072
	s_add_u32 s28, s26, 0xfff00080
	s_addc_u32 s29, s27, -1
	s_cmp_eq_u32 s50, 4
	s_cselect_b32 s31, s19, s29
	s_cselect_b32 s30, s18, s28
	s_cselect_b32 s29, s21, s49
	s_cselect_b32 s28, s20, s23
	s_mov_b32 m0, s36
	v_lshl_add_u64 v[142:143], s[26:27], 0, v[138:139]
	ds_read_b128 v[190:193], v148
	ds_read_b128 v[204:207], v148 offset:1024
	ds_read_b128 v[208:211], v148 offset:2048
	ds_read_b128 v[212:215], v148 offset:3072
	ds_read_b128 v[216:219], v148 offset:4096
	ds_read_b128 v[220:223], v148 offset:5120
	ds_read_b128 v[224:227], v148 offset:6144
	ds_read_b128 v[234:237], v148 offset:7168
	global_load_lds_dwordx4 v[142:143], off
	v_lshl_add_u64 v[142:143], s[26:27], 0, v[140:141]
	s_mov_b32 m0, s37
	s_nop 0
	global_load_lds_dwordx4 v[142:143], off
	s_waitcnt vmcnt(8)
	s_waitcnt lgkmcnt(0)
	s_barrier
	s_waitcnt lgkmcnt(0)
	v_mfma_f32_16x16x32_bf16 v[126:129], v[156:159], v[190:193], v[126:129]
	v_mfma_f32_16x16x32_bf16 v[122:125], v[164:167], v[190:193], v[122:125]
	v_mfma_f32_16x16x32_bf16 v[118:121], v[156:159], v[208:211], v[118:121]
	v_mfma_f32_16x16x32_bf16 v[110:113], v[164:167], v[208:211], v[110:113]
	v_mfma_f32_16x16x32_bf16 v[102:105], v[156:159], v[216:219], v[102:105]
	v_mfma_f32_16x16x32_bf16 v[94:97], v[164:167], v[216:219], v[94:97]
	v_mfma_f32_16x16x32_bf16 v[82:85], v[156:159], v[224:227], v[82:85]
	v_mfma_f32_16x16x32_bf16 v[74:77], v[164:167], v[224:227], v[74:77]
	v_mfma_f32_16x16x32_bf16 v[126:129], v[160:163], v[204:207], v[126:129]
	v_mfma_f32_16x16x32_bf16 v[122:125], v[168:171], v[204:207], v[122:125]
	v_mfma_f32_16x16x32_bf16 v[118:121], v[160:163], v[212:215], v[118:121]
	v_mfma_f32_16x16x32_bf16 v[110:113], v[168:171], v[212:215], v[110:113]
	v_mfma_f32_16x16x32_bf16 v[102:105], v[160:163], v[220:223], v[102:105]
	v_mfma_f32_16x16x32_bf16 v[94:97], v[168:171], v[220:223], v[94:97]
	v_mfma_f32_16x16x32_bf16 v[82:85], v[160:163], v[234:237], v[82:85]
	v_mfma_f32_16x16x32_bf16 v[74:77], v[168:171], v[234:237], v[74:77]
	v_mfma_f32_16x16x32_bf16 v[114:117], v[172:175], v[190:193], v[114:117]
	v_mfma_f32_16x16x32_bf16 v[106:109], v[180:183], v[190:193], v[106:109]
	v_mfma_f32_16x16x32_bf16 v[98:101], v[172:175], v[208:211], v[98:101]
	v_mfma_f32_16x16x32_bf16 v[90:93], v[180:183], v[208:211], v[90:93]
	v_mfma_f32_16x16x32_bf16 v[86:89], v[172:175], v[216:219], v[86:89]
	v_mfma_f32_16x16x32_bf16 v[78:81], v[180:183], v[216:219], v[78:81]
	v_mfma_f32_16x16x32_bf16 v[70:73], v[172:175], v[224:227], v[70:73]
	v_mfma_f32_16x16x32_bf16 v[66:69], v[180:183], v[224:227], v[66:69]
	v_mfma_f32_16x16x32_bf16 v[114:117], v[176:179], v[204:207], v[114:117]
	v_mfma_f32_16x16x32_bf16 v[106:109], v[184:187], v[204:207], v[106:109]
	v_mfma_f32_16x16x32_bf16 v[98:101], v[176:179], v[212:215], v[98:101]
	v_mfma_f32_16x16x32_bf16 v[90:93], v[184:187], v[212:215], v[90:93]
	s_barrier
	s_setprio 2
	v_mfma_f32_16x16x32_bf16 v[86:89], v[176:179], v[220:223], v[86:89]
	v_mfma_f32_16x16x32_bf16 v[78:81], v[184:187], v[220:223], v[78:81]
	v_mfma_f32_16x16x32_bf16 v[70:73], v[176:179], v[234:237], v[70:73]
	v_mfma_f32_16x16x32_bf16 v[66:69], v[184:187], v[234:237], v[66:69]
	s_setprio 0
	s_cmp_eq_u32 s98, 1
	s_cbranch_scc0 .Lmy_pr_Fold_0
	s_setprio 1
.Lmy_pr_Fold_0:
	s_mov_b32 m0, s38
	v_lshl_add_u64 v[142:143], s[28:29], 0, v[134:135]
	s_add_u32 s52, s28, 0x20000
	ds_read_b128 v[190:193], v148 offset:16384
	ds_read_b128 v[204:207], v148 offset:17408
	ds_read_b128 v[208:211], v148 offset:18432
	ds_read_b128 v[212:215], v148 offset:19456
	ds_read_b128 v[216:219], v148 offset:20480
	ds_read_b128 v[220:223], v148 offset:21504
	ds_read_b128 v[224:227], v148 offset:22528
	ds_read_b128 v[234:237], v148 offset:23552
	global_load_lds_dwordx4 v[142:143], off
	v_lshl_add_u64 v[152:153], s[28:29], 0, v[130:131]
	s_mov_b32 m0, s39
	s_addc_u32 s53, s29, 0
	global_load_lds_dwordx4 v[152:153], off
	v_lshl_add_u64 v[194:195], s[52:53], 0, v[134:135]
	s_mov_b32 m0, s40
	v_lshl_add_u64 v[200:201], s[30:31], 0, v[132:133]
	global_load_lds_dwordx4 v[194:195], off
	v_lshl_add_u64 v[194:195], s[52:53], 0, v[130:131]
	s_mov_b32 m0, s41
	s_nop 0
	global_load_lds_dwordx4 v[194:195], off
	v_lshl_add_u64 v[194:195], s[30:31], 0, v[136:137]
	s_mov_b32 m0, s9
	s_nop 0
	global_load_lds_dwordx4 v[194:195], off
	s_mov_b32 m0, s13
	s_nop 0
	global_load_lds_dwordx4 v[200:201], off
	s_waitcnt vmcnt(8)
	s_waitcnt lgkmcnt(0)
	s_barrier
	s_waitcnt lgkmcnt(0)
	v_mfma_f32_16x16x32_bf16 v[62:65], v[156:159], v[190:193], v[62:65]
	v_mfma_f32_16x16x32_bf16 v[58:61], v[164:167], v[190:193], v[58:61]
	v_mfma_f32_16x16x32_bf16 v[54:57], v[156:159], v[208:211], v[54:57]
	v_mfma_f32_16x16x32_bf16 v[46:49], v[164:167], v[208:211], v[46:49]
	v_mfma_f32_16x16x32_bf16 v[38:41], v[156:159], v[216:219], v[38:41]
	v_mfma_f32_16x16x32_bf16 v[30:33], v[164:167], v[216:219], v[30:33]
	v_mfma_f32_16x16x32_bf16 v[22:25], v[156:159], v[224:227], v[22:25]
	v_mfma_f32_16x16x32_bf16 v[14:17], v[164:167], v[224:227], v[14:17]
	v_mfma_f32_16x16x32_bf16 v[62:65], v[160:163], v[204:207], v[62:65]
	v_mfma_f32_16x16x32_bf16 v[58:61], v[168:171], v[204:207], v[58:61]
	v_mfma_f32_16x16x32_bf16 v[54:57], v[160:163], v[212:215], v[54:57]
	v_mfma_f32_16x16x32_bf16 v[46:49], v[168:171], v[212:215], v[46:49]
	v_mfma_f32_16x16x32_bf16 v[38:41], v[160:163], v[220:223], v[38:41]
	v_mfma_f32_16x16x32_bf16 v[30:33], v[168:171], v[220:223], v[30:33]
	v_mfma_f32_16x16x32_bf16 v[22:25], v[160:163], v[234:237], v[22:25]
	v_mfma_f32_16x16x32_bf16 v[14:17], v[168:171], v[234:237], v[14:17]
	v_mfma_f32_16x16x32_bf16 v[50:53], v[172:175], v[190:193], v[50:53]
	v_mfma_f32_16x16x32_bf16 v[42:45], v[180:183], v[190:193], v[42:45]
	v_mfma_f32_16x16x32_bf16 v[34:37], v[172:175], v[208:211], v[34:37]
	v_mfma_f32_16x16x32_bf16 v[26:29], v[180:183], v[208:211], v[26:29]
	v_mfma_f32_16x16x32_bf16 v[18:21], v[172:175], v[216:219], v[18:21]
	v_mfma_f32_16x16x32_bf16 v[10:13], v[180:183], v[216:219], v[10:13]
	v_mfma_f32_16x16x32_bf16 v[6:9], v[172:175], v[224:227], v[6:9]
	v_mfma_f32_16x16x32_bf16 v[2:5], v[180:183], v[224:227], v[2:5]
	v_mfma_f32_16x16x32_bf16 v[50:53], v[176:179], v[204:207], v[50:53]
	v_mfma_f32_16x16x32_bf16 v[42:45], v[184:187], v[204:207], v[42:45]
	v_mfma_f32_16x16x32_bf16 v[34:37], v[176:179], v[212:215], v[34:37]
	v_mfma_f32_16x16x32_bf16 v[26:29], v[184:187], v[212:215], v[26:29]
	s_barrier
	s_setprio 2
	v_mfma_f32_16x16x32_bf16 v[18:21], v[176:179], v[220:223], v[18:21]
	v_mfma_f32_16x16x32_bf16 v[10:13], v[184:187], v[220:223], v[10:13]
	v_mfma_f32_16x16x32_bf16 v[6:9], v[176:179], v[234:237], v[6:9]
	v_mfma_f32_16x16x32_bf16 v[2:5], v[184:187], v[234:237], v[2:5]
	s_setprio 0
	s_cmp_eq_u32 s98, 1
	s_cbranch_scc0 .Lmy_pr_Fold_1
	s_setprio 1
.Lmy_pr_Fold_1:
	ds_read_b128 v[156:159], v149
	ds_read_b128 v[160:163], v149 offset:1024
	ds_read_b128 v[164:167], v149 offset:2048
	ds_read_b128 v[168:171], v149 offset:3072
	ds_read_b128 v[172:175], v150
	ds_read_b128 v[176:179], v150 offset:1024
	ds_read_b128 v[180:183], v150 offset:2048
	ds_read_b128 v[184:187], v150 offset:3072
	s_add_u32 s30, s30, 0x100000
	s_addc_u32 s31, s31, 0
	s_mov_b32 m0, s14
	v_lshl_add_u64 v[238:239], s[30:31], 0, v[136:137]
	ds_read_b128 v[190:193], v148 offset:32768
	ds_read_b128 v[204:207], v148 offset:33792
	ds_read_b128 v[208:211], v148 offset:34816
	ds_read_b128 v[212:215], v148 offset:35840
	ds_read_b128 v[216:219], v148 offset:36864
	ds_read_b128 v[220:223], v148 offset:37888
	ds_read_b128 v[224:227], v148 offset:38912
	ds_read_b128 v[234:237], v148 offset:39936
	global_load_lds_dwordx4 v[238:239], off
	v_lshl_add_u64 v[238:239], s[30:31], 0, v[132:133]
	s_mov_b32 m0, s15
	s_nop 0
	global_load_lds_dwordx4 v[238:239], off
	s_waitcnt vmcnt(8)
	s_waitcnt lgkmcnt(0)
	s_barrier
	s_waitcnt lgkmcnt(0)
	v_mfma_f32_16x16x32_bf16 v[126:129], v[156:159], v[190:193], v[126:129]
	v_mfma_f32_16x16x32_bf16 v[122:125], v[164:167], v[190:193], v[122:125]
	v_mfma_f32_16x16x32_bf16 v[118:121], v[156:159], v[208:211], v[118:121]
	v_mfma_f32_16x16x32_bf16 v[110:113], v[164:167], v[208:211], v[110:113]
	v_mfma_f32_16x16x32_bf16 v[102:105], v[156:159], v[216:219], v[102:105]
	v_mfma_f32_16x16x32_bf16 v[94:97], v[164:167], v[216:219], v[94:97]
	v_mfma_f32_16x16x32_bf16 v[82:85], v[156:159], v[224:227], v[82:85]
	v_mfma_f32_16x16x32_bf16 v[74:77], v[164:167], v[224:227], v[74:77]
	v_mfma_f32_16x16x32_bf16 v[126:129], v[160:163], v[204:207], v[126:129]
	v_mfma_f32_16x16x32_bf16 v[122:125], v[168:171], v[204:207], v[122:125]
	v_mfma_f32_16x16x32_bf16 v[118:121], v[160:163], v[212:215], v[118:121]
	v_mfma_f32_16x16x32_bf16 v[110:113], v[168:171], v[212:215], v[110:113]
	v_mfma_f32_16x16x32_bf16 v[102:105], v[160:163], v[220:223], v[102:105]
	v_mfma_f32_16x16x32_bf16 v[94:97], v[168:171], v[220:223], v[94:97]
	v_mfma_f32_16x16x32_bf16 v[82:85], v[160:163], v[234:237], v[82:85]
	v_mfma_f32_16x16x32_bf16 v[74:77], v[168:171], v[234:237], v[74:77]
	v_mfma_f32_16x16x32_bf16 v[114:117], v[172:175], v[190:193], v[114:117]
	v_mfma_f32_16x16x32_bf16 v[106:109], v[180:183], v[190:193], v[106:109]
	v_mfma_f32_16x16x32_bf16 v[98:101], v[172:175], v[208:211], v[98:101]
	v_mfma_f32_16x16x32_bf16 v[90:93], v[180:183], v[208:211], v[90:93]
	v_mfma_f32_16x16x32_bf16 v[86:89], v[172:175], v[216:219], v[86:89]
	v_mfma_f32_16x16x32_bf16 v[78:81], v[180:183], v[216:219], v[78:81]
	v_mfma_f32_16x16x32_bf16 v[70:73], v[172:175], v[224:227], v[70:73]
	v_mfma_f32_16x16x32_bf16 v[66:69], v[180:183], v[224:227], v[66:69]
	v_mfma_f32_16x16x32_bf16 v[114:117], v[176:179], v[204:207], v[114:117]
	v_mfma_f32_16x16x32_bf16 v[106:109], v[184:187], v[204:207], v[106:109]
	v_mfma_f32_16x16x32_bf16 v[98:101], v[176:179], v[212:215], v[98:101]
	v_mfma_f32_16x16x32_bf16 v[90:93], v[184:187], v[212:215], v[90:93]
	s_barrier
	s_setprio 2
	v_mfma_f32_16x16x32_bf16 v[86:89], v[176:179], v[220:223], v[86:89]
	v_mfma_f32_16x16x32_bf16 v[78:81], v[184:187], v[220:223], v[78:81]
	v_mfma_f32_16x16x32_bf16 v[70:73], v[176:179], v[234:237], v[70:73]
	v_mfma_f32_16x16x32_bf16 v[66:69], v[184:187], v[234:237], v[66:69]
	s_setprio 0
	s_cmp_eq_u32 s98, 1
	s_cbranch_scc0 .Lmy_pr_Fold_2
	s_setprio 1
.Lmy_pr_Fold_2:
	s_mov_b32 m0, s42
	v_lshl_add_u64 v[142:143], v[142:143], 0, s[4:5]
	s_add_u32 s28, s28, 0x20080
	ds_read_b128 v[190:193], v148 offset:49152
	ds_read_b128 v[204:207], v148 offset:50176
	ds_read_b128 v[208:211], v148 offset:51200
	ds_read_b128 v[212:215], v148 offset:52224
	ds_read_b128 v[216:219], v148 offset:53248
	ds_read_b128 v[220:223], v148 offset:54272
	ds_read_b128 v[224:227], v148 offset:55296
	ds_read_b128 v[234:237], v148 offset:56320
	global_load_lds_dwordx4 v[142:143], off
	v_lshl_add_u64 v[142:143], v[152:153], 0, s[4:5]
	s_mov_b32 m0, s43
	s_addc_u32 s29, s29, 0
	global_load_lds_dwordx4 v[142:143], off
	v_lshl_add_u64 v[142:143], s[28:29], 0, v[134:135]
	s_mov_b32 m0, s44
	s_nop 0
	global_load_lds_dwordx4 v[142:143], off
	v_lshl_add_u64 v[142:143], s[28:29], 0, v[130:131]
	s_mov_b32 m0, s45
	s_nop 0
	global_load_lds_dwordx4 v[142:143], off
	v_lshl_add_u64 v[142:143], v[194:195], 0, s[4:5]
	s_mov_b32 m0, s34
	s_nop 0
	global_load_lds_dwordx4 v[142:143], off
	v_lshl_add_u64 v[142:143], v[200:201], 0, s[4:5]
	s_mov_b32 m0, s35
	s_nop 0
	global_load_lds_dwordx4 v[142:143], off
	s_waitcnt vmcnt(8)
	s_waitcnt lgkmcnt(0)
	s_barrier
	s_waitcnt lgkmcnt(0)
	v_mfma_f32_16x16x32_bf16 v[62:65], v[156:159], v[190:193], v[62:65]
	v_mfma_f32_16x16x32_bf16 v[58:61], v[164:167], v[190:193], v[58:61]
	v_mfma_f32_16x16x32_bf16 v[54:57], v[156:159], v[208:211], v[54:57]
	v_mfma_f32_16x16x32_bf16 v[46:49], v[164:167], v[208:211], v[46:49]
	v_mfma_f32_16x16x32_bf16 v[38:41], v[156:159], v[216:219], v[38:41]
	v_mfma_f32_16x16x32_bf16 v[30:33], v[164:167], v[216:219], v[30:33]
	v_mfma_f32_16x16x32_bf16 v[22:25], v[156:159], v[224:227], v[22:25]
	v_mfma_f32_16x16x32_bf16 v[14:17], v[164:167], v[224:227], v[14:17]
	v_mfma_f32_16x16x32_bf16 v[62:65], v[160:163], v[204:207], v[62:65]
	v_mfma_f32_16x16x32_bf16 v[58:61], v[168:171], v[204:207], v[58:61]
	v_mfma_f32_16x16x32_bf16 v[54:57], v[160:163], v[212:215], v[54:57]
	v_mfma_f32_16x16x32_bf16 v[46:49], v[168:171], v[212:215], v[46:49]
	v_mfma_f32_16x16x32_bf16 v[38:41], v[160:163], v[220:223], v[38:41]
	v_mfma_f32_16x16x32_bf16 v[30:33], v[168:171], v[220:223], v[30:33]
	v_mfma_f32_16x16x32_bf16 v[22:25], v[160:163], v[234:237], v[22:25]
	v_mfma_f32_16x16x32_bf16 v[14:17], v[168:171], v[234:237], v[14:17]
	v_mfma_f32_16x16x32_bf16 v[50:53], v[172:175], v[190:193], v[50:53]
	v_mfma_f32_16x16x32_bf16 v[42:45], v[180:183], v[190:193], v[42:45]
	v_mfma_f32_16x16x32_bf16 v[34:37], v[172:175], v[208:211], v[34:37]
	v_mfma_f32_16x16x32_bf16 v[26:29], v[180:183], v[208:211], v[26:29]
	v_mfma_f32_16x16x32_bf16 v[18:21], v[172:175], v[216:219], v[18:21]
	v_mfma_f32_16x16x32_bf16 v[10:13], v[180:183], v[216:219], v[10:13]
	v_mfma_f32_16x16x32_bf16 v[6:9], v[172:175], v[224:227], v[6:9]
	v_mfma_f32_16x16x32_bf16 v[2:5], v[180:183], v[224:227], v[2:5]
	v_mfma_f32_16x16x32_bf16 v[50:53], v[176:179], v[204:207], v[50:53]
	v_mfma_f32_16x16x32_bf16 v[42:45], v[184:187], v[204:207], v[42:45]
	v_mfma_f32_16x16x32_bf16 v[34:37], v[176:179], v[212:215], v[34:37]
	v_mfma_f32_16x16x32_bf16 v[26:29], v[184:187], v[212:215], v[26:29]
	s_barrier
	s_setprio 2
	v_mfma_f32_16x16x32_bf16 v[18:21], v[176:179], v[220:223], v[18:21]
	v_mfma_f32_16x16x32_bf16 v[10:13], v[184:187], v[220:223], v[10:13]
	v_mfma_f32_16x16x32_bf16 v[6:9], v[176:179], v[234:237], v[6:9]
	v_mfma_f32_16x16x32_bf16 v[2:5], v[184:187], v[234:237], v[2:5]
	s_setprio 0
	s_cmp_eq_u32 s98, 1
	s_cbranch_scc0 .Lmy_pr_Fold_3
	s_setprio 1
.Lmy_pr_Fold_3:
	s_add_i32 s50, s50, 2
	s_add_u32 s26, s26, 0x100
	s_addc_u32 s27, s27, 0
	s_add_u32 s23, s23, 0x100
	s_addc_u32 s49, s49, 0
	s_cmp_gt_u32 s50, 5
	s_cbranch_scc0 .LBB0_514
	s_and_b64 vcc, exec, s[6:7]
	s_cbranch_vccz .LBB0_517
	s_barrier

.LBB0_734:
	ds_read_b128 v[158:161], v227
	ds_read_b128 v[154:157], v227 offset:1024
	ds_read_b128 v[150:153], v227 offset:2048
	ds_read_b128 v[146:149], v227 offset:3072
	ds_read_b128 v[62:65], v233
	ds_read_b128 v[58:61], v233 offset:1024
	ds_read_b128 v[54:57], v233 offset:2048
	ds_read_b128 v[50:53], v233 offset:3072
	s_add_u32 s14, s30, s34
	s_addc_u32 s15, s31, s35
	s_add_u32 s14, s14, 0x100
	s_addc_u32 s15, s15, 0
	s_add_u32 s25, s77, s34
	s_addc_u32 s29, s78, s35
	s_cmpk_eq_i32 s34, 0xf00
	s_cselect_b32 s41, s31, s15
	s_cselect_b32 s40, s30, s14
	s_cselect_b32 s39, s1, s29
	s_cselect_b32 s38, s0, s25
	s_add_i32 s66, s23, 0xc000
	v_lshl_add_u64 v[240:241], v[162:163], 0, s[34:35]
	s_mov_b32 m0, s66
	s_add_i32 s67, s23, 0xe000
	ds_read_b128 v[166:169], v226
	ds_read_b128 v[170:173], v226 offset:1024
	ds_read_b128 v[174:177], v226 offset:2048
	ds_read_b128 v[178:181], v226 offset:3072
	ds_read_b128 v[182:185], v226 offset:4096
	ds_read_b128 v[186:189], v226 offset:5120
	ds_read_b128 v[190:193], v226 offset:6144
	ds_read_b128 v[236:239], v226 offset:7168
	global_load_lds_dwordx4 v[240:241], off
	v_lshl_add_u64 v[240:241], v[164:165], 0, s[34:35]
	s_mov_b32 m0, s67
	s_nop 0
	global_load_lds_dwordx4 v[240:241], off
	s_waitcnt vmcnt(8)
	s_waitcnt lgkmcnt(0)
	s_barrier
	s_waitcnt lgkmcnt(0)
	v_mfma_i32_16x16x64_i8 v[142:145], v[158:161], v[166:169], v[142:145]
	v_mfma_i32_16x16x64_i8 v[142:145], v[154:157], v[170:173], v[142:145]
	v_mfma_i32_16x16x64_i8 v[138:141], v[150:153], v[166:169], v[138:141]
	v_mfma_i32_16x16x64_i8 v[138:141], v[146:149], v[170:173], v[138:141]
	v_mfma_i32_16x16x64_i8 v[126:129], v[158:161], v[174:177], v[126:129]
	v_mfma_i32_16x16x64_i8 v[126:129], v[154:157], v[178:181], v[126:129]
	v_mfma_i32_16x16x64_i8 v[122:125], v[150:153], v[174:177], v[122:125]
	v_mfma_i32_16x16x64_i8 v[122:125], v[146:149], v[178:181], v[122:125]
	v_mfma_i32_16x16x64_i8 v[110:113], v[158:161], v[182:185], v[110:113]
	v_mfma_i32_16x16x64_i8 v[110:113], v[154:157], v[186:189], v[110:113]
	v_mfma_i32_16x16x64_i8 v[106:109], v[150:153], v[182:185], v[106:109]
	v_mfma_i32_16x16x64_i8 v[106:109], v[146:149], v[186:189], v[106:109]
	v_mfma_i32_16x16x64_i8 v[94:97], v[158:161], v[190:193], v[94:97]
	v_mfma_i32_16x16x64_i8 v[94:97], v[154:157], v[236:239], v[94:97]
	v_mfma_i32_16x16x64_i8 v[90:93], v[150:153], v[190:193], v[90:93]
	v_mfma_i32_16x16x64_i8 v[90:93], v[146:149], v[236:239], v[90:93]
	v_mfma_i32_16x16x64_i8 v[134:137], v[62:65], v[166:169], v[134:137]
	v_mfma_i32_16x16x64_i8 v[134:137], v[58:61], v[170:173], v[134:137]
	v_mfma_i32_16x16x64_i8 v[130:133], v[54:57], v[166:169], v[130:133]
	v_mfma_i32_16x16x64_i8 v[130:133], v[50:53], v[170:173], v[130:133]
	v_mfma_i32_16x16x64_i8 v[118:121], v[62:65], v[174:177], v[118:121]
	v_mfma_i32_16x16x64_i8 v[118:121], v[58:61], v[178:181], v[118:121]
	v_mfma_i32_16x16x64_i8 v[114:117], v[54:57], v[174:177], v[114:117]
	v_mfma_i32_16x16x64_i8 v[114:117], v[50:53], v[178:181], v[114:117]
	v_mfma_i32_16x16x64_i8 v[102:105], v[62:65], v[182:185], v[102:105]
	v_mfma_i32_16x16x64_i8 v[102:105], v[58:61], v[186:189], v[102:105]
	v_mfma_i32_16x16x64_i8 v[98:101], v[54:57], v[182:185], v[98:101]
	v_mfma_i32_16x16x64_i8 v[98:101], v[50:53], v[186:189], v[98:101]
	s_barrier
	s_setprio 2
	v_mfma_i32_16x16x64_i8 v[86:89], v[62:65], v[190:193], v[86:89]
	v_mfma_i32_16x16x64_i8 v[86:89], v[58:61], v[236:239], v[86:89]
	v_mfma_i32_16x16x64_i8 v[82:85], v[54:57], v[190:193], v[82:85]
	v_mfma_i32_16x16x64_i8 v[82:85], v[50:53], v[236:239], v[82:85]
	s_setprio 0
	s_cmp_eq_u32 s98, 1
	s_cbranch_scc0 .Lmy_pr_P3a_0
	s_setprio 1
.Lmy_pr_P3a_0:
	s_add_i32 s68, s60, s21
	s_add_i32 s69, s68, 0x2000
	v_lshl_add_u64 v[166:167], s[38:39], 0, v[202:203]
	s_mov_b32 m0, s68
	s_add_u32 s14, s38, 0x80000
	ds_read_b128 v[174:177], v226 offset:16384
	ds_read_b128 v[178:181], v226 offset:17408
	ds_read_b128 v[182:185], v226 offset:18432
	ds_read_b128 v[186:189], v226 offset:19456
	ds_read_b128 v[190:193], v226 offset:20480
	ds_read_b128 v[236:239], v226 offset:21504
	ds_read_b128 v[240:243], v226 offset:22528
	ds_read_b128 v[244:247], v226 offset:23552
	global_load_lds_dwordx4 v[166:167], off
	v_lshl_add_u64 v[168:169], s[38:39], 0, v[206:207]
	s_mov_b32 m0, s69
	s_addc_u32 s15, s39, 0
	s_add_i32 s70, s61, s21
	global_load_lds_dwordx4 v[168:169], off
	v_lshl_add_u64 v[170:171], s[14:15], 0, v[202:203]
	s_mov_b32 m0, s70
	s_add_i32 s71, s70, 0x2000
	global_load_lds_dwordx4 v[170:171], off
	v_lshl_add_u64 v[170:171], s[14:15], 0, v[206:207]
	s_mov_b32 m0, s71
	v_lshl_add_u64 v[172:173], s[40:41], 0, v[204:205]
	global_load_lds_dwordx4 v[170:171], off
	v_lshl_add_u64 v[170:171], s[40:41], 0, v[194:195]
	s_mov_b32 m0, s23
	s_nop 0
	global_load_lds_dwordx4 v[170:171], off
	s_mov_b32 m0, s42
	s_nop 0
	global_load_lds_dwordx4 v[172:173], off
	s_waitcnt vmcnt(8)
	s_waitcnt lgkmcnt(0)
	s_barrier
	s_waitcnt lgkmcnt(0)
	v_mfma_i32_16x16x64_i8 v[78:81], v[158:161], v[174:177], v[78:81]
	v_mfma_i32_16x16x64_i8 v[78:81], v[154:157], v[178:181], v[78:81]
	v_mfma_i32_16x16x64_i8 v[74:77], v[150:153], v[174:177], v[74:77]
	v_mfma_i32_16x16x64_i8 v[74:77], v[146:149], v[178:181], v[74:77]
	v_mfma_i32_16x16x64_i8 v[46:49], v[158:161], v[182:185], v[46:49]
	v_mfma_i32_16x16x64_i8 v[46:49], v[154:157], v[186:189], v[46:49]
	v_mfma_i32_16x16x64_i8 v[42:45], v[150:153], v[182:185], v[42:45]
	v_mfma_i32_16x16x64_i8 v[42:45], v[146:149], v[186:189], v[42:45]
	v_mfma_i32_16x16x64_i8 v[30:33], v[158:161], v[190:193], v[30:33]
	v_mfma_i32_16x16x64_i8 v[30:33], v[154:157], v[236:239], v[30:33]
	v_mfma_i32_16x16x64_i8 v[26:29], v[150:153], v[190:193], v[26:29]
	v_mfma_i32_16x16x64_i8 v[26:29], v[146:149], v[236:239], v[26:29]
	v_mfma_i32_16x16x64_i8 v[14:17], v[158:161], v[240:243], v[14:17]
	v_mfma_i32_16x16x64_i8 v[14:17], v[154:157], v[244:247], v[14:17]
	v_mfma_i32_16x16x64_i8 v[10:13], v[150:153], v[240:243], v[10:13]
	v_mfma_i32_16x16x64_i8 v[10:13], v[146:149], v[244:247], v[10:13]
	v_mfma_i32_16x16x64_i8 v[70:73], v[62:65], v[174:177], v[70:73]
	v_mfma_i32_16x16x64_i8 v[70:73], v[58:61], v[178:181], v[70:73]
	v_mfma_i32_16x16x64_i8 v[66:69], v[54:57], v[174:177], v[66:69]
	v_mfma_i32_16x16x64_i8 v[66:69], v[50:53], v[178:181], v[66:69]
	v_mfma_i32_16x16x64_i8 v[38:41], v[62:65], v[182:185], v[38:41]
	v_mfma_i32_16x16x64_i8 v[38:41], v[58:61], v[186:189], v[38:41]
	v_mfma_i32_16x16x64_i8 v[34:37], v[54:57], v[182:185], v[34:37]
	v_mfma_i32_16x16x64_i8 v[34:37], v[50:53], v[186:189], v[34:37]
	v_mfma_i32_16x16x64_i8 v[22:25], v[62:65], v[190:193], v[22:25]
	v_mfma_i32_16x16x64_i8 v[22:25], v[58:61], v[236:239], v[22:25]
	v_mfma_i32_16x16x64_i8 v[18:21], v[54:57], v[190:193], v[18:21]
	v_mfma_i32_16x16x64_i8 v[18:21], v[50:53], v[236:239], v[18:21]
	s_barrier
	s_setprio 2
	v_mfma_i32_16x16x64_i8 v[6:9], v[62:65], v[240:243], v[6:9]
	v_mfma_i32_16x16x64_i8 v[6:9], v[58:61], v[244:247], v[6:9]
	v_mfma_i32_16x16x64_i8 v[2:5], v[54:57], v[240:243], v[2:5]
	v_mfma_i32_16x16x64_i8 v[2:5], v[50:53], v[244:247], v[2:5]
	s_setprio 0
	s_cmp_eq_u32 s98, 1
	s_cbranch_scc0 .Lmy_pr_P3a_1
	s_setprio 1
.Lmy_pr_P3a_1:
	s_add_i32 s72, 0, 0x18000
	v_add_u32_e32 v235, s72, v225
	s_add_i32 s74, 0, 0x1c000
	v_add_u32_e32 v236, s74, v225
	ds_read_b128 v[50:53], v235
	ds_read_b128 v[54:57], v235 offset:1024
	ds_read_b128 v[58:61], v235 offset:2048
	ds_read_b128 v[62:65], v235 offset:3072
	ds_read_b128 v[146:149], v236
	ds_read_b128 v[150:153], v236 offset:1024
	ds_read_b128 v[154:157], v236 offset:2048
	ds_read_b128 v[158:161], v236 offset:3072
	s_add_u32 s14, s40, 0x80000
	s_addc_u32 s15, s41, 0
	s_mov_b32 m0, s43
	v_lshl_add_u64 v[250:251], s[14:15], 0, v[194:195]
	ds_read_b128 v[174:177], v226 offset:32768
	ds_read_b128 v[178:181], v226 offset:33792
	ds_read_b128 v[182:185], v226 offset:34816
	ds_read_b128 v[186:189], v226 offset:35840
	ds_read_b128 v[190:193], v226 offset:36864
	ds_read_b128 v[238:241], v226 offset:37888
	ds_read_b128 v[242:245], v226 offset:38912
	ds_read_b128 v[246:249], v226 offset:39936
	global_load_lds_dwordx4 v[250:251], off
	v_lshl_add_u64 v[250:251], s[14:15], 0, v[204:205]
	s_mov_b32 m0, s44
	s_nop 0
	global_load_lds_dwordx4 v[250:251], off
	s_waitcnt vmcnt(8)
	s_waitcnt lgkmcnt(0)
	s_barrier
	s_waitcnt lgkmcnt(0)
	v_mfma_i32_16x16x64_i8 v[142:145], v[50:53], v[174:177], v[142:145]
	v_mfma_i32_16x16x64_i8 v[142:145], v[54:57], v[178:181], v[142:145]
	v_mfma_i32_16x16x64_i8 v[138:141], v[58:61], v[174:177], v[138:141]
	v_mfma_i32_16x16x64_i8 v[138:141], v[62:65], v[178:181], v[138:141]
	v_mfma_i32_16x16x64_i8 v[126:129], v[50:53], v[182:185], v[126:129]
	v_mfma_i32_16x16x64_i8 v[126:129], v[54:57], v[186:189], v[126:129]
	v_mfma_i32_16x16x64_i8 v[122:125], v[58:61], v[182:185], v[122:125]
	v_mfma_i32_16x16x64_i8 v[122:125], v[62:65], v[186:189], v[122:125]
	v_mfma_i32_16x16x64_i8 v[110:113], v[50:53], v[190:193], v[110:113]
	v_mfma_i32_16x16x64_i8 v[110:113], v[54:57], v[238:241], v[110:113]
	v_mfma_i32_16x16x64_i8 v[106:109], v[58:61], v[190:193], v[106:109]
	v_mfma_i32_16x16x64_i8 v[106:109], v[62:65], v[238:241], v[106:109]
	v_mfma_i32_16x16x64_i8 v[94:97], v[50:53], v[242:245], v[94:97]
	v_mfma_i32_16x16x64_i8 v[94:97], v[54:57], v[246:249], v[94:97]
	v_mfma_i32_16x16x64_i8 v[90:93], v[58:61], v[242:245], v[90:93]
	v_mfma_i32_16x16x64_i8 v[90:93], v[62:65], v[246:249], v[90:93]
	v_mfma_i32_16x16x64_i8 v[134:137], v[146:149], v[174:177], v[134:137]
	v_mfma_i32_16x16x64_i8 v[134:137], v[150:153], v[178:181], v[134:137]
	v_mfma_i32_16x16x64_i8 v[130:133], v[154:157], v[174:177], v[130:133]
	v_mfma_i32_16x16x64_i8 v[130:133], v[158:161], v[178:181], v[130:133]
	v_mfma_i32_16x16x64_i8 v[118:121], v[146:149], v[182:185], v[118:121]
	v_mfma_i32_16x16x64_i8 v[118:121], v[150:153], v[186:189], v[118:121]
	v_mfma_i32_16x16x64_i8 v[114:117], v[154:157], v[182:185], v[114:117]
	v_mfma_i32_16x16x64_i8 v[114:117], v[158:161], v[186:189], v[114:117]
	v_mfma_i32_16x16x64_i8 v[102:105], v[146:149], v[190:193], v[102:105]
	v_mfma_i32_16x16x64_i8 v[102:105], v[150:153], v[238:241], v[102:105]
	v_mfma_i32_16x16x64_i8 v[98:101], v[154:157], v[190:193], v[98:101]
	v_mfma_i32_16x16x64_i8 v[98:101], v[158:161], v[238:241], v[98:101]
	s_barrier
	s_setprio 2
	v_mfma_i32_16x16x64_i8 v[86:89], v[146:149], v[242:245], v[86:89]
	v_mfma_i32_16x16x64_i8 v[86:89], v[150:153], v[246:249], v[86:89]
	v_mfma_i32_16x16x64_i8 v[82:85], v[154:157], v[242:245], v[82:85]
	v_mfma_i32_16x16x64_i8 v[82:85], v[158:161], v[246:249], v[82:85]
	s_setprio 0
	s_cmp_eq_u32 s98, 1
	s_cbranch_scc0 .Lmy_pr_P3a_2
	s_setprio 1
.Lmy_pr_P3a_2:
	s_add_i32 s72, s72, s21
	s_add_i32 s73, s72, 0x2000
	v_lshl_add_u64 v[166:167], v[166:167], 0, s[6:7]
	s_mov_b32 m0, s72
	s_add_u32 s14, s38, 0x80080
	ds_read_b128 v[174:177], v226 offset:49152
	ds_read_b128 v[178:181], v226 offset:50176
	ds_read_b128 v[182:185], v226 offset:51200
	ds_read_b128 v[186:189], v226 offset:52224
	ds_read_b128 v[190:193], v226 offset:53248
	ds_read_b128 v[238:241], v226 offset:54272
	ds_read_b128 v[242:245], v226 offset:55296
	ds_read_b128 v[246:249], v226 offset:56320
	global_load_lds_dwordx4 v[166:167], off
	v_lshl_add_u64 v[166:167], v[168:169], 0, s[6:7]
	s_mov_b32 m0, s73
	s_addc_u32 s15, s39, 0
	s_add_i32 s74, s74, s21
	global_load_lds_dwordx4 v[166:167], off
	v_lshl_add_u64 v[166:167], s[14:15], 0, v[202:203]
	s_mov_b32 m0, s74
	s_add_i32 s75, s74, 0x2000
	global_load_lds_dwordx4 v[166:167], off
	v_lshl_add_u64 v[166:167], s[14:15], 0, v[206:207]
	s_mov_b32 m0, s75
	s_nop 0
	global_load_lds_dwordx4 v[166:167], off
	v_lshl_add_u64 v[166:167], v[170:171], 0, s[6:7]
	s_mov_b32 m0, s51
	s_nop 0
	global_load_lds_dwordx4 v[166:167], off
	v_lshl_add_u64 v[166:167], v[172:173], 0, s[6:7]
	s_mov_b32 m0, s53
	s_nop 0
	global_load_lds_dwordx4 v[166:167], off
	s_waitcnt vmcnt(8)
	s_waitcnt lgkmcnt(0)
	s_barrier
	s_waitcnt lgkmcnt(0)
	v_mfma_i32_16x16x64_i8 v[78:81], v[50:53], v[174:177], v[78:81]
	v_mfma_i32_16x16x64_i8 v[78:81], v[54:57], v[178:181], v[78:81]
	v_mfma_i32_16x16x64_i8 v[74:77], v[58:61], v[174:177], v[74:77]
	v_mfma_i32_16x16x64_i8 v[74:77], v[62:65], v[178:181], v[74:77]
	v_mfma_i32_16x16x64_i8 v[46:49], v[50:53], v[182:185], v[46:49]
	v_mfma_i32_16x16x64_i8 v[46:49], v[54:57], v[186:189], v[46:49]
	v_mfma_i32_16x16x64_i8 v[42:45], v[58:61], v[182:185], v[42:45]
	v_mfma_i32_16x16x64_i8 v[42:45], v[62:65], v[186:189], v[42:45]
	v_mfma_i32_16x16x64_i8 v[30:33], v[50:53], v[190:193], v[30:33]
	v_mfma_i32_16x16x64_i8 v[30:33], v[54:57], v[238:241], v[30:33]
	v_mfma_i32_16x16x64_i8 v[26:29], v[58:61], v[190:193], v[26:29]
	v_mfma_i32_16x16x64_i8 v[26:29], v[62:65], v[238:241], v[26:29]
	v_mfma_i32_16x16x64_i8 v[14:17], v[50:53], v[242:245], v[14:17]
	v_mfma_i32_16x16x64_i8 v[14:17], v[54:57], v[246:249], v[14:17]
	v_mfma_i32_16x16x64_i8 v[10:13], v[58:61], v[242:245], v[10:13]
	v_mfma_i32_16x16x64_i8 v[10:13], v[62:65], v[246:249], v[10:13]
	v_mfma_i32_16x16x64_i8 v[70:73], v[146:149], v[174:177], v[70:73]
	v_mfma_i32_16x16x64_i8 v[70:73], v[150:153], v[178:181], v[70:73]
	v_mfma_i32_16x16x64_i8 v[66:69], v[154:157], v[174:177], v[66:69]
	v_mfma_i32_16x16x64_i8 v[66:69], v[158:161], v[178:181], v[66:69]
	v_mfma_i32_16x16x64_i8 v[38:41], v[146:149], v[182:185], v[38:41]
	v_mfma_i32_16x16x64_i8 v[38:41], v[150:153], v[186:189], v[38:41]
	v_mfma_i32_16x16x64_i8 v[34:37], v[154:157], v[182:185], v[34:37]
	v_mfma_i32_16x16x64_i8 v[34:37], v[158:161], v[186:189], v[34:37]
	v_mfma_i32_16x16x64_i8 v[22:25], v[146:149], v[190:193], v[22:25]
	v_mfma_i32_16x16x64_i8 v[22:25], v[150:153], v[238:241], v[22:25]
	v_mfma_i32_16x16x64_i8 v[18:21], v[154:157], v[190:193], v[18:21]
	v_mfma_i32_16x16x64_i8 v[18:21], v[158:161], v[238:241], v[18:21]
	s_barrier
	s_setprio 2
	v_mfma_i32_16x16x64_i8 v[6:9], v[146:149], v[242:245], v[6:9]
	v_mfma_i32_16x16x64_i8 v[6:9], v[150:153], v[246:249], v[6:9]
	v_mfma_i32_16x16x64_i8 v[2:5], v[154:157], v[242:245], v[2:5]
	v_mfma_i32_16x16x64_i8 v[2:5], v[158:161], v[246:249], v[2:5]
	s_setprio 0
	s_cmp_eq_u32 s98, 1
	s_cbranch_scc0 .Lmy_pr_P3a_3
	s_setprio 1
.Lmy_pr_P3a_3:
	s_add_i32 s3, s3, 2
	s_add_u32 s34, s34, 0x100
	s_addc_u32 s35, s35, 0
	s_cmp_gt_u32 s3, 29
	s_cbranch_scc0 .LBB0_734
	s_nop 15
	s_nop 15
	s_and_b64 vcc, exec, s[8:9]
	s_cbranch_vccz .LBB0_737
	s_barrier

.LBB0_740:
	ds_read_b128 v[158:161], v227
	ds_read_b128 v[154:157], v227 offset:1024
	ds_read_b128 v[150:153], v227 offset:2048
	ds_read_b128 v[146:149], v227 offset:3072
	ds_read_b128 v[62:65], v233
	ds_read_b128 v[58:61], v233 offset:1024
	ds_read_b128 v[54:57], v233 offset:2048
	ds_read_b128 v[50:53], v233 offset:3072
	s_add_u32 s36, s38, 0xfff80080
	s_addc_u32 s37, s39, -1
	s_cmp_eq_u32 s33, 28
	s_cselect_b32 s41, s1, s37
	s_cselect_b32 s40, s0, s36
	s_cselect_b32 s37, s15, s29
	s_cselect_b32 s36, s14, s25
	s_mov_b32 m0, s66
	v_lshl_add_u64 v[238:239], s[38:39], 0, v[208:209]
	ds_read_b128 v[162:165], v226
	ds_read_b128 v[166:169], v226 offset:1024
	ds_read_b128 v[170:173], v226 offset:2048
	ds_read_b128 v[174:177], v226 offset:3072
	ds_read_b128 v[178:181], v226 offset:4096
	ds_read_b128 v[182:185], v226 offset:5120
	ds_read_b128 v[186:189], v226 offset:6144
	ds_read_b128 v[190:193], v226 offset:7168
	global_load_lds_dwordx4 v[238:239], off
	v_lshl_add_u64 v[238:239], s[38:39], 0, v[212:213]
	s_mov_b32 m0, s67
	s_nop 0
	global_load_lds_dwordx4 v[238:239], off
	s_waitcnt vmcnt(8)
	s_waitcnt lgkmcnt(0)
	s_barrier
	s_waitcnt lgkmcnt(0)
	v_mfma_i32_16x16x64_i8 v[142:145], v[158:161], v[162:165], v[142:145]
	v_mfma_i32_16x16x64_i8 v[142:145], v[154:157], v[166:169], v[142:145]
	v_mfma_i32_16x16x64_i8 v[138:141], v[150:153], v[162:165], v[138:141]
	v_mfma_i32_16x16x64_i8 v[138:141], v[146:149], v[166:169], v[138:141]
	v_mfma_i32_16x16x64_i8 v[126:129], v[158:161], v[170:173], v[126:129]
	v_mfma_i32_16x16x64_i8 v[126:129], v[154:157], v[174:177], v[126:129]
	v_mfma_i32_16x16x64_i8 v[122:125], v[150:153], v[170:173], v[122:125]
	v_mfma_i32_16x16x64_i8 v[122:125], v[146:149], v[174:177], v[122:125]
	v_mfma_i32_16x16x64_i8 v[110:113], v[158:161], v[178:181], v[110:113]
	v_mfma_i32_16x16x64_i8 v[110:113], v[154:157], v[182:185], v[110:113]
	v_mfma_i32_16x16x64_i8 v[106:109], v[150:153], v[178:181], v[106:109]
	v_mfma_i32_16x16x64_i8 v[106:109], v[146:149], v[182:185], v[106:109]
	v_mfma_i32_16x16x64_i8 v[94:97], v[158:161], v[186:189], v[94:97]
	v_mfma_i32_16x16x64_i8 v[94:97], v[154:157], v[190:193], v[94:97]
	v_mfma_i32_16x16x64_i8 v[90:93], v[150:153], v[186:189], v[90:93]
	v_mfma_i32_16x16x64_i8 v[90:93], v[146:149], v[190:193], v[90:93]
	v_mfma_i32_16x16x64_i8 v[134:137], v[62:65], v[162:165], v[134:137]
	v_mfma_i32_16x16x64_i8 v[134:137], v[58:61], v[166:169], v[134:137]
	v_mfma_i32_16x16x64_i8 v[130:133], v[54:57], v[162:165], v[130:133]
	v_mfma_i32_16x16x64_i8 v[130:133], v[50:53], v[166:169], v[130:133]
	v_mfma_i32_16x16x64_i8 v[118:121], v[62:65], v[170:173], v[118:121]
	v_mfma_i32_16x16x64_i8 v[118:121], v[58:61], v[174:177], v[118:121]
	v_mfma_i32_16x16x64_i8 v[114:117], v[54:57], v[170:173], v[114:117]
	v_mfma_i32_16x16x64_i8 v[114:117], v[50:53], v[174:177], v[114:117]
	v_mfma_i32_16x16x64_i8 v[102:105], v[62:65], v[178:181], v[102:105]
	v_mfma_i32_16x16x64_i8 v[102:105], v[58:61], v[182:185], v[102:105]
	v_mfma_i32_16x16x64_i8 v[98:101], v[54:57], v[178:181], v[98:101]
	v_mfma_i32_16x16x64_i8 v[98:101], v[50:53], v[182:185], v[98:101]
	s_barrier
	s_setprio 2
	v_mfma_i32_16x16x64_i8 v[86:89], v[62:65], v[186:189], v[86:89]
	v_mfma_i32_16x16x64_i8 v[86:89], v[58:61], v[190:193], v[86:89]
	v_mfma_i32_16x16x64_i8 v[82:85], v[54:57], v[186:189], v[82:85]
	v_mfma_i32_16x16x64_i8 v[82:85], v[50:53], v[190:193], v[82:85]
	s_setprio 0
	s_cmp_eq_u32 s98, 1
	s_cbranch_scc0 .Lmy_pr_P3b_0
	s_setprio 1
.Lmy_pr_P3b_0:
	s_mov_b32 m0, s68
	v_lshl_add_u64 v[162:163], s[36:37], 0, v[202:203]
	s_add_u32 s80, s36, 0x80000
	ds_read_b128 v[170:173], v226 offset:16384
	ds_read_b128 v[174:177], v226 offset:17408
	ds_read_b128 v[178:181], v226 offset:18432
	ds_read_b128 v[182:185], v226 offset:19456
	ds_read_b128 v[186:189], v226 offset:20480
	ds_read_b128 v[190:193], v226 offset:21504
	ds_read_b128 v[238:241], v226 offset:22528
	ds_read_b128 v[242:245], v226 offset:23552
	global_load_lds_dwordx4 v[162:163], off
	v_lshl_add_u64 v[164:165], s[36:37], 0, v[206:207]
	s_mov_b32 m0, s69
	s_addc_u32 s81, s37, 0
	global_load_lds_dwordx4 v[164:165], off
	v_lshl_add_u64 v[166:167], s[80:81], 0, v[202:203]
	s_mov_b32 m0, s70
	v_lshl_add_u64 v[168:169], s[40:41], 0, v[204:205]
	global_load_lds_dwordx4 v[166:167], off
	v_lshl_add_u64 v[166:167], s[80:81], 0, v[206:207]
	s_mov_b32 m0, s71
	s_nop 0
	global_load_lds_dwordx4 v[166:167], off
	v_lshl_add_u64 v[166:167], s[40:41], 0, v[194:195]
	s_mov_b32 m0, s23
	s_nop 0
	global_load_lds_dwordx4 v[166:167], off
	s_mov_b32 m0, s42
	s_nop 0
	global_load_lds_dwordx4 v[168:169], off
	s_waitcnt vmcnt(8)
	s_waitcnt lgkmcnt(0)
	s_barrier
	s_waitcnt lgkmcnt(0)
	v_mfma_i32_16x16x64_i8 v[78:81], v[158:161], v[170:173], v[78:81]
	v_mfma_i32_16x16x64_i8 v[78:81], v[154:157], v[174:177], v[78:81]
	v_mfma_i32_16x16x64_i8 v[74:77], v[150:153], v[170:173], v[74:77]
	v_mfma_i32_16x16x64_i8 v[74:77], v[146:149], v[174:177], v[74:77]
	v_mfma_i32_16x16x64_i8 v[46:49], v[158:161], v[178:181], v[46:49]
	v_mfma_i32_16x16x64_i8 v[46:49], v[154:157], v[182:185], v[46:49]
	v_mfma_i32_16x16x64_i8 v[42:45], v[150:153], v[178:181], v[42:45]
	v_mfma_i32_16x16x64_i8 v[42:45], v[146:149], v[182:185], v[42:45]
	v_mfma_i32_16x16x64_i8 v[30:33], v[158:161], v[186:189], v[30:33]
	v_mfma_i32_16x16x64_i8 v[30:33], v[154:157], v[190:193], v[30:33]
	v_mfma_i32_16x16x64_i8 v[26:29], v[150:153], v[186:189], v[26:29]
	v_mfma_i32_16x16x64_i8 v[26:29], v[146:149], v[190:193], v[26:29]
	v_mfma_i32_16x16x64_i8 v[14:17], v[158:161], v[238:241], v[14:17]
	v_mfma_i32_16x16x64_i8 v[14:17], v[154:157], v[242:245], v[14:17]
	v_mfma_i32_16x16x64_i8 v[10:13], v[150:153], v[238:241], v[10:13]
	v_mfma_i32_16x16x64_i8 v[10:13], v[146:149], v[242:245], v[10:13]
	v_mfma_i32_16x16x64_i8 v[70:73], v[62:65], v[170:173], v[70:73]
	v_mfma_i32_16x16x64_i8 v[70:73], v[58:61], v[174:177], v[70:73]
	v_mfma_i32_16x16x64_i8 v[66:69], v[54:57], v[170:173], v[66:69]
	v_mfma_i32_16x16x64_i8 v[66:69], v[50:53], v[174:177], v[66:69]
	v_mfma_i32_16x16x64_i8 v[38:41], v[62:65], v[178:181], v[38:41]
	v_mfma_i32_16x16x64_i8 v[38:41], v[58:61], v[182:185], v[38:41]
	v_mfma_i32_16x16x64_i8 v[34:37], v[54:57], v[178:181], v[34:37]
	v_mfma_i32_16x16x64_i8 v[34:37], v[50:53], v[182:185], v[34:37]
	v_mfma_i32_16x16x64_i8 v[22:25], v[62:65], v[186:189], v[22:25]
	v_mfma_i32_16x16x64_i8 v[22:25], v[58:61], v[190:193], v[22:25]
	v_mfma_i32_16x16x64_i8 v[18:21], v[54:57], v[186:189], v[18:21]
	v_mfma_i32_16x16x64_i8 v[18:21], v[50:53], v[190:193], v[18:21]
	s_barrier
	s_setprio 2
	v_mfma_i32_16x16x64_i8 v[6:9], v[62:65], v[238:241], v[6:9]
	v_mfma_i32_16x16x64_i8 v[6:9], v[58:61], v[242:245], v[6:9]
	v_mfma_i32_16x16x64_i8 v[2:5], v[54:57], v[238:241], v[2:5]
	v_mfma_i32_16x16x64_i8 v[2:5], v[50:53], v[242:245], v[2:5]
	s_setprio 0
	s_cmp_eq_u32 s98, 1
	s_cbranch_scc0 .Lmy_pr_P3b_1
	s_setprio 1
.Lmy_pr_P3b_1:
	ds_read_b128 v[50:53], v235
	ds_read_b128 v[54:57], v235 offset:1024
	ds_read_b128 v[58:61], v235 offset:2048
	ds_read_b128 v[62:65], v235 offset:3072
	ds_read_b128 v[146:149], v236
	ds_read_b128 v[150:153], v236 offset:1024
	ds_read_b128 v[154:157], v236 offset:2048
	ds_read_b128 v[158:161], v236 offset:3072
	s_add_u32 s40, s40, 0x80000
	s_addc_u32 s41, s41, 0
	s_mov_b32 m0, s43
	v_lshl_add_u64 v[246:247], s[40:41], 0, v[194:195]
	ds_read_b128 v[170:173], v226 offset:32768
	ds_read_b128 v[174:177], v226 offset:33792
	ds_read_b128 v[178:181], v226 offset:34816
	ds_read_b128 v[182:185], v226 offset:35840
	ds_read_b128 v[186:189], v226 offset:36864
	ds_read_b128 v[190:193], v226 offset:37888
	ds_read_b128 v[238:241], v226 offset:38912
	ds_read_b128 v[242:245], v226 offset:39936
	global_load_lds_dwordx4 v[246:247], off
	v_lshl_add_u64 v[246:247], s[40:41], 0, v[204:205]
	s_mov_b32 m0, s44
	s_nop 0
	global_load_lds_dwordx4 v[246:247], off
	s_waitcnt vmcnt(8)
	s_waitcnt lgkmcnt(0)
	s_barrier
	s_waitcnt lgkmcnt(0)
	v_mfma_i32_16x16x64_i8 v[142:145], v[50:53], v[170:173], v[142:145]
	v_mfma_i32_16x16x64_i8 v[142:145], v[54:57], v[174:177], v[142:145]
	v_mfma_i32_16x16x64_i8 v[138:141], v[58:61], v[170:173], v[138:141]
	v_mfma_i32_16x16x64_i8 v[138:141], v[62:65], v[174:177], v[138:141]
	v_mfma_i32_16x16x64_i8 v[126:129], v[50:53], v[178:181], v[126:129]
	v_mfma_i32_16x16x64_i8 v[126:129], v[54:57], v[182:185], v[126:129]
	v_mfma_i32_16x16x64_i8 v[122:125], v[58:61], v[178:181], v[122:125]
	v_mfma_i32_16x16x64_i8 v[122:125], v[62:65], v[182:185], v[122:125]
	v_mfma_i32_16x16x64_i8 v[110:113], v[50:53], v[186:189], v[110:113]
	v_mfma_i32_16x16x64_i8 v[110:113], v[54:57], v[190:193], v[110:113]
	v_mfma_i32_16x16x64_i8 v[106:109], v[58:61], v[186:189], v[106:109]
	v_mfma_i32_16x16x64_i8 v[106:109], v[62:65], v[190:193], v[106:109]
	v_mfma_i32_16x16x64_i8 v[94:97], v[50:53], v[238:241], v[94:97]
	v_mfma_i32_16x16x64_i8 v[94:97], v[54:57], v[242:245], v[94:97]
	v_mfma_i32_16x16x64_i8 v[90:93], v[58:61], v[238:241], v[90:93]
	v_mfma_i32_16x16x64_i8 v[90:93], v[62:65], v[242:245], v[90:93]
	v_mfma_i32_16x16x64_i8 v[134:137], v[146:149], v[170:173], v[134:137]
	v_mfma_i32_16x16x64_i8 v[134:137], v[150:153], v[174:177], v[134:137]
	v_mfma_i32_16x16x64_i8 v[130:133], v[154:157], v[170:173], v[130:133]
	v_mfma_i32_16x16x64_i8 v[130:133], v[158:161], v[174:177], v[130:133]
	v_mfma_i32_16x16x64_i8 v[118:121], v[146:149], v[178:181], v[118:121]
	v_mfma_i32_16x16x64_i8 v[118:121], v[150:153], v[182:185], v[118:121]
	v_mfma_i32_16x16x64_i8 v[114:117], v[154:157], v[178:181], v[114:117]
	v_mfma_i32_16x16x64_i8 v[114:117], v[158:161], v[182:185], v[114:117]
	v_mfma_i32_16x16x64_i8 v[102:105], v[146:149], v[186:189], v[102:105]
	v_mfma_i32_16x16x64_i8 v[102:105], v[150:153], v[190:193], v[102:105]
	v_mfma_i32_16x16x64_i8 v[98:101], v[154:157], v[186:189], v[98:101]
	v_mfma_i32_16x16x64_i8 v[98:101], v[158:161], v[190:193], v[98:101]
	s_barrier
	s_setprio 2
	v_mfma_i32_16x16x64_i8 v[86:89], v[146:149], v[238:241], v[86:89]
	v_mfma_i32_16x16x64_i8 v[86:89], v[150:153], v[242:245], v[86:89]
	v_mfma_i32_16x16x64_i8 v[82:85], v[154:157], v[238:241], v[82:85]
	v_mfma_i32_16x16x64_i8 v[82:85], v[158:161], v[242:245], v[82:85]
	s_setprio 0
	s_cmp_eq_u32 s98, 1
	s_cbranch_scc0 .Lmy_pr_P3b_2
	s_setprio 1
.Lmy_pr_P3b_2:
	s_mov_b32 m0, s72
	v_lshl_add_u64 v[162:163], v[162:163], 0, s[6:7]
	s_add_u32 s36, s36, 0x80080
	ds_read_b128 v[170:173], v226 offset:49152
	ds_read_b128 v[174:177], v226 offset:50176
	ds_read_b128 v[178:181], v226 offset:51200
	ds_read_b128 v[182:185], v226 offset:52224
	ds_read_b128 v[186:189], v226 offset:53248
	ds_read_b128 v[190:193], v226 offset:54272
	ds_read_b128 v[238:241], v226 offset:55296
	ds_read_b128 v[242:245], v226 offset:56320
	global_load_lds_dwordx4 v[162:163], off
	v_lshl_add_u64 v[162:163], v[164:165], 0, s[6:7]
	s_mov_b32 m0, s73
	s_addc_u32 s37, s37, 0
	global_load_lds_dwordx4 v[162:163], off
	v_lshl_add_u64 v[162:163], s[36:37], 0, v[202:203]
	s_mov_b32 m0, s74
	s_nop 0
	global_load_lds_dwordx4 v[162:163], off
	v_lshl_add_u64 v[162:163], s[36:37], 0, v[206:207]
	s_mov_b32 m0, s75
	s_nop 0
	global_load_lds_dwordx4 v[162:163], off
	v_lshl_add_u64 v[162:163], v[166:167], 0, s[6:7]
	s_mov_b32 m0, s51
	s_nop 0
	global_load_lds_dwordx4 v[162:163], off
	v_lshl_add_u64 v[162:163], v[168:169], 0, s[6:7]
	s_mov_b32 m0, s53
	s_nop 0
	global_load_lds_dwordx4 v[162:163], off
	s_waitcnt vmcnt(8)
	s_waitcnt lgkmcnt(0)
	s_barrier
	s_waitcnt lgkmcnt(0)
	v_mfma_i32_16x16x64_i8 v[78:81], v[50:53], v[170:173], v[78:81]
	v_mfma_i32_16x16x64_i8 v[78:81], v[54:57], v[174:177], v[78:81]
	v_mfma_i32_16x16x64_i8 v[74:77], v[58:61], v[170:173], v[74:77]
	v_mfma_i32_16x16x64_i8 v[74:77], v[62:65], v[174:177], v[74:77]
	v_mfma_i32_16x16x64_i8 v[46:49], v[50:53], v[178:181], v[46:49]
	v_mfma_i32_16x16x64_i8 v[46:49], v[54:57], v[182:185], v[46:49]
	v_mfma_i32_16x16x64_i8 v[42:45], v[58:61], v[178:181], v[42:45]
	v_mfma_i32_16x16x64_i8 v[42:45], v[62:65], v[182:185], v[42:45]
	v_mfma_i32_16x16x64_i8 v[30:33], v[50:53], v[186:189], v[30:33]
	v_mfma_i32_16x16x64_i8 v[30:33], v[54:57], v[190:193], v[30:33]
	v_mfma_i32_16x16x64_i8 v[26:29], v[58:61], v[186:189], v[26:29]
	v_mfma_i32_16x16x64_i8 v[26:29], v[62:65], v[190:193], v[26:29]
	v_mfma_i32_16x16x64_i8 v[14:17], v[50:53], v[238:241], v[14:17]
	v_mfma_i32_16x16x64_i8 v[14:17], v[54:57], v[242:245], v[14:17]
	v_mfma_i32_16x16x64_i8 v[10:13], v[58:61], v[238:241], v[10:13]
	v_mfma_i32_16x16x64_i8 v[10:13], v[62:65], v[242:245], v[10:13]
	v_mfma_i32_16x16x64_i8 v[70:73], v[146:149], v[170:173], v[70:73]
	v_mfma_i32_16x16x64_i8 v[70:73], v[150:153], v[174:177], v[70:73]
	v_mfma_i32_16x16x64_i8 v[66:69], v[154:157], v[170:173], v[66:69]
	v_mfma_i32_16x16x64_i8 v[66:69], v[158:161], v[174:177], v[66:69]
	v_mfma_i32_16x16x64_i8 v[38:41], v[146:149], v[178:181], v[38:41]
	v_mfma_i32_16x16x64_i8 v[38:41], v[150:153], v[182:185], v[38:41]
	v_mfma_i32_16x16x64_i8 v[34:37], v[154:157], v[178:181], v[34:37]
	v_mfma_i32_16x16x64_i8 v[34:37], v[158:161], v[182:185], v[34:37]
	v_mfma_i32_16x16x64_i8 v[22:25], v[146:149], v[186:189], v[22:25]
	v_mfma_i32_16x16x64_i8 v[22:25], v[150:153], v[190:193], v[22:25]
	v_mfma_i32_16x16x64_i8 v[18:21], v[154:157], v[186:189], v[18:21]
	v_mfma_i32_16x16x64_i8 v[18:21], v[158:161], v[190:193], v[18:21]
	s_barrier
	s_setprio 2
	v_mfma_i32_16x16x64_i8 v[6:9], v[146:149], v[238:241], v[6:9]
	v_mfma_i32_16x16x64_i8 v[6:9], v[150:153], v[242:245], v[6:9]
	v_mfma_i32_16x16x64_i8 v[2:5], v[154:157], v[238:241], v[2:5]
	v_mfma_i32_16x16x64_i8 v[2:5], v[158:161], v[242:245], v[2:5]
	s_setprio 0
	s_cmp_eq_u32 s98, 1
	s_cbranch_scc0 .Lmy_pr_P3b_3
	s_setprio 1
.Lmy_pr_P3b_3:
	s_add_i32 s33, s33, 2
	s_add_u32 s38, s38, 0x100
	s_addc_u32 s39, s39, 0
	s_add_u32 s25, s25, 0x100
	s_addc_u32 s29, s29, 0
	s_cmp_gt_u32 s33, 29
	s_cbranch_scc0 .LBB0_740
	s_nop 15
	s_nop 15
	s_and_b64 vcc, exec, s[8:9]
	s_cbranch_vccz .LBB0_743
	s_barrier

.LBB0_746:
	ds_read_b128 v[158:161], v227
	ds_read_b128 v[154:157], v227 offset:1024
	ds_read_b128 v[150:153], v227 offset:2048
	ds_read_b128 v[146:149], v227 offset:3072
	ds_read_b128 v[142:145], v233
	ds_read_b128 v[138:141], v233 offset:1024
	ds_read_b128 v[134:137], v233 offset:2048
	ds_read_b128 v[130:133], v233 offset:3072
	s_add_u32 s38, s29, s36
	s_addc_u32 s39, s33, s37
	s_add_u32 s38, s38, 0x3d000100
	s_addc_u32 s39, s39, 0
	s_add_u32 s81, s25, s36
	s_addc_u32 s82, s79, s37
	s_cmpk_eq_i32 s36, 0x700
	s_cselect_b32 s41, s1, s39
	s_cselect_b32 s40, s0, s38
	s_cselect_b32 s39, s15, s82
	s_cselect_b32 s38, s14, s81
	s_mov_b32 m0, s66
	v_lshl_add_u64 v[242:243], v[162:163], 0, s[36:37]
	ds_read_b128 v[166:169], v226
	ds_read_b128 v[170:173], v226 offset:1024
	ds_read_b128 v[174:177], v226 offset:2048
	ds_read_b128 v[178:181], v226 offset:3072
	ds_read_b128 v[182:185], v226 offset:4096
	ds_read_b128 v[186:189], v226 offset:5120
	ds_read_b128 v[190:193], v226 offset:6144
	ds_read_b128 v[238:241], v226 offset:7168
	global_load_lds_dwordx4 v[242:243], off
	v_lshl_add_u64 v[242:243], v[164:165], 0, s[36:37]
	s_mov_b32 m0, s67
	s_nop 0
	global_load_lds_dwordx4 v[242:243], off
	s_waitcnt vmcnt(8)
	s_waitcnt lgkmcnt(0)
	s_barrier
	s_waitcnt lgkmcnt(0)
	v_mfma_i32_16x16x64_i8 v[30:33], v[158:161], v[166:169], v[30:33]
	v_mfma_i32_16x16x64_i8 v[30:33], v[154:157], v[170:173], v[30:33]
	v_mfma_i32_16x16x64_i8 v[26:29], v[150:153], v[166:169], v[26:29]
	v_mfma_i32_16x16x64_i8 v[26:29], v[146:149], v[170:173], v[26:29]
	v_mfma_i32_16x16x64_i8 v[46:49], v[158:161], v[174:177], v[46:49]
	v_mfma_i32_16x16x64_i8 v[46:49], v[154:157], v[178:181], v[46:49]
	v_mfma_i32_16x16x64_i8 v[42:45], v[150:153], v[174:177], v[42:45]
	v_mfma_i32_16x16x64_i8 v[42:45], v[146:149], v[178:181], v[42:45]
	v_mfma_i32_16x16x64_i8 v[74:77], v[158:161], v[182:185], v[74:77]
	v_mfma_i32_16x16x64_i8 v[74:77], v[154:157], v[186:189], v[74:77]
	v_mfma_i32_16x16x64_i8 v[70:73], v[150:153], v[182:185], v[70:73]
	v_mfma_i32_16x16x64_i8 v[70:73], v[146:149], v[186:189], v[70:73]
	v_mfma_i32_16x16x64_i8 v[94:97], v[158:161], v[190:193], v[94:97]
	v_mfma_i32_16x16x64_i8 v[94:97], v[154:157], v[238:241], v[94:97]
	v_mfma_i32_16x16x64_i8 v[90:93], v[150:153], v[190:193], v[90:93]
	v_mfma_i32_16x16x64_i8 v[90:93], v[146:149], v[238:241], v[90:93]
	v_mfma_i32_16x16x64_i8 v[38:41], v[142:145], v[166:169], v[38:41]
	v_mfma_i32_16x16x64_i8 v[38:41], v[138:141], v[170:173], v[38:41]
	v_mfma_i32_16x16x64_i8 v[34:37], v[134:137], v[166:169], v[34:37]
	v_mfma_i32_16x16x64_i8 v[34:37], v[130:133], v[170:173], v[34:37]
	v_mfma_i32_16x16x64_i8 v[58:61], v[142:145], v[174:177], v[58:61]
	v_mfma_i32_16x16x64_i8 v[58:61], v[138:141], v[178:181], v[58:61]
	v_mfma_i32_16x16x64_i8 v[54:57], v[134:137], v[174:177], v[54:57]
	v_mfma_i32_16x16x64_i8 v[54:57], v[130:133], v[178:181], v[54:57]
	v_mfma_i32_16x16x64_i8 v[86:89], v[142:145], v[182:185], v[86:89]
	v_mfma_i32_16x16x64_i8 v[86:89], v[138:141], v[186:189], v[86:89]
	v_mfma_i32_16x16x64_i8 v[82:85], v[134:137], v[182:185], v[82:85]
	v_mfma_i32_16x16x64_i8 v[82:85], v[130:133], v[186:189], v[82:85]
	s_barrier
	s_setprio 2
	v_mfma_i32_16x16x64_i8 v[102:105], v[142:145], v[190:193], v[102:105]
	v_mfma_i32_16x16x64_i8 v[102:105], v[138:141], v[238:241], v[102:105]
	v_mfma_i32_16x16x64_i8 v[98:101], v[134:137], v[190:193], v[98:101]
	v_mfma_i32_16x16x64_i8 v[98:101], v[130:133], v[238:241], v[98:101]
	s_setprio 0
	s_cmp_eq_u32 s98, 1
	s_cbranch_scc0 .Lmy_pr_P3c_0
	s_setprio 1
.Lmy_pr_P3c_0:
	s_mov_b32 m0, s68
	v_lshl_add_u64 v[166:167], s[38:39], 0, v[202:203]
	s_add_u32 s82, s38, 0x80000
	ds_read_b128 v[174:177], v226 offset:16384
	ds_read_b128 v[178:181], v226 offset:17408
	ds_read_b128 v[182:185], v226 offset:18432
	ds_read_b128 v[186:189], v226 offset:19456
	ds_read_b128 v[190:193], v226 offset:20480
	ds_read_b128 v[238:241], v226 offset:21504
	ds_read_b128 v[242:245], v226 offset:22528
	ds_read_b128 v[246:249], v226 offset:23552
	global_load_lds_dwordx4 v[166:167], off
	v_lshl_add_u64 v[168:169], s[38:39], 0, v[206:207]
	s_mov_b32 m0, s69
	s_addc_u32 s83, s39, 0
	global_load_lds_dwordx4 v[168:169], off
	v_lshl_add_u64 v[170:171], s[82:83], 0, v[202:203]
	s_mov_b32 m0, s70
	v_lshl_add_u64 v[172:173], s[40:41], 0, v[204:205]
	global_load_lds_dwordx4 v[170:171], off
	v_lshl_add_u64 v[170:171], s[82:83], 0, v[206:207]
	s_mov_b32 m0, s71
	s_nop 0
	global_load_lds_dwordx4 v[170:171], off
	v_lshl_add_u64 v[170:171], s[40:41], 0, v[194:195]
	s_mov_b32 m0, s23
	s_nop 0
	global_load_lds_dwordx4 v[170:171], off
	s_mov_b32 m0, s42
	s_nop 0
	global_load_lds_dwordx4 v[172:173], off
	s_waitcnt vmcnt(8)
	s_waitcnt lgkmcnt(0)
	s_barrier
	s_waitcnt lgkmcnt(0)
	v_mfma_i32_16x16x64_i8 v[110:113], v[158:161], v[174:177], v[110:113]
	v_mfma_i32_16x16x64_i8 v[110:113], v[154:157], v[178:181], v[110:113]
	v_mfma_i32_16x16x64_i8 v[106:109], v[150:153], v[174:177], v[106:109]
	v_mfma_i32_16x16x64_i8 v[106:109], v[146:149], v[178:181], v[106:109]
	v_mfma_i32_16x16x64_i8 v[126:129], v[158:161], v[182:185], v[126:129]
	v_mfma_i32_16x16x64_i8 v[126:129], v[154:157], v[186:189], v[126:129]
	v_mfma_i32_16x16x64_i8 v[118:121], v[150:153], v[182:185], v[118:121]
	v_mfma_i32_16x16x64_i8 v[118:121], v[146:149], v[186:189], v[118:121]
	v_mfma_i32_16x16x64_i8 v[62:65], v[158:161], v[190:193], v[62:65]
	v_mfma_i32_16x16x64_i8 v[62:65], v[154:157], v[238:241], v[62:65]
	v_mfma_i32_16x16x64_i8 v[50:53], v[150:153], v[190:193], v[50:53]
	v_mfma_i32_16x16x64_i8 v[50:53], v[146:149], v[238:241], v[50:53]
	v_mfma_i32_16x16x64_i8 v[14:17], v[158:161], v[242:245], v[14:17]
	v_mfma_i32_16x16x64_i8 v[14:17], v[154:157], v[246:249], v[14:17]
	v_mfma_i32_16x16x64_i8 v[10:13], v[150:153], v[242:245], v[10:13]
	v_mfma_i32_16x16x64_i8 v[10:13], v[146:149], v[246:249], v[10:13]
	v_mfma_i32_16x16x64_i8 v[122:125], v[142:145], v[174:177], v[122:125]
	v_mfma_i32_16x16x64_i8 v[122:125], v[138:141], v[178:181], v[122:125]
	v_mfma_i32_16x16x64_i8 v[114:117], v[134:137], v[174:177], v[114:117]
	v_mfma_i32_16x16x64_i8 v[114:117], v[130:133], v[178:181], v[114:117]
	v_mfma_i32_16x16x64_i8 v[78:81], v[142:145], v[182:185], v[78:81]
	v_mfma_i32_16x16x64_i8 v[78:81], v[138:141], v[186:189], v[78:81]
	v_mfma_i32_16x16x64_i8 v[66:69], v[134:137], v[182:185], v[66:69]
	v_mfma_i32_16x16x64_i8 v[66:69], v[130:133], v[186:189], v[66:69]
	v_mfma_i32_16x16x64_i8 v[22:25], v[142:145], v[190:193], v[22:25]
	v_mfma_i32_16x16x64_i8 v[22:25], v[138:141], v[238:241], v[22:25]
	v_mfma_i32_16x16x64_i8 v[18:21], v[134:137], v[190:193], v[18:21]
	v_mfma_i32_16x16x64_i8 v[18:21], v[130:133], v[238:241], v[18:21]
	s_barrier
	s_setprio 2
	v_mfma_i32_16x16x64_i8 v[6:9], v[142:145], v[242:245], v[6:9]
	v_mfma_i32_16x16x64_i8 v[6:9], v[138:141], v[246:249], v[6:9]
	v_mfma_i32_16x16x64_i8 v[2:5], v[134:137], v[242:245], v[2:5]
	v_mfma_i32_16x16x64_i8 v[2:5], v[130:133], v[246:249], v[2:5]
	s_setprio 0
	s_cmp_eq_u32 s98, 1
	s_cbranch_scc0 .Lmy_pr_P3c_1
	s_setprio 1
.Lmy_pr_P3c_1:
	ds_read_b128 v[130:133], v235
	ds_read_b128 v[134:137], v235 offset:1024
	ds_read_b128 v[138:141], v235 offset:2048
	ds_read_b128 v[142:145], v235 offset:3072
	ds_read_b128 v[146:149], v236
	ds_read_b128 v[150:153], v236 offset:1024
	ds_read_b128 v[154:157], v236 offset:2048
	ds_read_b128 v[158:161], v236 offset:3072
	s_add_u32 s40, s40, 0x80000
	s_addc_u32 s41, s41, 0
	s_mov_b32 m0, s43
	v_lshl_add_u64 v[250:251], s[40:41], 0, v[194:195]
	ds_read_b128 v[174:177], v226 offset:32768
	ds_read_b128 v[178:181], v226 offset:33792
	ds_read_b128 v[182:185], v226 offset:34816
	ds_read_b128 v[186:189], v226 offset:35840
	ds_read_b128 v[190:193], v226 offset:36864
	ds_read_b128 v[238:241], v226 offset:37888
	ds_read_b128 v[242:245], v226 offset:38912
	ds_read_b128 v[246:249], v226 offset:39936
	global_load_lds_dwordx4 v[250:251], off
	v_lshl_add_u64 v[250:251], s[40:41], 0, v[204:205]
	s_mov_b32 m0, s44
	s_nop 0
	global_load_lds_dwordx4 v[250:251], off
	s_waitcnt vmcnt(8)
	s_waitcnt lgkmcnt(0)
	s_barrier
	s_waitcnt lgkmcnt(0)
	v_mfma_i32_16x16x64_i8 v[30:33], v[130:133], v[174:177], v[30:33]
	v_mfma_i32_16x16x64_i8 v[30:33], v[134:137], v[178:181], v[30:33]
	v_mfma_i32_16x16x64_i8 v[26:29], v[138:141], v[174:177], v[26:29]
	v_mfma_i32_16x16x64_i8 v[26:29], v[142:145], v[178:181], v[26:29]
	v_mfma_i32_16x16x64_i8 v[46:49], v[130:133], v[182:185], v[46:49]
	v_mfma_i32_16x16x64_i8 v[46:49], v[134:137], v[186:189], v[46:49]
	v_mfma_i32_16x16x64_i8 v[42:45], v[138:141], v[182:185], v[42:45]
	v_mfma_i32_16x16x64_i8 v[42:45], v[142:145], v[186:189], v[42:45]
	v_mfma_i32_16x16x64_i8 v[74:77], v[130:133], v[190:193], v[74:77]
	v_mfma_i32_16x16x64_i8 v[74:77], v[134:137], v[238:241], v[74:77]
	v_mfma_i32_16x16x64_i8 v[70:73], v[138:141], v[190:193], v[70:73]
	v_mfma_i32_16x16x64_i8 v[70:73], v[142:145], v[238:241], v[70:73]
	v_mfma_i32_16x16x64_i8 v[94:97], v[130:133], v[242:245], v[94:97]
	v_mfma_i32_16x16x64_i8 v[94:97], v[134:137], v[246:249], v[94:97]
	v_mfma_i32_16x16x64_i8 v[90:93], v[138:141], v[242:245], v[90:93]
	v_mfma_i32_16x16x64_i8 v[90:93], v[142:145], v[246:249], v[90:93]
	v_mfma_i32_16x16x64_i8 v[38:41], v[146:149], v[174:177], v[38:41]
	v_mfma_i32_16x16x64_i8 v[38:41], v[150:153], v[178:181], v[38:41]
	v_mfma_i32_16x16x64_i8 v[34:37], v[154:157], v[174:177], v[34:37]
	v_mfma_i32_16x16x64_i8 v[34:37], v[158:161], v[178:181], v[34:37]
	v_mfma_i32_16x16x64_i8 v[58:61], v[146:149], v[182:185], v[58:61]
	v_mfma_i32_16x16x64_i8 v[58:61], v[150:153], v[186:189], v[58:61]
	v_mfma_i32_16x16x64_i8 v[54:57], v[154:157], v[182:185], v[54:57]
	v_mfma_i32_16x16x64_i8 v[54:57], v[158:161], v[186:189], v[54:57]
	v_mfma_i32_16x16x64_i8 v[86:89], v[146:149], v[190:193], v[86:89]
	v_mfma_i32_16x16x64_i8 v[86:89], v[150:153], v[238:241], v[86:89]
	v_mfma_i32_16x16x64_i8 v[82:85], v[154:157], v[190:193], v[82:85]
	v_mfma_i32_16x16x64_i8 v[82:85], v[158:161], v[238:241], v[82:85]
	s_barrier
	s_setprio 2
	v_mfma_i32_16x16x64_i8 v[102:105], v[146:149], v[242:245], v[102:105]
	v_mfma_i32_16x16x64_i8 v[102:105], v[150:153], v[246:249], v[102:105]
	v_mfma_i32_16x16x64_i8 v[98:101], v[154:157], v[242:245], v[98:101]
	v_mfma_i32_16x16x64_i8 v[98:101], v[158:161], v[246:249], v[98:101]
	s_setprio 0
	s_cmp_eq_u32 s98, 1
	s_cbranch_scc0 .Lmy_pr_P3c_2
	s_setprio 1
.Lmy_pr_P3c_2:
	s_mov_b32 m0, s72
	v_lshl_add_u64 v[166:167], v[166:167], 0, s[6:7]
	s_add_u32 s38, s38, 0x80080
	ds_read_b128 v[174:177], v226 offset:49152
	ds_read_b128 v[178:181], v226 offset:50176
	ds_read_b128 v[182:185], v226 offset:51200
	ds_read_b128 v[186:189], v226 offset:52224
	ds_read_b128 v[190:193], v226 offset:53248
	ds_read_b128 v[238:241], v226 offset:54272
	ds_read_b128 v[242:245], v226 offset:55296
	ds_read_b128 v[246:249], v226 offset:56320
	global_load_lds_dwordx4 v[166:167], off
	v_lshl_add_u64 v[166:167], v[168:169], 0, s[6:7]
	s_mov_b32 m0, s73
	s_addc_u32 s39, s39, 0
	global_load_lds_dwordx4 v[166:167], off
	v_lshl_add_u64 v[166:167], s[38:39], 0, v[202:203]
	s_mov_b32 m0, s74
	s_nop 0
	global_load_lds_dwordx4 v[166:167], off
	v_lshl_add_u64 v[166:167], s[38:39], 0, v[206:207]
	s_mov_b32 m0, s75
	s_nop 0
	global_load_lds_dwordx4 v[166:167], off
	v_lshl_add_u64 v[166:167], v[170:171], 0, s[6:7]
	s_mov_b32 m0, s51
	s_nop 0
	global_load_lds_dwordx4 v[166:167], off
	v_lshl_add_u64 v[166:167], v[172:173], 0, s[6:7]
	s_mov_b32 m0, s53
	s_nop 0
	global_load_lds_dwordx4 v[166:167], off
	s_waitcnt vmcnt(8)
	s_waitcnt lgkmcnt(0)
	s_barrier
	s_waitcnt lgkmcnt(0)
	v_mfma_i32_16x16x64_i8 v[110:113], v[130:133], v[174:177], v[110:113]
	v_mfma_i32_16x16x64_i8 v[110:113], v[134:137], v[178:181], v[110:113]
	v_mfma_i32_16x16x64_i8 v[106:109], v[138:141], v[174:177], v[106:109]
	v_mfma_i32_16x16x64_i8 v[106:109], v[142:145], v[178:181], v[106:109]
	v_mfma_i32_16x16x64_i8 v[126:129], v[130:133], v[182:185], v[126:129]
	v_mfma_i32_16x16x64_i8 v[126:129], v[134:137], v[186:189], v[126:129]
	v_mfma_i32_16x16x64_i8 v[118:121], v[138:141], v[182:185], v[118:121]
	v_mfma_i32_16x16x64_i8 v[118:121], v[142:145], v[186:189], v[118:121]
	v_mfma_i32_16x16x64_i8 v[62:65], v[130:133], v[190:193], v[62:65]
	v_mfma_i32_16x16x64_i8 v[62:65], v[134:137], v[238:241], v[62:65]
	v_mfma_i32_16x16x64_i8 v[50:53], v[138:141], v[190:193], v[50:53]
	v_mfma_i32_16x16x64_i8 v[50:53], v[142:145], v[238:241], v[50:53]
	v_mfma_i32_16x16x64_i8 v[14:17], v[130:133], v[242:245], v[14:17]
	v_mfma_i32_16x16x64_i8 v[14:17], v[134:137], v[246:249], v[14:17]
	v_mfma_i32_16x16x64_i8 v[10:13], v[138:141], v[242:245], v[10:13]
	v_mfma_i32_16x16x64_i8 v[10:13], v[142:145], v[246:249], v[10:13]
	v_mfma_i32_16x16x64_i8 v[122:125], v[146:149], v[174:177], v[122:125]
	v_mfma_i32_16x16x64_i8 v[122:125], v[150:153], v[178:181], v[122:125]
	v_mfma_i32_16x16x64_i8 v[114:117], v[154:157], v[174:177], v[114:117]
	v_mfma_i32_16x16x64_i8 v[114:117], v[158:161], v[178:181], v[114:117]
	v_mfma_i32_16x16x64_i8 v[78:81], v[146:149], v[182:185], v[78:81]
	v_mfma_i32_16x16x64_i8 v[78:81], v[150:153], v[186:189], v[78:81]
	v_mfma_i32_16x16x64_i8 v[66:69], v[154:157], v[182:185], v[66:69]
	v_mfma_i32_16x16x64_i8 v[66:69], v[158:161], v[186:189], v[66:69]
	v_mfma_i32_16x16x64_i8 v[22:25], v[146:149], v[190:193], v[22:25]
	v_mfma_i32_16x16x64_i8 v[22:25], v[150:153], v[238:241], v[22:25]
	v_mfma_i32_16x16x64_i8 v[18:21], v[154:157], v[190:193], v[18:21]
	v_mfma_i32_16x16x64_i8 v[18:21], v[158:161], v[238:241], v[18:21]
	s_barrier
	s_setprio 2
	v_mfma_i32_16x16x64_i8 v[6:9], v[146:149], v[242:245], v[6:9]
	v_mfma_i32_16x16x64_i8 v[6:9], v[150:153], v[246:249], v[6:9]
	v_mfma_i32_16x16x64_i8 v[2:5], v[154:157], v[242:245], v[2:5]
	v_mfma_i32_16x16x64_i8 v[2:5], v[158:161], v[246:249], v[2:5]
	s_setprio 0
	s_cmp_eq_u32 s98, 1
	s_cbranch_scc0 .Lmy_pr_P3c_3
	s_setprio 1
.Lmy_pr_P3c_3:
	s_add_i32 s80, s80, 2
	s_add_u32 s36, s36, 0x100
	s_addc_u32 s37, s37, 0
	s_cmp_gt_u32 s80, 13
	s_cbranch_scc0 .LBB0_746
	s_nop 15
	s_nop 15
	s_and_b64 vcc, exec, s[8:9]
	s_cbranch_vccz .LBB0_749
	s_barrier

.LBB0_752:
	ds_read_b128 v[134:137], v227
	ds_read_b128 v[138:141], v227 offset:1024
	ds_read_b128 v[142:145], v227 offset:2048
	ds_read_b128 v[146:149], v227 offset:3072
	ds_read_b128 v[150:153], v233
	ds_read_b128 v[154:157], v233 offset:1024
	ds_read_b128 v[158:161], v233 offset:2048
	ds_read_b128 v[162:165], v233 offset:3072
	s_add_u32 s30, s29, s2
	s_addc_u32 s31, s33, s3
	s_add_u32 s30, s30, 0x200100
	s_addc_u32 s31, s31, 0
	s_add_u32 s77, s25, s2
	s_addc_u32 s78, s40, s3
	s_cmpk_eq_i32 s2, 0xf00
	s_cselect_b32 s35, s0, s31
	s_cselect_b32 s34, s1, s30
	s_cselect_b32 s31, s14, s78
	s_cselect_b32 s30, s15, s77
	s_mov_b32 m0, s66
	v_lshl_add_u64 v[242:243], v[130:131], 0, s[2:3]
	ds_read_b128 v[166:169], v226
	ds_read_b128 v[170:173], v226 offset:1024
	ds_read_b128 v[174:177], v226 offset:2048
	ds_read_b128 v[178:181], v226 offset:3072
	ds_read_b128 v[182:185], v226 offset:4096
	ds_read_b128 v[186:189], v226 offset:5120
	ds_read_b128 v[190:193], v226 offset:6144
	ds_read_b128 v[238:241], v226 offset:7168
	global_load_lds_dwordx4 v[242:243], off
	v_lshl_add_u64 v[242:243], v[132:133], 0, s[2:3]
	s_mov_b32 m0, s67
	s_nop 0
	global_load_lds_dwordx4 v[242:243], off
	s_waitcnt vmcnt(8)
	s_waitcnt lgkmcnt(0)
	s_barrier
	s_waitcnt lgkmcnt(0)
	v_mfma_f32_16x16x32_bf16 v[26:29], v[134:137], v[166:169], v[26:29]
	v_mfma_f32_16x16x32_bf16 v[30:33], v[142:145], v[166:169], v[30:33]
	v_mfma_f32_16x16x32_bf16 v[42:45], v[134:137], v[174:177], v[42:45]
	v_mfma_f32_16x16x32_bf16 v[46:49], v[142:145], v[174:177], v[46:49]
	v_mfma_f32_16x16x32_bf16 v[70:73], v[134:137], v[182:185], v[70:73]
	v_mfma_f32_16x16x32_bf16 v[74:77], v[142:145], v[182:185], v[74:77]
	v_mfma_f32_16x16x32_bf16 v[90:93], v[134:137], v[190:193], v[90:93]
	v_mfma_f32_16x16x32_bf16 v[94:97], v[142:145], v[190:193], v[94:97]
	v_mfma_f32_16x16x32_bf16 v[26:29], v[138:141], v[170:173], v[26:29]
	v_mfma_f32_16x16x32_bf16 v[30:33], v[146:149], v[170:173], v[30:33]
	v_mfma_f32_16x16x32_bf16 v[42:45], v[138:141], v[178:181], v[42:45]
	v_mfma_f32_16x16x32_bf16 v[46:49], v[146:149], v[178:181], v[46:49]
	v_mfma_f32_16x16x32_bf16 v[70:73], v[138:141], v[186:189], v[70:73]
	v_mfma_f32_16x16x32_bf16 v[74:77], v[146:149], v[186:189], v[74:77]
	v_mfma_f32_16x16x32_bf16 v[90:93], v[138:141], v[238:241], v[90:93]
	v_mfma_f32_16x16x32_bf16 v[94:97], v[146:149], v[238:241], v[94:97]
	v_mfma_f32_16x16x32_bf16 v[34:37], v[150:153], v[166:169], v[34:37]
	v_mfma_f32_16x16x32_bf16 v[38:41], v[158:161], v[166:169], v[38:41]
	v_mfma_f32_16x16x32_bf16 v[54:57], v[150:153], v[174:177], v[54:57]
	v_mfma_f32_16x16x32_bf16 v[58:61], v[158:161], v[174:177], v[58:61]
	v_mfma_f32_16x16x32_bf16 v[82:85], v[150:153], v[182:185], v[82:85]
	v_mfma_f32_16x16x32_bf16 v[86:89], v[158:161], v[182:185], v[86:89]
	v_mfma_f32_16x16x32_bf16 v[98:101], v[150:153], v[190:193], v[98:101]
	v_mfma_f32_16x16x32_bf16 v[102:105], v[158:161], v[190:193], v[102:105]
	v_mfma_f32_16x16x32_bf16 v[34:37], v[154:157], v[170:173], v[34:37]
	v_mfma_f32_16x16x32_bf16 v[38:41], v[162:165], v[170:173], v[38:41]
	v_mfma_f32_16x16x32_bf16 v[54:57], v[154:157], v[178:181], v[54:57]
	v_mfma_f32_16x16x32_bf16 v[58:61], v[162:165], v[178:181], v[58:61]
	s_barrier
	s_setprio 2
	v_mfma_f32_16x16x32_bf16 v[82:85], v[154:157], v[186:189], v[82:85]
	v_mfma_f32_16x16x32_bf16 v[86:89], v[162:165], v[186:189], v[86:89]
	v_mfma_f32_16x16x32_bf16 v[98:101], v[154:157], v[238:241], v[98:101]
	v_mfma_f32_16x16x32_bf16 v[102:105], v[162:165], v[238:241], v[102:105]
	s_setprio 0
	s_cmp_eq_u32 s98, 1
	s_cbranch_scc0 .Lmy_pr_P3d_0
	s_setprio 1
.Lmy_pr_P3d_0:
	s_mov_b32 m0, s68
	v_lshl_add_u64 v[242:243], s[30:31], 0, v[202:203]
	s_add_u32 s78, s30, 0x80000
	ds_read_b128 v[166:169], v226 offset:16384
	ds_read_b128 v[170:173], v226 offset:17408
	ds_read_b128 v[174:177], v226 offset:18432
	ds_read_b128 v[178:181], v226 offset:19456
	ds_read_b128 v[182:185], v226 offset:20480
	ds_read_b128 v[186:189], v226 offset:21504
	ds_read_b128 v[190:193], v226 offset:22528
	ds_read_b128 v[238:241], v226 offset:23552
	global_load_lds_dwordx4 v[242:243], off
	v_lshl_add_u64 v[244:245], s[30:31], 0, v[206:207]
	s_mov_b32 m0, s69
	s_addc_u32 s79, s31, 0
	global_load_lds_dwordx4 v[244:245], off
	v_lshl_add_u64 v[246:247], s[78:79], 0, v[202:203]
	s_mov_b32 m0, s70
	v_lshl_add_u64 v[248:249], s[34:35], 0, v[204:205]
	global_load_lds_dwordx4 v[246:247], off
	v_lshl_add_u64 v[246:247], s[78:79], 0, v[206:207]
	s_mov_b32 m0, s71
	s_nop 0
	global_load_lds_dwordx4 v[246:247], off
	v_lshl_add_u64 v[246:247], s[34:35], 0, v[194:195]
	s_mov_b32 m0, s23
	s_nop 0
	global_load_lds_dwordx4 v[246:247], off
	s_mov_b32 m0, s42
	s_nop 0
	global_load_lds_dwordx4 v[248:249], off
	s_waitcnt vmcnt(8)
	s_waitcnt lgkmcnt(0)
	s_barrier
	s_waitcnt lgkmcnt(0)
	v_mfma_f32_16x16x32_bf16 v[106:109], v[134:137], v[166:169], v[106:109]
	v_mfma_f32_16x16x32_bf16 v[110:113], v[142:145], v[166:169], v[110:113]
	v_mfma_f32_16x16x32_bf16 v[118:121], v[134:137], v[174:177], v[118:121]
	v_mfma_f32_16x16x32_bf16 v[126:129], v[142:145], v[174:177], v[126:129]
	v_mfma_f32_16x16x32_bf16 v[50:53], v[134:137], v[182:185], v[50:53]
	v_mfma_f32_16x16x32_bf16 v[62:65], v[142:145], v[182:185], v[62:65]
	v_mfma_f32_16x16x32_bf16 v[10:13], v[134:137], v[190:193], v[10:13]
	v_mfma_f32_16x16x32_bf16 v[14:17], v[142:145], v[190:193], v[14:17]
	v_mfma_f32_16x16x32_bf16 v[106:109], v[138:141], v[170:173], v[106:109]
	v_mfma_f32_16x16x32_bf16 v[110:113], v[146:149], v[170:173], v[110:113]
	v_mfma_f32_16x16x32_bf16 v[118:121], v[138:141], v[178:181], v[118:121]
	v_mfma_f32_16x16x32_bf16 v[126:129], v[146:149], v[178:181], v[126:129]
	v_mfma_f32_16x16x32_bf16 v[50:53], v[138:141], v[186:189], v[50:53]
	v_mfma_f32_16x16x32_bf16 v[62:65], v[146:149], v[186:189], v[62:65]
	v_mfma_f32_16x16x32_bf16 v[10:13], v[138:141], v[238:241], v[10:13]
	v_mfma_f32_16x16x32_bf16 v[14:17], v[146:149], v[238:241], v[14:17]
	v_mfma_f32_16x16x32_bf16 v[114:117], v[150:153], v[166:169], v[114:117]
	v_mfma_f32_16x16x32_bf16 v[122:125], v[158:161], v[166:169], v[122:125]
	v_mfma_f32_16x16x32_bf16 v[66:69], v[150:153], v[174:177], v[66:69]
	v_mfma_f32_16x16x32_bf16 v[78:81], v[158:161], v[174:177], v[78:81]
	v_mfma_f32_16x16x32_bf16 v[18:21], v[150:153], v[182:185], v[18:21]
	v_mfma_f32_16x16x32_bf16 v[22:25], v[158:161], v[182:185], v[22:25]
	v_mfma_f32_16x16x32_bf16 v[2:5], v[150:153], v[190:193], v[2:5]
	v_mfma_f32_16x16x32_bf16 v[6:9], v[158:161], v[190:193], v[6:9]
	v_mfma_f32_16x16x32_bf16 v[114:117], v[154:157], v[170:173], v[114:117]
	v_mfma_f32_16x16x32_bf16 v[122:125], v[162:165], v[170:173], v[122:125]
	v_mfma_f32_16x16x32_bf16 v[66:69], v[154:157], v[178:181], v[66:69]
	v_mfma_f32_16x16x32_bf16 v[78:81], v[162:165], v[178:181], v[78:81]
	s_barrier
	s_setprio 2
	v_mfma_f32_16x16x32_bf16 v[18:21], v[154:157], v[186:189], v[18:21]
	v_mfma_f32_16x16x32_bf16 v[22:25], v[162:165], v[186:189], v[22:25]
	v_mfma_f32_16x16x32_bf16 v[2:5], v[154:157], v[238:241], v[2:5]
	v_mfma_f32_16x16x32_bf16 v[6:9], v[162:165], v[238:241], v[6:9]
	s_setprio 0
	s_cmp_eq_u32 s98, 1
	s_cbranch_scc0 .Lmy_pr_P3d_1
	s_setprio 1
.Lmy_pr_P3d_1:
	ds_read_b128 v[134:137], v235
	ds_read_b128 v[138:141], v235 offset:1024
	ds_read_b128 v[142:145], v235 offset:2048
	ds_read_b128 v[146:149], v235 offset:3072
	ds_read_b128 v[150:153], v236
	ds_read_b128 v[154:157], v236 offset:1024
	ds_read_b128 v[158:161], v236 offset:2048
	ds_read_b128 v[162:165], v236 offset:3072
	s_add_u32 s34, s34, 0x80000
	s_addc_u32 s35, s35, 0
	s_mov_b32 m0, s43
	v_lshl_add_u64 v[250:251], s[34:35], 0, v[194:195]
	ds_read_b128 v[166:169], v226 offset:32768
	ds_read_b128 v[170:173], v226 offset:33792
	ds_read_b128 v[174:177], v226 offset:34816
	ds_read_b128 v[178:181], v226 offset:35840
	ds_read_b128 v[182:185], v226 offset:36864
	ds_read_b128 v[186:189], v226 offset:37888
	ds_read_b128 v[190:193], v226 offset:38912
	ds_read_b128 v[238:241], v226 offset:39936
	global_load_lds_dwordx4 v[250:251], off
	v_lshl_add_u64 v[250:251], s[34:35], 0, v[204:205]
	s_mov_b32 m0, s44
	s_nop 0
	global_load_lds_dwordx4 v[250:251], off
	s_waitcnt vmcnt(8)
	s_waitcnt lgkmcnt(0)
	s_barrier
	s_waitcnt lgkmcnt(0)
	v_mfma_f32_16x16x32_bf16 v[26:29], v[134:137], v[166:169], v[26:29]
	v_mfma_f32_16x16x32_bf16 v[30:33], v[142:145], v[166:169], v[30:33]
	v_mfma_f32_16x16x32_bf16 v[42:45], v[134:137], v[174:177], v[42:45]
	v_mfma_f32_16x16x32_bf16 v[46:49], v[142:145], v[174:177], v[46:49]
	v_mfma_f32_16x16x32_bf16 v[70:73], v[134:137], v[182:185], v[70:73]
	v_mfma_f32_16x16x32_bf16 v[74:77], v[142:145], v[182:185], v[74:77]
	v_mfma_f32_16x16x32_bf16 v[90:93], v[134:137], v[190:193], v[90:93]
	v_mfma_f32_16x16x32_bf16 v[94:97], v[142:145], v[190:193], v[94:97]
	v_mfma_f32_16x16x32_bf16 v[26:29], v[138:141], v[170:173], v[26:29]
	v_mfma_f32_16x16x32_bf16 v[30:33], v[146:149], v[170:173], v[30:33]
	v_mfma_f32_16x16x32_bf16 v[42:45], v[138:141], v[178:181], v[42:45]
	v_mfma_f32_16x16x32_bf16 v[46:49], v[146:149], v[178:181], v[46:49]
	v_mfma_f32_16x16x32_bf16 v[70:73], v[138:141], v[186:189], v[70:73]
	v_mfma_f32_16x16x32_bf16 v[74:77], v[146:149], v[186:189], v[74:77]
	v_mfma_f32_16x16x32_bf16 v[90:93], v[138:141], v[238:241], v[90:93]
	v_mfma_f32_16x16x32_bf16 v[94:97], v[146:149], v[238:241], v[94:97]
	v_mfma_f32_16x16x32_bf16 v[34:37], v[150:153], v[166:169], v[34:37]
	v_mfma_f32_16x16x32_bf16 v[38:41], v[158:161], v[166:169], v[38:41]
	v_mfma_f32_16x16x32_bf16 v[54:57], v[150:153], v[174:177], v[54:57]
	v_mfma_f32_16x16x32_bf16 v[58:61], v[158:161], v[174:177], v[58:61]
	v_mfma_f32_16x16x32_bf16 v[82:85], v[150:153], v[182:185], v[82:85]
	v_mfma_f32_16x16x32_bf16 v[86:89], v[158:161], v[182:185], v[86:89]
	v_mfma_f32_16x16x32_bf16 v[98:101], v[150:153], v[190:193], v[98:101]
	v_mfma_f32_16x16x32_bf16 v[102:105], v[158:161], v[190:193], v[102:105]
	v_mfma_f32_16x16x32_bf16 v[34:37], v[154:157], v[170:173], v[34:37]
	v_mfma_f32_16x16x32_bf16 v[38:41], v[162:165], v[170:173], v[38:41]
	v_mfma_f32_16x16x32_bf16 v[54:57], v[154:157], v[178:181], v[54:57]
	v_mfma_f32_16x16x32_bf16 v[58:61], v[162:165], v[178:181], v[58:61]
	s_barrier
	s_setprio 2
	v_mfma_f32_16x16x32_bf16 v[82:85], v[154:157], v[186:189], v[82:85]
	v_mfma_f32_16x16x32_bf16 v[86:89], v[162:165], v[186:189], v[86:89]
	v_mfma_f32_16x16x32_bf16 v[98:101], v[154:157], v[238:241], v[98:101]
	v_mfma_f32_16x16x32_bf16 v[102:105], v[162:165], v[238:241], v[102:105]
	s_setprio 0
	s_cmp_eq_u32 s98, 1
	s_cbranch_scc0 .Lmy_pr_P3d_2
	s_setprio 1
.Lmy_pr_P3d_2:
	s_mov_b32 m0, s72
	v_lshl_add_u64 v[242:243], v[242:243], 0, s[6:7]
	s_add_u32 s30, s30, 0x80080
	ds_read_b128 v[166:169], v226 offset:49152
	ds_read_b128 v[170:173], v226 offset:50176
	ds_read_b128 v[174:177], v226 offset:51200
	ds_read_b128 v[178:181], v226 offset:52224
	ds_read_b128 v[182:185], v226 offset:53248
	ds_read_b128 v[186:189], v226 offset:54272
	ds_read_b128 v[190:193], v226 offset:55296
	ds_read_b128 v[238:241], v226 offset:56320
	global_load_lds_dwordx4 v[242:243], off
	v_lshl_add_u64 v[242:243], v[244:245], 0, s[6:7]
	s_mov_b32 m0, s73
	s_addc_u32 s31, s31, 0
	global_load_lds_dwordx4 v[242:243], off
	v_lshl_add_u64 v[242:243], s[30:31], 0, v[202:203]
	s_mov_b32 m0, s74
	s_nop 0
	global_load_lds_dwordx4 v[242:243], off
	v_lshl_add_u64 v[242:243], s[30:31], 0, v[206:207]
	s_mov_b32 m0, s75
	s_nop 0
	global_load_lds_dwordx4 v[242:243], off
	v_lshl_add_u64 v[242:243], v[246:247], 0, s[6:7]
	s_mov_b32 m0, s51
	s_nop 0
	global_load_lds_dwordx4 v[242:243], off
	v_lshl_add_u64 v[242:243], v[248:249], 0, s[6:7]
	s_mov_b32 m0, s53
	s_nop 0
	global_load_lds_dwordx4 v[242:243], off
	s_waitcnt vmcnt(8)
	s_waitcnt lgkmcnt(0)
	s_barrier
	s_waitcnt lgkmcnt(0)
	v_mfma_f32_16x16x32_bf16 v[106:109], v[134:137], v[166:169], v[106:109]
	v_mfma_f32_16x16x32_bf16 v[110:113], v[142:145], v[166:169], v[110:113]
	v_mfma_f32_16x16x32_bf16 v[118:121], v[134:137], v[174:177], v[118:121]
	v_mfma_f32_16x16x32_bf16 v[126:129], v[142:145], v[174:177], v[126:129]
	v_mfma_f32_16x16x32_bf16 v[50:53], v[134:137], v[182:185], v[50:53]
	v_mfma_f32_16x16x32_bf16 v[62:65], v[142:145], v[182:185], v[62:65]
	v_mfma_f32_16x16x32_bf16 v[10:13], v[134:137], v[190:193], v[10:13]
	v_mfma_f32_16x16x32_bf16 v[14:17], v[142:145], v[190:193], v[14:17]
	v_mfma_f32_16x16x32_bf16 v[106:109], v[138:141], v[170:173], v[106:109]
	v_mfma_f32_16x16x32_bf16 v[110:113], v[146:149], v[170:173], v[110:113]
	v_mfma_f32_16x16x32_bf16 v[118:121], v[138:141], v[178:181], v[118:121]
	v_mfma_f32_16x16x32_bf16 v[126:129], v[146:149], v[178:181], v[126:129]
	v_mfma_f32_16x16x32_bf16 v[50:53], v[138:141], v[186:189], v[50:53]
	v_mfma_f32_16x16x32_bf16 v[62:65], v[146:149], v[186:189], v[62:65]
	v_mfma_f32_16x16x32_bf16 v[10:13], v[138:141], v[238:241], v[10:13]
	v_mfma_f32_16x16x32_bf16 v[14:17], v[146:149], v[238:241], v[14:17]
	v_mfma_f32_16x16x32_bf16 v[114:117], v[150:153], v[166:169], v[114:117]
	v_mfma_f32_16x16x32_bf16 v[122:125], v[158:161], v[166:169], v[122:125]
	v_mfma_f32_16x16x32_bf16 v[66:69], v[150:153], v[174:177], v[66:69]
	v_mfma_f32_16x16x32_bf16 v[78:81], v[158:161], v[174:177], v[78:81]
	v_mfma_f32_16x16x32_bf16 v[18:21], v[150:153], v[182:185], v[18:21]
	v_mfma_f32_16x16x32_bf16 v[22:25], v[158:161], v[182:185], v[22:25]
	v_mfma_f32_16x16x32_bf16 v[2:5], v[150:153], v[190:193], v[2:5]
	v_mfma_f32_16x16x32_bf16 v[6:9], v[158:161], v[190:193], v[6:9]
	v_mfma_f32_16x16x32_bf16 v[114:117], v[154:157], v[170:173], v[114:117]
	v_mfma_f32_16x16x32_bf16 v[122:125], v[162:165], v[170:173], v[122:125]
	v_mfma_f32_16x16x32_bf16 v[66:69], v[154:157], v[178:181], v[66:69]
	v_mfma_f32_16x16x32_bf16 v[78:81], v[162:165], v[178:181], v[78:81]
	s_barrier
	s_setprio 2
	v_mfma_f32_16x16x32_bf16 v[18:21], v[154:157], v[186:189], v[18:21]
	v_mfma_f32_16x16x32_bf16 v[22:25], v[162:165], v[186:189], v[22:25]
	v_mfma_f32_16x16x32_bf16 v[2:5], v[154:157], v[238:241], v[2:5]
	v_mfma_f32_16x16x32_bf16 v[6:9], v[162:165], v[238:241], v[6:9]
	s_setprio 0
	s_cmp_eq_u32 s98, 1
	s_cbranch_scc0 .Lmy_pr_P3d_3
	s_setprio 1
.Lmy_pr_P3d_3:
	s_add_i32 s41, s41, 2
	s_add_u32 s2, s2, 0x100
	s_addc_u32 s3, s3, 0
	s_cmp_gt_u32 s41, 29
	s_cbranch_scc0 .LBB0_752
	s_and_b64 vcc, exec, s[8:9]
	s_cbranch_vccz .LBB0_755
	s_barrier

.LBB0_817:
	ds_read_b128 v[130:133], v223
	ds_read_b128 v[134:137], v223 offset:1024
	ds_read_b128 v[138:141], v223 offset:2048
	ds_read_b128 v[142:145], v223 offset:3072
	ds_read_b128 v[146:149], v224
	ds_read_b128 v[150:153], v224 offset:1024
	ds_read_b128 v[154:157], v224 offset:2048
	ds_read_b128 v[158:161], v224 offset:3072
	s_add_u32 s6, s4, 0xfff00080
	s_addc_u32 s7, s5, -1
	s_cmp_eq_u32 s14, 60
	s_cselect_b32 s9, s19, s7
	s_cselect_b32 s8, s18, s6
	s_cselect_b32 s7, s79, s1
	s_cselect_b32 s6, s78, s0
	v_lshl_add_u64 v[194:195], s[4:5], 0, v[170:171]
	s_add_i32 m0, s35, 0xc000
	ds_read_b128 v[174:177], v225
	ds_read_b128 v[178:181], v225 offset:1024
	ds_read_b128 v[182:185], v225 offset:2048
	ds_read_b128 v[186:189], v225 offset:3072
	ds_read_b128 v[190:193], v225 offset:4096
	ds_read_b128 v[202:205], v225 offset:5120
	ds_read_b128 v[206:209], v225 offset:6144
	ds_read_b128 v[210:213], v225 offset:7168
	global_load_lds_dwordx4 v[194:195], off
	v_lshl_add_u64 v[194:195], s[4:5], 0, v[172:173]
	s_add_i32 m0, s35, 0xe000
	s_nop 0
	global_load_lds_dwordx4 v[194:195], off
	s_waitcnt vmcnt(8)
	s_waitcnt lgkmcnt(0)
	s_barrier
	s_waitcnt lgkmcnt(0)
	v_mfma_f32_16x16x32_bf16 v[14:17], v[130:133], v[174:177], v[14:17]
	v_mfma_f32_16x16x32_bf16 v[10:13], v[138:141], v[174:177], v[10:13]
	v_mfma_f32_16x16x32_bf16 v[34:37], v[130:133], v[182:185], v[34:37]
	v_mfma_f32_16x16x32_bf16 v[26:29], v[138:141], v[182:185], v[26:29]
	v_mfma_f32_16x16x32_bf16 v[46:49], v[130:133], v[190:193], v[46:49]
	v_mfma_f32_16x16x32_bf16 v[42:45], v[138:141], v[190:193], v[42:45]
	v_mfma_f32_16x16x32_bf16 v[62:65], v[130:133], v[206:209], v[62:65]
	v_mfma_f32_16x16x32_bf16 v[58:61], v[138:141], v[206:209], v[58:61]
	v_mfma_f32_16x16x32_bf16 v[14:17], v[134:137], v[178:181], v[14:17]
	v_mfma_f32_16x16x32_bf16 v[10:13], v[142:145], v[178:181], v[10:13]
	v_mfma_f32_16x16x32_bf16 v[34:37], v[134:137], v[186:189], v[34:37]
	v_mfma_f32_16x16x32_bf16 v[26:29], v[142:145], v[186:189], v[26:29]
	v_mfma_f32_16x16x32_bf16 v[46:49], v[134:137], v[202:205], v[46:49]
	v_mfma_f32_16x16x32_bf16 v[42:45], v[142:145], v[202:205], v[42:45]
	v_mfma_f32_16x16x32_bf16 v[62:65], v[134:137], v[210:213], v[62:65]
	v_mfma_f32_16x16x32_bf16 v[58:61], v[142:145], v[210:213], v[58:61]
	v_mfma_f32_16x16x32_bf16 v[6:9], v[146:149], v[174:177], v[6:9]
	v_mfma_f32_16x16x32_bf16 v[2:5], v[154:157], v[174:177], v[2:5]
	v_mfma_f32_16x16x32_bf16 v[22:25], v[146:149], v[182:185], v[22:25]
	v_mfma_f32_16x16x32_bf16 v[18:21], v[154:157], v[182:185], v[18:21]
	v_mfma_f32_16x16x32_bf16 v[38:41], v[146:149], v[190:193], v[38:41]
	v_mfma_f32_16x16x32_bf16 v[30:33], v[154:157], v[190:193], v[30:33]
	v_mfma_f32_16x16x32_bf16 v[54:57], v[146:149], v[206:209], v[54:57]
	v_mfma_f32_16x16x32_bf16 v[50:53], v[154:157], v[206:209], v[50:53]
	v_mfma_f32_16x16x32_bf16 v[6:9], v[150:153], v[178:181], v[6:9]
	v_mfma_f32_16x16x32_bf16 v[2:5], v[158:161], v[178:181], v[2:5]
	v_mfma_f32_16x16x32_bf16 v[22:25], v[150:153], v[186:189], v[22:25]
	v_mfma_f32_16x16x32_bf16 v[18:21], v[158:161], v[186:189], v[18:21]
	s_barrier
	s_setprio 2
	v_mfma_f32_16x16x32_bf16 v[38:41], v[150:153], v[202:205], v[38:41]
	v_mfma_f32_16x16x32_bf16 v[30:33], v[158:161], v[202:205], v[30:33]
	v_mfma_f32_16x16x32_bf16 v[54:57], v[150:153], v[210:213], v[54:57]
	v_mfma_f32_16x16x32_bf16 v[50:53], v[158:161], v[210:213], v[50:53]
	s_setprio 0
	s_cmp_eq_u32 s98, 1
	s_cbranch_scc0 .Lmy_pr_P4_0
	s_setprio 1
.Lmy_pr_P4_0:
	s_add_i32 s15, s17, s33
	v_lshl_add_u64 v[194:195], s[6:7], 0, v[164:165]
	s_mov_b32 m0, s15
	ds_read_b128 v[174:177], v225 offset:16384
	ds_read_b128 v[178:181], v225 offset:17408
	ds_read_b128 v[182:185], v225 offset:18432
	ds_read_b128 v[186:189], v225 offset:19456
	ds_read_b128 v[190:193], v225 offset:20480
	ds_read_b128 v[202:205], v225 offset:21504
	ds_read_b128 v[206:209], v225 offset:22528
	ds_read_b128 v[210:213], v225 offset:23552
	global_load_lds_dwordx4 v[194:195], off
	s_add_i32 m0, s15, 0x2000
	s_add_u32 s44, s6, 0x100000
	v_lshl_add_u64 v[214:215], s[6:7], 0, v[168:169]
	s_addc_u32 s45, s7, 0
	s_add_i32 s15, s55, s33
	global_load_lds_dwordx4 v[214:215], off
	v_lshl_add_u64 v[216:217], s[44:45], 0, v[164:165]
	s_mov_b32 m0, s15
	v_lshl_add_u64 v[218:219], s[8:9], 0, v[166:167]
	global_load_lds_dwordx4 v[216:217], off
	v_lshl_add_u64 v[216:217], s[44:45], 0, v[168:169]
	s_add_i32 m0, s15, 0x2000
	s_nop 0
	global_load_lds_dwordx4 v[216:217], off
	v_lshl_add_u64 v[216:217], s[8:9], 0, v[162:163]
	s_mov_b32 m0, s35
	s_nop 0
	global_load_lds_dwordx4 v[216:217], off
	s_mov_b32 m0, s80
	s_nop 0
	global_load_lds_dwordx4 v[218:219], off
	s_waitcnt vmcnt(8)
	s_waitcnt lgkmcnt(0)
	s_barrier
	s_waitcnt lgkmcnt(0)
	v_mfma_f32_16x16x32_bf16 v[78:81], v[130:133], v[174:177], v[78:81]
	v_mfma_f32_16x16x32_bf16 v[74:77], v[138:141], v[174:177], v[74:77]
	v_mfma_f32_16x16x32_bf16 v[94:97], v[130:133], v[182:185], v[94:97]
	v_mfma_f32_16x16x32_bf16 v[90:93], v[138:141], v[182:185], v[90:93]
	v_mfma_f32_16x16x32_bf16 v[110:113], v[130:133], v[190:193], v[110:113]
	v_mfma_f32_16x16x32_bf16 v[106:109], v[138:141], v[190:193], v[106:109]
	v_mfma_f32_16x16x32_bf16 v[118:121], v[130:133], v[206:209], v[118:121]
	v_mfma_f32_16x16x32_bf16 v[114:117], v[138:141], v[206:209], v[114:117]
	v_mfma_f32_16x16x32_bf16 v[78:81], v[134:137], v[178:181], v[78:81]
	v_mfma_f32_16x16x32_bf16 v[74:77], v[142:145], v[178:181], v[74:77]
	v_mfma_f32_16x16x32_bf16 v[94:97], v[134:137], v[186:189], v[94:97]
	v_mfma_f32_16x16x32_bf16 v[90:93], v[142:145], v[186:189], v[90:93]
	v_mfma_f32_16x16x32_bf16 v[110:113], v[134:137], v[202:205], v[110:113]
	v_mfma_f32_16x16x32_bf16 v[106:109], v[142:145], v[202:205], v[106:109]
	v_mfma_f32_16x16x32_bf16 v[118:121], v[134:137], v[210:213], v[118:121]
	v_mfma_f32_16x16x32_bf16 v[114:117], v[142:145], v[210:213], v[114:117]
	v_mfma_f32_16x16x32_bf16 v[70:73], v[146:149], v[174:177], v[70:73]
	v_mfma_f32_16x16x32_bf16 v[66:69], v[154:157], v[174:177], v[66:69]
	v_mfma_f32_16x16x32_bf16 v[86:89], v[146:149], v[182:185], v[86:89]
	v_mfma_f32_16x16x32_bf16 v[82:85], v[154:157], v[182:185], v[82:85]
	v_mfma_f32_16x16x32_bf16 v[102:105], v[146:149], v[190:193], v[102:105]
	v_mfma_f32_16x16x32_bf16 v[98:101], v[154:157], v[190:193], v[98:101]
	v_mfma_f32_16x16x32_bf16 v[122:125], v[146:149], v[206:209], v[122:125]
	v_mfma_f32_16x16x32_bf16 v[126:129], v[154:157], v[206:209], v[126:129]
	v_mfma_f32_16x16x32_bf16 v[70:73], v[150:153], v[178:181], v[70:73]
	v_mfma_f32_16x16x32_bf16 v[66:69], v[158:161], v[178:181], v[66:69]
	v_mfma_f32_16x16x32_bf16 v[86:89], v[150:153], v[186:189], v[86:89]
	v_mfma_f32_16x16x32_bf16 v[82:85], v[158:161], v[186:189], v[82:85]
	s_barrier
	s_setprio 2
	v_mfma_f32_16x16x32_bf16 v[102:105], v[150:153], v[202:205], v[102:105]
	v_mfma_f32_16x16x32_bf16 v[98:101], v[158:161], v[202:205], v[98:101]
	v_mfma_f32_16x16x32_bf16 v[122:125], v[150:153], v[210:213], v[122:125]
	v_mfma_f32_16x16x32_bf16 v[126:129], v[158:161], v[210:213], v[126:129]
	s_setprio 0
	s_cmp_eq_u32 s98, 1
	s_cbranch_scc0 .Lmy_pr_P4_1
	s_setprio 1
.Lmy_pr_P4_1:
	s_add_i32 s56, 0, 0x18000
	s_add_i32 s57, 0, 0x1c000
	v_add_u32_e32 v142, s56, v222
	v_add_u32_e32 v158, s57, v222
	ds_read_b128 v[130:133], v142
	ds_read_b128 v[134:137], v142 offset:1024
	ds_read_b128 v[138:141], v142 offset:2048
	ds_read_b128 v[142:145], v142 offset:3072
	ds_read_b128 v[146:149], v158
	ds_read_b128 v[150:153], v158 offset:1024
	ds_read_b128 v[154:157], v158 offset:2048
	ds_read_b128 v[158:161], v158 offset:3072
	s_add_u32 s8, s8, 0x100000
	s_addc_u32 s9, s9, 0
	s_mov_b32 m0, s59
	v_lshl_add_u64 v[238:239], s[8:9], 0, v[162:163]
	ds_read_b128 v[174:177], v225 offset:32768
	ds_read_b128 v[178:181], v225 offset:33792
	ds_read_b128 v[182:185], v225 offset:34816
	ds_read_b128 v[186:189], v225 offset:35840
	ds_read_b128 v[190:193], v225 offset:36864
	ds_read_b128 v[202:205], v225 offset:37888
	ds_read_b128 v[206:209], v225 offset:38912
	ds_read_b128 v[210:213], v225 offset:39936
	global_load_lds_dwordx4 v[238:239], off
	v_lshl_add_u64 v[238:239], s[8:9], 0, v[166:167]
	s_mov_b32 m0, s60
	s_nop 0
	global_load_lds_dwordx4 v[238:239], off
	s_waitcnt vmcnt(8)
	s_waitcnt lgkmcnt(0)
	s_barrier
	s_waitcnt lgkmcnt(0)
	v_mfma_f32_16x16x32_bf16 v[14:17], v[130:133], v[174:177], v[14:17]
	v_mfma_f32_16x16x32_bf16 v[10:13], v[138:141], v[174:177], v[10:13]
	v_mfma_f32_16x16x32_bf16 v[34:37], v[130:133], v[182:185], v[34:37]
	v_mfma_f32_16x16x32_bf16 v[26:29], v[138:141], v[182:185], v[26:29]
	v_mfma_f32_16x16x32_bf16 v[46:49], v[130:133], v[190:193], v[46:49]
	v_mfma_f32_16x16x32_bf16 v[42:45], v[138:141], v[190:193], v[42:45]
	v_mfma_f32_16x16x32_bf16 v[62:65], v[130:133], v[206:209], v[62:65]
	v_mfma_f32_16x16x32_bf16 v[58:61], v[138:141], v[206:209], v[58:61]
	v_mfma_f32_16x16x32_bf16 v[14:17], v[134:137], v[178:181], v[14:17]
	v_mfma_f32_16x16x32_bf16 v[10:13], v[142:145], v[178:181], v[10:13]
	v_mfma_f32_16x16x32_bf16 v[34:37], v[134:137], v[186:189], v[34:37]
	v_mfma_f32_16x16x32_bf16 v[26:29], v[142:145], v[186:189], v[26:29]
	v_mfma_f32_16x16x32_bf16 v[46:49], v[134:137], v[202:205], v[46:49]
	v_mfma_f32_16x16x32_bf16 v[42:45], v[142:145], v[202:205], v[42:45]
	v_mfma_f32_16x16x32_bf16 v[62:65], v[134:137], v[210:213], v[62:65]
	v_mfma_f32_16x16x32_bf16 v[58:61], v[142:145], v[210:213], v[58:61]
	v_mfma_f32_16x16x32_bf16 v[6:9], v[146:149], v[174:177], v[6:9]
	v_mfma_f32_16x16x32_bf16 v[2:5], v[154:157], v[174:177], v[2:5]
	v_mfma_f32_16x16x32_bf16 v[22:25], v[146:149], v[182:185], v[22:25]
	v_mfma_f32_16x16x32_bf16 v[18:21], v[154:157], v[182:185], v[18:21]
	v_mfma_f32_16x16x32_bf16 v[38:41], v[146:149], v[190:193], v[38:41]
	v_mfma_f32_16x16x32_bf16 v[30:33], v[154:157], v[190:193], v[30:33]
	v_mfma_f32_16x16x32_bf16 v[54:57], v[146:149], v[206:209], v[54:57]
	v_mfma_f32_16x16x32_bf16 v[50:53], v[154:157], v[206:209], v[50:53]
	v_mfma_f32_16x16x32_bf16 v[6:9], v[150:153], v[178:181], v[6:9]
	v_mfma_f32_16x16x32_bf16 v[2:5], v[158:161], v[178:181], v[2:5]
	v_mfma_f32_16x16x32_bf16 v[22:25], v[150:153], v[186:189], v[22:25]
	v_mfma_f32_16x16x32_bf16 v[18:21], v[158:161], v[186:189], v[18:21]
	s_barrier
	s_setprio 2
	v_mfma_f32_16x16x32_bf16 v[38:41], v[150:153], v[202:205], v[38:41]
	v_mfma_f32_16x16x32_bf16 v[30:33], v[158:161], v[202:205], v[30:33]
	v_mfma_f32_16x16x32_bf16 v[54:57], v[150:153], v[210:213], v[54:57]
	v_mfma_f32_16x16x32_bf16 v[50:53], v[158:161], v[210:213], v[50:53]
	s_setprio 0
	s_cmp_eq_u32 s98, 1
	s_cbranch_scc0 .Lmy_pr_P4_2
	s_setprio 1
.Lmy_pr_P4_2:
	s_add_i32 s8, s56, s33
	v_lshl_add_u64 v[194:195], v[194:195], 0, s[26:27]
	s_mov_b32 m0, s8
	ds_read_b128 v[174:177], v225 offset:49152
	ds_read_b128 v[178:181], v225 offset:50176
	ds_read_b128 v[182:185], v225 offset:51200
	ds_read_b128 v[186:189], v225 offset:52224
	ds_read_b128 v[190:193], v225 offset:53248
	ds_read_b128 v[202:205], v225 offset:54272
	ds_read_b128 v[206:209], v225 offset:55296
	ds_read_b128 v[210:213], v225 offset:56320
	global_load_lds_dwordx4 v[194:195], off
	s_add_i32 m0, s8, 0x2000
	s_add_u32 s6, s6, 0x100080
	v_lshl_add_u64 v[194:195], v[214:215], 0, s[26:27]
	s_addc_u32 s7, s7, 0
	s_add_i32 s8, s57, s33
	global_load_lds_dwordx4 v[194:195], off
	v_lshl_add_u64 v[194:195], s[6:7], 0, v[164:165]
	s_mov_b32 m0, s8
	s_nop 0
	global_load_lds_dwordx4 v[194:195], off
	v_lshl_add_u64 v[194:195], s[6:7], 0, v[168:169]
	s_add_i32 m0, s8, 0x2000
	s_nop 0
	global_load_lds_dwordx4 v[194:195], off
	v_lshl_add_u64 v[194:195], v[216:217], 0, s[26:27]
	s_mov_b32 m0, s65
	s_nop 0
	global_load_lds_dwordx4 v[194:195], off
	v_lshl_add_u64 v[194:195], v[218:219], 0, s[26:27]
	s_mov_b32 m0, s66
	s_nop 0
	global_load_lds_dwordx4 v[194:195], off
	s_waitcnt vmcnt(8)
	s_waitcnt lgkmcnt(0)
	s_barrier
	s_waitcnt lgkmcnt(0)
	v_mfma_f32_16x16x32_bf16 v[78:81], v[130:133], v[174:177], v[78:81]
	v_mfma_f32_16x16x32_bf16 v[74:77], v[138:141], v[174:177], v[74:77]
	v_mfma_f32_16x16x32_bf16 v[94:97], v[130:133], v[182:185], v[94:97]
	v_mfma_f32_16x16x32_bf16 v[90:93], v[138:141], v[182:185], v[90:93]
	v_mfma_f32_16x16x32_bf16 v[110:113], v[130:133], v[190:193], v[110:113]
	v_mfma_f32_16x16x32_bf16 v[106:109], v[138:141], v[190:193], v[106:109]
	v_mfma_f32_16x16x32_bf16 v[118:121], v[130:133], v[206:209], v[118:121]
	v_mfma_f32_16x16x32_bf16 v[114:117], v[138:141], v[206:209], v[114:117]
	v_mfma_f32_16x16x32_bf16 v[78:81], v[134:137], v[178:181], v[78:81]
	v_mfma_f32_16x16x32_bf16 v[74:77], v[142:145], v[178:181], v[74:77]
	v_mfma_f32_16x16x32_bf16 v[94:97], v[134:137], v[186:189], v[94:97]
	v_mfma_f32_16x16x32_bf16 v[90:93], v[142:145], v[186:189], v[90:93]
	v_mfma_f32_16x16x32_bf16 v[110:113], v[134:137], v[202:205], v[110:113]
	v_mfma_f32_16x16x32_bf16 v[106:109], v[142:145], v[202:205], v[106:109]
	v_mfma_f32_16x16x32_bf16 v[118:121], v[134:137], v[210:213], v[118:121]
	v_mfma_f32_16x16x32_bf16 v[114:117], v[142:145], v[210:213], v[114:117]
	v_mfma_f32_16x16x32_bf16 v[70:73], v[146:149], v[174:177], v[70:73]
	v_mfma_f32_16x16x32_bf16 v[66:69], v[154:157], v[174:177], v[66:69]
	v_mfma_f32_16x16x32_bf16 v[86:89], v[146:149], v[182:185], v[86:89]
	v_mfma_f32_16x16x32_bf16 v[82:85], v[154:157], v[182:185], v[82:85]
	v_mfma_f32_16x16x32_bf16 v[102:105], v[146:149], v[190:193], v[102:105]
	v_mfma_f32_16x16x32_bf16 v[98:101], v[154:157], v[190:193], v[98:101]
	v_mfma_f32_16x16x32_bf16 v[122:125], v[146:149], v[206:209], v[122:125]
	v_mfma_f32_16x16x32_bf16 v[126:129], v[154:157], v[206:209], v[126:129]
	v_mfma_f32_16x16x32_bf16 v[70:73], v[150:153], v[178:181], v[70:73]
	v_mfma_f32_16x16x32_bf16 v[66:69], v[158:161], v[178:181], v[66:69]
	v_mfma_f32_16x16x32_bf16 v[86:89], v[150:153], v[186:189], v[86:89]
	v_mfma_f32_16x16x32_bf16 v[82:85], v[158:161], v[186:189], v[82:85]
	s_barrier
	s_setprio 2
	v_mfma_f32_16x16x32_bf16 v[102:105], v[150:153], v[202:205], v[102:105]
	v_mfma_f32_16x16x32_bf16 v[98:101], v[158:161], v[202:205], v[98:101]
	v_mfma_f32_16x16x32_bf16 v[122:125], v[150:153], v[210:213], v[122:125]
	v_mfma_f32_16x16x32_bf16 v[126:129], v[158:161], v[210:213], v[126:129]
	s_setprio 0
	s_cmp_eq_u32 s98, 1
	s_cbranch_scc0 .Lmy_pr_P4_3
	s_setprio 1
.Lmy_pr_P4_3:
	s_add_i32 s14, s14, 2
	s_add_u32 s4, s4, 0x100
	s_addc_u32 s5, s5, 0
	s_add_u32 s0, s0, 0x100
	s_addc_u32 s1, s1, 0
	s_cmp_gt_u32 s14, 61
	s_cbranch_scc0 .LBB0_817
	s_and_b64 vcc, exec, s[28:29]
	s_cbranch_vccz .LBB0_820
	s_barrier

.LBB0_961:
	ds_read_b128 v[158:161], v185
	ds_read_b128 v[154:157], v185 offset:1024
	ds_read_b128 v[150:153], v185 offset:2048
	ds_read_b128 v[146:149], v185 offset:3072
	ds_read_b128 v[142:145], v186
	ds_read_b128 v[138:141], v186 offset:1024
	ds_read_b128 v[134:137], v186 offset:2048
	ds_read_b128 v[130:133], v186 offset:3072
	s_add_u32 s30, s28, 0xfff80080
	s_addc_u32 s31, s29, -1
	s_cmp_eq_u32 s45, 28
	s_cselect_b32 s35, s1, s31
	s_cselect_b32 s34, s15, s30
	s_cselect_b32 s31, s19, s44
	s_cselect_b32 s30, s42, s43
	v_lshl_add_u64 v[220:221], s[28:29], 0, v[170:171]
	s_add_i32 m0, s27, 0xc000
	ds_read_b128 v[174:177], v187
	ds_read_b128 v[178:181], v187 offset:1024
	ds_read_b128 v[188:191], v187 offset:2048
	ds_read_b128 v[192:195], v187 offset:3072
	ds_read_b128 v[202:205], v187 offset:4096
	ds_read_b128 v[206:209], v187 offset:5120
	ds_read_b128 v[210:213], v187 offset:6144
	ds_read_b128 v[214:217], v187 offset:7168
	global_load_lds_dwordx4 v[220:221], off
	v_lshl_add_u64 v[220:221], s[28:29], 0, v[172:173]
	s_add_i32 m0, s27, 0xe000
	s_nop 0
	global_load_lds_dwordx4 v[220:221], off
	s_waitcnt vmcnt(8)
	s_waitcnt lgkmcnt(0)
	s_barrier
	s_waitcnt lgkmcnt(0)
	v_mfma_i32_16x16x64_i8 v[126:129], v[158:161], v[174:177], v[126:129]
	v_mfma_i32_16x16x64_i8 v[126:129], v[154:157], v[178:181], v[126:129]
	v_mfma_i32_16x16x64_i8 v[122:125], v[150:153], v[174:177], v[122:125]
	v_mfma_i32_16x16x64_i8 v[122:125], v[146:149], v[178:181], v[122:125]
	v_mfma_i32_16x16x64_i8 v[110:113], v[158:161], v[188:191], v[110:113]
	v_mfma_i32_16x16x64_i8 v[110:113], v[154:157], v[192:195], v[110:113]
	v_mfma_i32_16x16x64_i8 v[106:109], v[150:153], v[188:191], v[106:109]
	v_mfma_i32_16x16x64_i8 v[106:109], v[146:149], v[192:195], v[106:109]
	v_mfma_i32_16x16x64_i8 v[94:97], v[158:161], v[202:205], v[94:97]
	v_mfma_i32_16x16x64_i8 v[94:97], v[154:157], v[206:209], v[94:97]
	v_mfma_i32_16x16x64_i8 v[90:93], v[150:153], v[202:205], v[90:93]
	v_mfma_i32_16x16x64_i8 v[90:93], v[146:149], v[206:209], v[90:93]
	v_mfma_i32_16x16x64_i8 v[78:81], v[158:161], v[210:213], v[78:81]
	v_mfma_i32_16x16x64_i8 v[78:81], v[154:157], v[214:217], v[78:81]
	v_mfma_i32_16x16x64_i8 v[74:77], v[150:153], v[210:213], v[74:77]
	v_mfma_i32_16x16x64_i8 v[74:77], v[146:149], v[214:217], v[74:77]
	v_mfma_i32_16x16x64_i8 v[118:121], v[142:145], v[174:177], v[118:121]
	v_mfma_i32_16x16x64_i8 v[118:121], v[138:141], v[178:181], v[118:121]
	v_mfma_i32_16x16x64_i8 v[114:117], v[134:137], v[174:177], v[114:117]
	v_mfma_i32_16x16x64_i8 v[114:117], v[130:133], v[178:181], v[114:117]
	v_mfma_i32_16x16x64_i8 v[102:105], v[142:145], v[188:191], v[102:105]
	v_mfma_i32_16x16x64_i8 v[102:105], v[138:141], v[192:195], v[102:105]
	v_mfma_i32_16x16x64_i8 v[98:101], v[134:137], v[188:191], v[98:101]
	v_mfma_i32_16x16x64_i8 v[98:101], v[130:133], v[192:195], v[98:101]
	v_mfma_i32_16x16x64_i8 v[86:89], v[142:145], v[202:205], v[86:89]
	v_mfma_i32_16x16x64_i8 v[86:89], v[138:141], v[206:209], v[86:89]
	v_mfma_i32_16x16x64_i8 v[82:85], v[134:137], v[202:205], v[82:85]
	v_mfma_i32_16x16x64_i8 v[82:85], v[130:133], v[206:209], v[82:85]
	s_barrier
	s_setprio 2
	v_mfma_i32_16x16x64_i8 v[70:73], v[142:145], v[210:213], v[70:73]
	v_mfma_i32_16x16x64_i8 v[70:73], v[138:141], v[214:217], v[70:73]
	v_mfma_i32_16x16x64_i8 v[66:69], v[134:137], v[210:213], v[66:69]
	v_mfma_i32_16x16x64_i8 v[66:69], v[130:133], v[214:217], v[66:69]
	s_setprio 0
	s_cmp_eq_u32 s98, 1
	s_cbranch_scc0 .Lmy_pr_P5_0
	s_setprio 1
.Lmy_pr_P5_0:
	s_add_i32 s46, s17, s9
	v_lshl_add_u64 v[174:175], s[30:31], 0, v[166:167]
	s_mov_b32 m0, s46
	ds_read_b128 v[188:191], v187 offset:16384
	ds_read_b128 v[192:195], v187 offset:17408
	ds_read_b128 v[202:205], v187 offset:18432
	ds_read_b128 v[206:209], v187 offset:19456
	ds_read_b128 v[210:213], v187 offset:20480
	ds_read_b128 v[214:217], v187 offset:21504
	ds_read_b128 v[220:223], v187 offset:22528
	ds_read_b128 v[224:227], v187 offset:23552
	global_load_lds_dwordx4 v[174:175], off
	s_add_i32 m0, s46, 0x2000
	s_add_u32 s46, s30, 0x80000
	v_lshl_add_u64 v[176:177], s[30:31], 0, v[162:163]
	s_addc_u32 s47, s31, 0
	s_add_i32 s48, s55, s9
	global_load_lds_dwordx4 v[176:177], off
	v_lshl_add_u64 v[178:179], s[46:47], 0, v[166:167]
	s_mov_b32 m0, s48
	v_lshl_add_u64 v[180:181], s[34:35], 0, v[164:165]
	global_load_lds_dwordx4 v[178:179], off
	v_lshl_add_u64 v[178:179], s[46:47], 0, v[162:163]
	s_add_i32 m0, s48, 0x2000
	s_nop 0
	global_load_lds_dwordx4 v[178:179], off
	v_lshl_add_u64 v[178:179], s[34:35], 0, v[168:169]
	s_mov_b32 m0, s27
	s_nop 0
	global_load_lds_dwordx4 v[178:179], off
	s_mov_b32 m0, s33
	s_nop 0
	global_load_lds_dwordx4 v[180:181], off
	s_waitcnt vmcnt(8)
	s_waitcnt lgkmcnt(0)
	s_barrier
	s_waitcnt lgkmcnt(0)
	v_mfma_i32_16x16x64_i8 v[62:65], v[158:161], v[188:191], v[62:65]
	v_mfma_i32_16x16x64_i8 v[62:65], v[154:157], v[192:195], v[62:65]
	v_mfma_i32_16x16x64_i8 v[58:61], v[150:153], v[188:191], v[58:61]
	v_mfma_i32_16x16x64_i8 v[58:61], v[146:149], v[192:195], v[58:61]
	v_mfma_i32_16x16x64_i8 v[46:49], v[158:161], v[202:205], v[46:49]
	v_mfma_i32_16x16x64_i8 v[46:49], v[154:157], v[206:209], v[46:49]
	v_mfma_i32_16x16x64_i8 v[42:45], v[150:153], v[202:205], v[42:45]
	v_mfma_i32_16x16x64_i8 v[42:45], v[146:149], v[206:209], v[42:45]
	v_mfma_i32_16x16x64_i8 v[30:33], v[158:161], v[210:213], v[30:33]
	v_mfma_i32_16x16x64_i8 v[30:33], v[154:157], v[214:217], v[30:33]
	v_mfma_i32_16x16x64_i8 v[26:29], v[150:153], v[210:213], v[26:29]
	v_mfma_i32_16x16x64_i8 v[26:29], v[146:149], v[214:217], v[26:29]
	v_mfma_i32_16x16x64_i8 v[14:17], v[158:161], v[220:223], v[14:17]
	v_mfma_i32_16x16x64_i8 v[14:17], v[154:157], v[224:227], v[14:17]
	v_mfma_i32_16x16x64_i8 v[10:13], v[150:153], v[220:223], v[10:13]
	v_mfma_i32_16x16x64_i8 v[10:13], v[146:149], v[224:227], v[10:13]
	v_mfma_i32_16x16x64_i8 v[54:57], v[142:145], v[188:191], v[54:57]
	v_mfma_i32_16x16x64_i8 v[54:57], v[138:141], v[192:195], v[54:57]
	v_mfma_i32_16x16x64_i8 v[50:53], v[134:137], v[188:191], v[50:53]
	v_mfma_i32_16x16x64_i8 v[50:53], v[130:133], v[192:195], v[50:53]
	v_mfma_i32_16x16x64_i8 v[38:41], v[142:145], v[202:205], v[38:41]
	v_mfma_i32_16x16x64_i8 v[38:41], v[138:141], v[206:209], v[38:41]
	v_mfma_i32_16x16x64_i8 v[34:37], v[134:137], v[202:205], v[34:37]
	v_mfma_i32_16x16x64_i8 v[34:37], v[130:133], v[206:209], v[34:37]
	v_mfma_i32_16x16x64_i8 v[22:25], v[142:145], v[210:213], v[22:25]
	v_mfma_i32_16x16x64_i8 v[22:25], v[138:141], v[214:217], v[22:25]
	v_mfma_i32_16x16x64_i8 v[18:21], v[134:137], v[210:213], v[18:21]
	v_mfma_i32_16x16x64_i8 v[18:21], v[130:133], v[214:217], v[18:21]
	s_barrier
	s_setprio 2
	v_mfma_i32_16x16x64_i8 v[6:9], v[142:145], v[220:223], v[6:9]
	v_mfma_i32_16x16x64_i8 v[6:9], v[138:141], v[224:227], v[6:9]
	v_mfma_i32_16x16x64_i8 v[2:5], v[134:137], v[220:223], v[2:5]
	v_mfma_i32_16x16x64_i8 v[2:5], v[130:133], v[224:227], v[2:5]
	s_setprio 0
	s_cmp_eq_u32 s98, 1
	s_cbranch_scc0 .Lmy_pr_P5_1
	s_setprio 1
.Lmy_pr_P5_1:
	v_add_u32_e32 v142, s56, v183
	v_add_u32_e32 v158, s57, v183
	ds_read_b128 v[130:133], v142
	ds_read_b128 v[134:137], v142 offset:1024
	ds_read_b128 v[138:141], v142 offset:2048
	ds_read_b128 v[142:145], v142 offset:3072
	ds_read_b128 v[146:149], v158
	ds_read_b128 v[150:153], v158 offset:1024
	ds_read_b128 v[154:157], v158 offset:2048
	ds_read_b128 v[158:161], v158 offset:3072
	s_add_u32 s34, s34, 0x80000
	s_addc_u32 s35, s35, 0
	s_mov_b32 m0, s36
	v_lshl_add_u64 v[232:233], s[34:35], 0, v[168:169]
	ds_read_b128 v[188:191], v187 offset:32768
	ds_read_b128 v[192:195], v187 offset:33792
	ds_read_b128 v[202:205], v187 offset:34816
	ds_read_b128 v[206:209], v187 offset:35840
	ds_read_b128 v[210:213], v187 offset:36864
	ds_read_b128 v[214:217], v187 offset:37888
	ds_read_b128 v[220:223], v187 offset:38912
	ds_read_b128 v[224:227], v187 offset:39936
	global_load_lds_dwordx4 v[232:233], off
	v_lshl_add_u64 v[232:233], s[34:35], 0, v[164:165]
	s_mov_b32 m0, s37
	s_nop 0
	global_load_lds_dwordx4 v[232:233], off
	s_waitcnt vmcnt(8)
	s_waitcnt lgkmcnt(0)
	s_barrier
	s_waitcnt lgkmcnt(0)
	v_mfma_i32_16x16x64_i8 v[126:129], v[130:133], v[188:191], v[126:129]
	v_mfma_i32_16x16x64_i8 v[126:129], v[134:137], v[192:195], v[126:129]
	v_mfma_i32_16x16x64_i8 v[122:125], v[138:141], v[188:191], v[122:125]
	v_mfma_i32_16x16x64_i8 v[122:125], v[142:145], v[192:195], v[122:125]
	v_mfma_i32_16x16x64_i8 v[110:113], v[130:133], v[202:205], v[110:113]
	v_mfma_i32_16x16x64_i8 v[110:113], v[134:137], v[206:209], v[110:113]
	v_mfma_i32_16x16x64_i8 v[106:109], v[138:141], v[202:205], v[106:109]
	v_mfma_i32_16x16x64_i8 v[106:109], v[142:145], v[206:209], v[106:109]
	v_mfma_i32_16x16x64_i8 v[94:97], v[130:133], v[210:213], v[94:97]
	v_mfma_i32_16x16x64_i8 v[94:97], v[134:137], v[214:217], v[94:97]
	v_mfma_i32_16x16x64_i8 v[90:93], v[138:141], v[210:213], v[90:93]
	v_mfma_i32_16x16x64_i8 v[90:93], v[142:145], v[214:217], v[90:93]
	v_mfma_i32_16x16x64_i8 v[78:81], v[130:133], v[220:223], v[78:81]
	v_mfma_i32_16x16x64_i8 v[78:81], v[134:137], v[224:227], v[78:81]
	v_mfma_i32_16x16x64_i8 v[74:77], v[138:141], v[220:223], v[74:77]
	v_mfma_i32_16x16x64_i8 v[74:77], v[142:145], v[224:227], v[74:77]
	v_mfma_i32_16x16x64_i8 v[118:121], v[146:149], v[188:191], v[118:121]
	v_mfma_i32_16x16x64_i8 v[118:121], v[150:153], v[192:195], v[118:121]
	v_mfma_i32_16x16x64_i8 v[114:117], v[154:157], v[188:191], v[114:117]
	v_mfma_i32_16x16x64_i8 v[114:117], v[158:161], v[192:195], v[114:117]
	v_mfma_i32_16x16x64_i8 v[102:105], v[146:149], v[202:205], v[102:105]
	v_mfma_i32_16x16x64_i8 v[102:105], v[150:153], v[206:209], v[102:105]
	v_mfma_i32_16x16x64_i8 v[98:101], v[154:157], v[202:205], v[98:101]
	v_mfma_i32_16x16x64_i8 v[98:101], v[158:161], v[206:209], v[98:101]
	v_mfma_i32_16x16x64_i8 v[86:89], v[146:149], v[210:213], v[86:89]
	v_mfma_i32_16x16x64_i8 v[86:89], v[150:153], v[214:217], v[86:89]
	v_mfma_i32_16x16x64_i8 v[82:85], v[154:157], v[210:213], v[82:85]
	v_mfma_i32_16x16x64_i8 v[82:85], v[158:161], v[214:217], v[82:85]
	s_barrier
	s_setprio 2
	v_mfma_i32_16x16x64_i8 v[70:73], v[146:149], v[220:223], v[70:73]
	v_mfma_i32_16x16x64_i8 v[70:73], v[150:153], v[224:227], v[70:73]
	v_mfma_i32_16x16x64_i8 v[66:69], v[154:157], v[220:223], v[66:69]
	v_mfma_i32_16x16x64_i8 v[66:69], v[158:161], v[224:227], v[66:69]
	s_setprio 0
	s_cmp_eq_u32 s98, 1
	s_cbranch_scc0 .Lmy_pr_P5_2
	s_setprio 1
.Lmy_pr_P5_2:
	s_add_i32 s34, s56, s9
	v_lshl_add_u64 v[174:175], v[174:175], 0, s[4:5]
	s_mov_b32 m0, s34
	ds_read_b128 v[188:191], v187 offset:49152
	ds_read_b128 v[192:195], v187 offset:50176
	ds_read_b128 v[202:205], v187 offset:51200
	ds_read_b128 v[206:209], v187 offset:52224
	ds_read_b128 v[210:213], v187 offset:53248
	ds_read_b128 v[214:217], v187 offset:54272
	ds_read_b128 v[220:223], v187 offset:55296
	ds_read_b128 v[224:227], v187 offset:56320
	global_load_lds_dwordx4 v[174:175], off
	s_add_i32 m0, s34, 0x2000
	s_add_u32 s30, s30, 0x80080
	v_lshl_add_u64 v[174:175], v[176:177], 0, s[4:5]
	s_addc_u32 s31, s31, 0
	s_add_i32 s34, s57, s9
	global_load_lds_dwordx4 v[174:175], off
	v_lshl_add_u64 v[174:175], s[30:31], 0, v[166:167]
	s_mov_b32 m0, s34
	s_nop 0
	global_load_lds_dwordx4 v[174:175], off
	v_lshl_add_u64 v[174:175], s[30:31], 0, v[162:163]
	s_add_i32 m0, s34, 0x2000
	s_nop 0
	global_load_lds_dwordx4 v[174:175], off
	v_lshl_add_u64 v[174:175], v[178:179], 0, s[4:5]
	s_mov_b32 m0, s39
	s_nop 0
	global_load_lds_dwordx4 v[174:175], off
	v_lshl_add_u64 v[174:175], v[180:181], 0, s[4:5]
	s_mov_b32 m0, s40
	s_nop 0
	global_load_lds_dwordx4 v[174:175], off
	s_waitcnt vmcnt(8)
	s_waitcnt lgkmcnt(0)
	s_barrier
	s_waitcnt lgkmcnt(0)
	v_mfma_i32_16x16x64_i8 v[62:65], v[130:133], v[188:191], v[62:65]
	v_mfma_i32_16x16x64_i8 v[62:65], v[134:137], v[192:195], v[62:65]
	v_mfma_i32_16x16x64_i8 v[58:61], v[138:141], v[188:191], v[58:61]
	v_mfma_i32_16x16x64_i8 v[58:61], v[142:145], v[192:195], v[58:61]
	v_mfma_i32_16x16x64_i8 v[46:49], v[130:133], v[202:205], v[46:49]
	v_mfma_i32_16x16x64_i8 v[46:49], v[134:137], v[206:209], v[46:49]
	v_mfma_i32_16x16x64_i8 v[42:45], v[138:141], v[202:205], v[42:45]
	v_mfma_i32_16x16x64_i8 v[42:45], v[142:145], v[206:209], v[42:45]
	v_mfma_i32_16x16x64_i8 v[30:33], v[130:133], v[210:213], v[30:33]
	v_mfma_i32_16x16x64_i8 v[30:33], v[134:137], v[214:217], v[30:33]
	v_mfma_i32_16x16x64_i8 v[26:29], v[138:141], v[210:213], v[26:29]
	v_mfma_i32_16x16x64_i8 v[26:29], v[142:145], v[214:217], v[26:29]
	v_mfma_i32_16x16x64_i8 v[14:17], v[130:133], v[220:223], v[14:17]
	v_mfma_i32_16x16x64_i8 v[14:17], v[134:137], v[224:227], v[14:17]
	v_mfma_i32_16x16x64_i8 v[10:13], v[138:141], v[220:223], v[10:13]
	v_mfma_i32_16x16x64_i8 v[10:13], v[142:145], v[224:227], v[10:13]
	v_mfma_i32_16x16x64_i8 v[54:57], v[146:149], v[188:191], v[54:57]
	v_mfma_i32_16x16x64_i8 v[54:57], v[150:153], v[192:195], v[54:57]
	v_mfma_i32_16x16x64_i8 v[50:53], v[154:157], v[188:191], v[50:53]
	v_mfma_i32_16x16x64_i8 v[50:53], v[158:161], v[192:195], v[50:53]
	v_mfma_i32_16x16x64_i8 v[38:41], v[146:149], v[202:205], v[38:41]
	v_mfma_i32_16x16x64_i8 v[38:41], v[150:153], v[206:209], v[38:41]
	v_mfma_i32_16x16x64_i8 v[34:37], v[154:157], v[202:205], v[34:37]
	v_mfma_i32_16x16x64_i8 v[34:37], v[158:161], v[206:209], v[34:37]
	v_mfma_i32_16x16x64_i8 v[22:25], v[146:149], v[210:213], v[22:25]
	v_mfma_i32_16x16x64_i8 v[22:25], v[150:153], v[214:217], v[22:25]
	v_mfma_i32_16x16x64_i8 v[18:21], v[154:157], v[210:213], v[18:21]
	v_mfma_i32_16x16x64_i8 v[18:21], v[158:161], v[214:217], v[18:21]
	s_barrier
	s_setprio 2
	v_mfma_i32_16x16x64_i8 v[6:9], v[146:149], v[220:223], v[6:9]
	v_mfma_i32_16x16x64_i8 v[6:9], v[150:153], v[224:227], v[6:9]
	v_mfma_i32_16x16x64_i8 v[2:5], v[154:157], v[220:223], v[2:5]
	v_mfma_i32_16x16x64_i8 v[2:5], v[158:161], v[224:227], v[2:5]
	s_setprio 0
	s_cmp_eq_u32 s98, 1
	s_cbranch_scc0 .Lmy_pr_P5_3
	s_setprio 1
.Lmy_pr_P5_3:
	s_add_i32 s45, s45, 2
	s_add_u32 s28, s28, 0x100
	s_addc_u32 s29, s29, 0
	s_add_u32 s43, s43, 0x100
	s_addc_u32 s44, s44, 0
	s_cmp_gt_u32 s45, 29
	s_cbranch_scc0 .LBB0_961
	s_nop 15
	s_nop 15
	s_and_b64 vcc, exec, s[6:7]
	s_cbranch_vccz .LBB0_964
	s_barrier

.LBB0_1058:
	ds_read_b128 v[128:131], v194
	ds_read_b128 v[132:135], v194 offset:1024
	ds_read_b128 v[136:139], v194 offset:2048
	ds_read_b128 v[140:143], v194 offset:3072
	ds_read_b128 v[144:147], v195
	ds_read_b128 v[148:151], v195 offset:1024
	ds_read_b128 v[152:155], v195 offset:2048
	ds_read_b128 v[156:159], v195 offset:3072
	s_add_u32 s2, s0, 0x100
	s_addc_u32 s3, s1, 0
	s_cmpk_eq_i32 s39, 0xa8
	s_cselect_b32 s37, s31, s3
	s_cselect_b32 s36, s30, s2
	s_cselect_b32 s5, s7, s38
	s_cselect_b32 s4, s6, s29
	v_lshl_add_u64 v[188:189], s[0:1], 0, v[168:169]
	s_add_i32 m0, s27, 0xc000
	ds_read_b128 v[172:175], v196
	ds_read_b128 v[176:179], v196 offset:1024
	ds_read_b128 v[180:183], v196 offset:2048
	ds_read_b128 v[184:187], v196 offset:3072
	ds_read_b128 v[200:203], v196 offset:4096
	ds_read_b128 v[204:207], v196 offset:5120
	ds_read_b128 v[208:211], v196 offset:6144
	ds_read_b128 v[212:215], v196 offset:7168
	global_load_lds_dwordx4 v[188:189], off
	v_lshl_add_u64 v[188:189], s[0:1], 0, v[170:171]
	s_add_i32 m0, s27, 0xe000
	s_nop 0
	global_load_lds_dwordx4 v[188:189], off
	s_waitcnt vmcnt(8)
	s_waitcnt lgkmcnt(0)
	s_barrier
	s_waitcnt lgkmcnt(0)
	v_mfma_f32_16x16x32_bf16 v[12:15], v[128:131], v[172:175], v[12:15]
	v_mfma_f32_16x16x32_bf16 v[8:11], v[136:139], v[172:175], v[8:11]
	v_mfma_f32_16x16x32_bf16 v[36:39], v[128:131], v[180:183], v[36:39]
	v_mfma_f32_16x16x32_bf16 v[32:35], v[136:139], v[180:183], v[32:35]
	v_mfma_f32_16x16x32_bf16 v[44:47], v[128:131], v[200:203], v[44:47]
	v_mfma_f32_16x16x32_bf16 v[40:43], v[136:139], v[200:203], v[40:43]
	v_mfma_f32_16x16x32_bf16 v[64:67], v[128:131], v[208:211], v[64:67]
	v_mfma_f32_16x16x32_bf16 v[56:59], v[136:139], v[208:211], v[56:59]
	v_mfma_f32_16x16x32_bf16 v[12:15], v[132:135], v[176:179], v[12:15]
	v_mfma_f32_16x16x32_bf16 v[8:11], v[140:143], v[176:179], v[8:11]
	v_mfma_f32_16x16x32_bf16 v[36:39], v[132:135], v[184:187], v[36:39]
	v_mfma_f32_16x16x32_bf16 v[32:35], v[140:143], v[184:187], v[32:35]
	v_mfma_f32_16x16x32_bf16 v[44:47], v[132:135], v[204:207], v[44:47]
	v_mfma_f32_16x16x32_bf16 v[40:43], v[140:143], v[204:207], v[40:43]
	v_mfma_f32_16x16x32_bf16 v[64:67], v[132:135], v[212:215], v[64:67]
	v_mfma_f32_16x16x32_bf16 v[56:59], v[140:143], v[212:215], v[56:59]
	v_mfma_f32_16x16x32_bf16 v[4:7], v[144:147], v[172:175], v[4:7]
	v_mfma_f32_16x16x32_bf16 v[0:3], v[152:155], v[172:175], v[0:3]
	v_mfma_f32_16x16x32_bf16 v[24:27], v[144:147], v[180:183], v[24:27]
	v_mfma_f32_16x16x32_bf16 v[16:19], v[152:155], v[180:183], v[16:19]
	v_mfma_f32_16x16x32_bf16 v[28:31], v[144:147], v[200:203], v[28:31]
	v_mfma_f32_16x16x32_bf16 v[20:23], v[152:155], v[200:203], v[20:23]
	v_mfma_f32_16x16x32_bf16 v[52:55], v[144:147], v[208:211], v[52:55]
	v_mfma_f32_16x16x32_bf16 v[48:51], v[152:155], v[208:211], v[48:51]
	v_mfma_f32_16x16x32_bf16 v[4:7], v[148:151], v[176:179], v[4:7]
	v_mfma_f32_16x16x32_bf16 v[0:3], v[156:159], v[176:179], v[0:3]
	v_mfma_f32_16x16x32_bf16 v[24:27], v[148:151], v[184:187], v[24:27]
	v_mfma_f32_16x16x32_bf16 v[16:19], v[156:159], v[184:187], v[16:19]
	s_barrier
	s_setprio 2
	v_mfma_f32_16x16x32_bf16 v[28:31], v[148:151], v[204:207], v[28:31]
	v_mfma_f32_16x16x32_bf16 v[20:23], v[156:159], v[204:207], v[20:23]
	v_mfma_f32_16x16x32_bf16 v[52:55], v[148:151], v[212:215], v[52:55]
	v_mfma_f32_16x16x32_bf16 v[48:51], v[156:159], v[212:215], v[48:51]
	s_setprio 0
	s_cmp_eq_u32 s98, 1
	s_cbranch_scc0 .Lmy_pr_P6_0
	s_setprio 1
.Lmy_pr_P6_0:
	s_add_i32 s0, s17, s25
	v_lshl_add_u64 v[188:189], s[4:5], 0, v[162:163]
	s_mov_b32 m0, s0
	ds_read_b128 v[172:175], v196 offset:16384
	ds_read_b128 v[176:179], v196 offset:17408
	ds_read_b128 v[180:183], v196 offset:18432
	ds_read_b128 v[184:187], v196 offset:19456
	ds_read_b128 v[200:203], v196 offset:20480
	ds_read_b128 v[204:207], v196 offset:21504
	ds_read_b128 v[208:211], v196 offset:22528
	ds_read_b128 v[212:215], v196 offset:23552
	global_load_lds_dwordx4 v[188:189], off
	s_add_i32 m0, s0, 0x2000
	s_add_u32 s0, s4, 0x2b0000
	v_lshl_add_u64 v[216:217], s[4:5], 0, v[166:167]
	s_addc_u32 s1, s5, 0
	s_add_i32 s40, s55, s25
	global_load_lds_dwordx4 v[216:217], off
	v_lshl_add_u64 v[220:221], s[0:1], 0, v[162:163]
	s_mov_b32 m0, s40
	v_lshl_add_u64 v[222:223], s[36:37], 0, v[164:165]
	global_load_lds_dwordx4 v[220:221], off
	v_lshl_add_u64 v[220:221], s[0:1], 0, v[166:167]
	s_add_i32 m0, s40, 0x2000
	s_nop 0
	global_load_lds_dwordx4 v[220:221], off
	v_lshl_add_u64 v[220:221], s[36:37], 0, v[160:161]
	s_mov_b32 m0, s27
	s_nop 0
	global_load_lds_dwordx4 v[220:221], off
	s_mov_b32 m0, s33
	s_nop 0
	global_load_lds_dwordx4 v[222:223], off
	s_waitcnt vmcnt(8)
	s_waitcnt lgkmcnt(0)
	s_barrier
	s_waitcnt lgkmcnt(0)
	v_mfma_f32_16x16x32_bf16 v[76:79], v[128:131], v[172:175], v[76:79]
	v_mfma_f32_16x16x32_bf16 v[72:75], v[136:139], v[172:175], v[72:75]
	v_mfma_f32_16x16x32_bf16 v[92:95], v[128:131], v[180:183], v[92:95]
	v_mfma_f32_16x16x32_bf16 v[88:91], v[136:139], v[180:183], v[88:91]
	v_mfma_f32_16x16x32_bf16 v[108:111], v[128:131], v[200:203], v[108:111]
	v_mfma_f32_16x16x32_bf16 v[104:107], v[136:139], v[200:203], v[104:107]
	v_mfma_f32_16x16x32_bf16 v[124:127], v[128:131], v[208:211], v[124:127]
	v_mfma_f32_16x16x32_bf16 v[120:123], v[136:139], v[208:211], v[120:123]
	v_mfma_f32_16x16x32_bf16 v[76:79], v[132:135], v[176:179], v[76:79]
	v_mfma_f32_16x16x32_bf16 v[72:75], v[140:143], v[176:179], v[72:75]
	v_mfma_f32_16x16x32_bf16 v[92:95], v[132:135], v[184:187], v[92:95]
	v_mfma_f32_16x16x32_bf16 v[88:91], v[140:143], v[184:187], v[88:91]
	v_mfma_f32_16x16x32_bf16 v[108:111], v[132:135], v[204:207], v[108:111]
	v_mfma_f32_16x16x32_bf16 v[104:107], v[140:143], v[204:207], v[104:107]
	v_mfma_f32_16x16x32_bf16 v[124:127], v[132:135], v[212:215], v[124:127]
	v_mfma_f32_16x16x32_bf16 v[120:123], v[140:143], v[212:215], v[120:123]
	v_mfma_f32_16x16x32_bf16 v[68:71], v[144:147], v[172:175], v[68:71]
	v_mfma_f32_16x16x32_bf16 v[60:63], v[152:155], v[172:175], v[60:63]
	v_mfma_f32_16x16x32_bf16 v[84:87], v[144:147], v[180:183], v[84:87]
	v_mfma_f32_16x16x32_bf16 v[80:83], v[152:155], v[180:183], v[80:83]
	v_mfma_f32_16x16x32_bf16 v[100:103], v[144:147], v[200:203], v[100:103]
	v_mfma_f32_16x16x32_bf16 v[96:99], v[152:155], v[200:203], v[96:99]
	v_mfma_f32_16x16x32_bf16 v[116:119], v[144:147], v[208:211], v[116:119]
	v_mfma_f32_16x16x32_bf16 v[112:115], v[152:155], v[208:211], v[112:115]
	v_mfma_f32_16x16x32_bf16 v[68:71], v[148:151], v[176:179], v[68:71]
	v_mfma_f32_16x16x32_bf16 v[60:63], v[156:159], v[176:179], v[60:63]
	v_mfma_f32_16x16x32_bf16 v[84:87], v[148:151], v[184:187], v[84:87]
	v_mfma_f32_16x16x32_bf16 v[80:83], v[156:159], v[184:187], v[80:83]
	s_barrier
	s_setprio 2
	v_mfma_f32_16x16x32_bf16 v[100:103], v[148:151], v[204:207], v[100:103]
	v_mfma_f32_16x16x32_bf16 v[96:99], v[156:159], v[204:207], v[96:99]
	v_mfma_f32_16x16x32_bf16 v[116:119], v[148:151], v[212:215], v[116:119]
	v_mfma_f32_16x16x32_bf16 v[112:115], v[156:159], v[212:215], v[112:115]
	s_setprio 0
	s_cmp_eq_u32 s98, 1
	s_cbranch_scc0 .Lmy_pr_P6_1
	s_setprio 1
.Lmy_pr_P6_1:
	v_add_u32_e32 v140, s56, v193
	v_add_u32_e32 v156, s57, v193
	ds_read_b128 v[128:131], v140
	ds_read_b128 v[132:135], v140 offset:1024
	ds_read_b128 v[136:139], v140 offset:2048
	ds_read_b128 v[140:143], v140 offset:3072
	ds_read_b128 v[144:147], v156
	ds_read_b128 v[148:151], v156 offset:1024
	ds_read_b128 v[152:155], v156 offset:2048
	ds_read_b128 v[156:159], v156 offset:3072
	s_add_u32 s0, s36, 0x2b0000
	s_addc_u32 s1, s37, 0
	s_mov_b32 m0, s46
	v_lshl_add_u64 v[224:225], s[0:1], 0, v[160:161]
	ds_read_b128 v[172:175], v196 offset:32768
	ds_read_b128 v[176:179], v196 offset:33792
	ds_read_b128 v[180:183], v196 offset:34816
	ds_read_b128 v[184:187], v196 offset:35840
	ds_read_b128 v[200:203], v196 offset:36864
	ds_read_b128 v[204:207], v196 offset:37888
	ds_read_b128 v[208:211], v196 offset:38912
	ds_read_b128 v[212:215], v196 offset:39936
	global_load_lds_dwordx4 v[224:225], off
	v_lshl_add_u64 v[224:225], s[0:1], 0, v[164:165]
	s_mov_b32 m0, s47
	s_nop 0
	global_load_lds_dwordx4 v[224:225], off
	s_waitcnt vmcnt(8)
	s_waitcnt lgkmcnt(0)
	s_barrier
	s_waitcnt lgkmcnt(0)
	v_mfma_f32_16x16x32_bf16 v[12:15], v[128:131], v[172:175], v[12:15]
	v_mfma_f32_16x16x32_bf16 v[8:11], v[136:139], v[172:175], v[8:11]
	v_mfma_f32_16x16x32_bf16 v[36:39], v[128:131], v[180:183], v[36:39]
	v_mfma_f32_16x16x32_bf16 v[32:35], v[136:139], v[180:183], v[32:35]
	v_mfma_f32_16x16x32_bf16 v[44:47], v[128:131], v[200:203], v[44:47]
	v_mfma_f32_16x16x32_bf16 v[40:43], v[136:139], v[200:203], v[40:43]
	v_mfma_f32_16x16x32_bf16 v[64:67], v[128:131], v[208:211], v[64:67]
	v_mfma_f32_16x16x32_bf16 v[56:59], v[136:139], v[208:211], v[56:59]
	v_mfma_f32_16x16x32_bf16 v[12:15], v[132:135], v[176:179], v[12:15]
	v_mfma_f32_16x16x32_bf16 v[8:11], v[140:143], v[176:179], v[8:11]
	v_mfma_f32_16x16x32_bf16 v[36:39], v[132:135], v[184:187], v[36:39]
	v_mfma_f32_16x16x32_bf16 v[32:35], v[140:143], v[184:187], v[32:35]
	v_mfma_f32_16x16x32_bf16 v[44:47], v[132:135], v[204:207], v[44:47]
	v_mfma_f32_16x16x32_bf16 v[40:43], v[140:143], v[204:207], v[40:43]
	v_mfma_f32_16x16x32_bf16 v[64:67], v[132:135], v[212:215], v[64:67]
	v_mfma_f32_16x16x32_bf16 v[56:59], v[140:143], v[212:215], v[56:59]
	v_mfma_f32_16x16x32_bf16 v[4:7], v[144:147], v[172:175], v[4:7]
	v_mfma_f32_16x16x32_bf16 v[0:3], v[152:155], v[172:175], v[0:3]
	v_mfma_f32_16x16x32_bf16 v[24:27], v[144:147], v[180:183], v[24:27]
	v_mfma_f32_16x16x32_bf16 v[16:19], v[152:155], v[180:183], v[16:19]
	v_mfma_f32_16x16x32_bf16 v[28:31], v[144:147], v[200:203], v[28:31]
	v_mfma_f32_16x16x32_bf16 v[20:23], v[152:155], v[200:203], v[20:23]
	v_mfma_f32_16x16x32_bf16 v[52:55], v[144:147], v[208:211], v[52:55]
	v_mfma_f32_16x16x32_bf16 v[48:51], v[152:155], v[208:211], v[48:51]
	v_mfma_f32_16x16x32_bf16 v[4:7], v[148:151], v[176:179], v[4:7]
	v_mfma_f32_16x16x32_bf16 v[0:3], v[156:159], v[176:179], v[0:3]
	v_mfma_f32_16x16x32_bf16 v[24:27], v[148:151], v[184:187], v[24:27]
	v_mfma_f32_16x16x32_bf16 v[16:19], v[156:159], v[184:187], v[16:19]
	s_barrier
	s_setprio 2
	v_mfma_f32_16x16x32_bf16 v[28:31], v[148:151], v[204:207], v[28:31]
	v_mfma_f32_16x16x32_bf16 v[20:23], v[156:159], v[204:207], v[20:23]
	v_mfma_f32_16x16x32_bf16 v[52:55], v[148:151], v[212:215], v[52:55]
	v_mfma_f32_16x16x32_bf16 v[48:51], v[156:159], v[212:215], v[48:51]
	s_setprio 0
	s_cmp_eq_u32 s98, 1
	s_cbranch_scc0 .Lmy_pr_P6_2
	s_setprio 1
.Lmy_pr_P6_2:
	s_add_i32 s0, s56, s25
	v_lshl_add_u64 v[188:189], v[188:189], 0, s[18:19]
	s_mov_b32 m0, s0
	ds_read_b128 v[172:175], v196 offset:49152
	ds_read_b128 v[176:179], v196 offset:50176
	ds_read_b128 v[180:183], v196 offset:51200
	ds_read_b128 v[184:187], v196 offset:52224
	ds_read_b128 v[200:203], v196 offset:53248
	ds_read_b128 v[204:207], v196 offset:54272
	ds_read_b128 v[208:211], v196 offset:55296
	ds_read_b128 v[212:215], v196 offset:56320
	global_load_lds_dwordx4 v[188:189], off
	s_add_i32 m0, s0, 0x2000
	s_add_u32 s0, s4, 0x2b0080
	v_lshl_add_u64 v[188:189], v[216:217], 0, s[18:19]
	s_addc_u32 s1, s5, 0
	s_add_i32 s4, s57, s25
	global_load_lds_dwordx4 v[188:189], off
	v_lshl_add_u64 v[188:189], s[0:1], 0, v[162:163]
	s_mov_b32 m0, s4
	s_nop 0
	global_load_lds_dwordx4 v[188:189], off
	v_lshl_add_u64 v[188:189], s[0:1], 0, v[166:167]
	s_add_i32 m0, s4, 0x2000
	s_nop 0
	global_load_lds_dwordx4 v[188:189], off
	v_lshl_add_u64 v[188:189], v[220:221], 0, s[18:19]
	s_mov_b32 m0, s52
	s_nop 0
	global_load_lds_dwordx4 v[188:189], off
	v_lshl_add_u64 v[188:189], v[222:223], 0, s[18:19]
	s_mov_b32 m0, s53
	s_nop 0
	global_load_lds_dwordx4 v[188:189], off
	s_waitcnt vmcnt(8)
	s_waitcnt lgkmcnt(0)
	s_barrier
	s_waitcnt lgkmcnt(0)
	v_mfma_f32_16x16x32_bf16 v[76:79], v[128:131], v[172:175], v[76:79]
	v_mfma_f32_16x16x32_bf16 v[72:75], v[136:139], v[172:175], v[72:75]
	v_mfma_f32_16x16x32_bf16 v[92:95], v[128:131], v[180:183], v[92:95]
	v_mfma_f32_16x16x32_bf16 v[88:91], v[136:139], v[180:183], v[88:91]
	v_mfma_f32_16x16x32_bf16 v[108:111], v[128:131], v[200:203], v[108:111]
	v_mfma_f32_16x16x32_bf16 v[104:107], v[136:139], v[200:203], v[104:107]
	v_mfma_f32_16x16x32_bf16 v[124:127], v[128:131], v[208:211], v[124:127]
	v_mfma_f32_16x16x32_bf16 v[120:123], v[136:139], v[208:211], v[120:123]
	v_mfma_f32_16x16x32_bf16 v[76:79], v[132:135], v[176:179], v[76:79]
	v_mfma_f32_16x16x32_bf16 v[72:75], v[140:143], v[176:179], v[72:75]
	v_mfma_f32_16x16x32_bf16 v[92:95], v[132:135], v[184:187], v[92:95]
	v_mfma_f32_16x16x32_bf16 v[88:91], v[140:143], v[184:187], v[88:91]
	v_mfma_f32_16x16x32_bf16 v[108:111], v[132:135], v[204:207], v[108:111]
	v_mfma_f32_16x16x32_bf16 v[104:107], v[140:143], v[204:207], v[104:107]
	v_mfma_f32_16x16x32_bf16 v[124:127], v[132:135], v[212:215], v[124:127]
	v_mfma_f32_16x16x32_bf16 v[120:123], v[140:143], v[212:215], v[120:123]
	v_mfma_f32_16x16x32_bf16 v[68:71], v[144:147], v[172:175], v[68:71]
	v_mfma_f32_16x16x32_bf16 v[60:63], v[152:155], v[172:175], v[60:63]
	v_mfma_f32_16x16x32_bf16 v[84:87], v[144:147], v[180:183], v[84:87]
	v_mfma_f32_16x16x32_bf16 v[80:83], v[152:155], v[180:183], v[80:83]
	v_mfma_f32_16x16x32_bf16 v[100:103], v[144:147], v[200:203], v[100:103]
	v_mfma_f32_16x16x32_bf16 v[96:99], v[152:155], v[200:203], v[96:99]
	v_mfma_f32_16x16x32_bf16 v[116:119], v[144:147], v[208:211], v[116:119]
	v_mfma_f32_16x16x32_bf16 v[112:115], v[152:155], v[208:211], v[112:115]
	v_mfma_f32_16x16x32_bf16 v[68:71], v[148:151], v[176:179], v[68:71]
	v_mfma_f32_16x16x32_bf16 v[60:63], v[156:159], v[176:179], v[60:63]
	v_mfma_f32_16x16x32_bf16 v[84:87], v[148:151], v[184:187], v[84:87]
	v_mfma_f32_16x16x32_bf16 v[80:83], v[156:159], v[184:187], v[80:83]
	s_barrier
	s_setprio 2
	v_mfma_f32_16x16x32_bf16 v[100:103], v[148:151], v[204:207], v[100:103]
	v_mfma_f32_16x16x32_bf16 v[96:99], v[156:159], v[204:207], v[96:99]
	v_mfma_f32_16x16x32_bf16 v[116:119], v[148:151], v[212:215], v[116:119]
	v_mfma_f32_16x16x32_bf16 v[112:115], v[156:159], v[212:215], v[112:115]
	s_setprio 0
	s_cmp_eq_u32 s98, 1
	s_cbranch_scc0 .Lmy_pr_P6_3
	s_setprio 1
.Lmy_pr_P6_3:
	s_add_i32 s39, s39, 2
	s_add_u32 s29, s29, 0x100
	s_addc_u32 s38, s38, 0
	s_cmpk_gt_u32 s39, 0xa9
	s_mov_b64 s[0:1], s[2:3]
	s_cbranch_scc0 .LBB0_1058
	s_and_b64 vcc, exec, s[20:21]
	s_cbranch_vccz .LBB0_1061
	s_barrier

	.amdhsa_kernel _Z10fwd_kernel4Args
		.amdhsa_group_segment_fixed_size 0
		.amdhsa_private_segment_fixed_size 0
		.amdhsa_kernarg_size 416
		.amdhsa_user_sgpr_count 2
		.amdhsa_user_sgpr_dispatch_ptr 0
		.amdhsa_user_sgpr_queue_ptr 0
		.amdhsa_user_sgpr_kernarg_segment_ptr 1
		.amdhsa_user_sgpr_dispatch_id 0
		.amdhsa_user_sgpr_kernarg_preload_length 0
		.amdhsa_user_sgpr_kernarg_preload_offset 0
		.amdhsa_user_sgpr_private_segment_size 0
		.amdhsa_uses_dynamic_stack 0
		.amdhsa_enable_private_segment 0
		.amdhsa_system_sgpr_workgroup_id_x 1
		.amdhsa_system_sgpr_workgroup_id_y 0
		.amdhsa_system_sgpr_workgroup_id_z 0
		.amdhsa_system_sgpr_workgroup_info 0
		.amdhsa_system_vgpr_workitem_id 0
		.amdhsa_next_free_vgpr 255
		.amdhsa_next_free_sgpr 102
		.amdhsa_accum_offset 256
		.amdhsa_reserve_vcc 1
		.amdhsa_float_round_mode_32 0
		.amdhsa_float_round_mode_16_64 0
		.amdhsa_float_denorm_mode_32 3
		.amdhsa_float_denorm_mode_16_64 3
		.amdhsa_dx10_clamp 1
		.amdhsa_ieee_mode 1
		.amdhsa_fp16_overflow 0
		.amdhsa_tg_split 0
		.amdhsa_exception_fp_ieee_invalid_op 0
		.amdhsa_exception_fp_denorm_src 0
		.amdhsa_exception_fp_ieee_div_zero 0
		.amdhsa_exception_fp_ieee_overflow 0
		.amdhsa_exception_fp_ieee_underflow 0
		.amdhsa_exception_fp_ieee_inexact 0
		.amdhsa_exception_int_div_zero 0
	.end_amdhsa_kernel

amdhsa.kernels:
  - .agpr_count:     0
    .args:
      - .offset:         0
        .size:           160
        .value_kind:     by_value
      - .offset:         160
        .size:           4
        .value_kind:     hidden_block_count_x
      - .offset:         164
        .size:           4
        .value_kind:     hidden_block_count_y
      - .offset:         168
        .size:           4
        .value_kind:     hidden_block_count_z
      - .offset:         172
        .size:           2
        .value_kind:     hidden_group_size_x
      - .offset:         174
        .size:           2
        .value_kind:     hidden_group_size_y
      - .offset:         176
        .size:           2
        .value_kind:     hidden_group_size_z
      - .offset:         178
        .size:           2
        .value_kind:     hidden_remainder_x
      - .offset:         180
        .size:           2
        .value_kind:     hidden_remainder_y
      - .offset:         182
        .size:           2
        .value_kind:     hidden_remainder_z
      - .offset:         200
        .size:           8
        .value_kind:     hidden_global_offset_x
      - .offset:         208
        .size:           8
        .value_kind:     hidden_global_offset_y
      - .offset:         216
        .size:           8
        .value_kind:     hidden_global_offset_z
      - .offset:         224
        .size:           2
        .value_kind:     hidden_grid_dims
      - .offset:         280
        .size:           4
        .value_kind:     hidden_dynamic_lds_size
    .group_segment_fixed_size: 0
    .kernarg_segment_align: 8
    .kernarg_segment_size: 416
    .language:       OpenCL C
    .language_version:
      - 2
      - 0
    .max_flat_workgroup_size: 512
    .name:           _Z10fwd_kernel4Args
    .private_segment_fixed_size: 0
    .sgpr_count:     108
    .sgpr_spill_count: 115
    .symbol:         _Z10fwd_kernel4Args.kd
    .uniform_work_group_size: 1
    .uses_dynamic_stack: false
    .vgpr_count:     255
    .vgpr_spill_count: 0
    .wavefront_size: 64
